# v10 plus: LDS-DMA loads first in load segments, merged waitcnts
# baseline (speedup 1.0000x reference)
; #define PG8_STAGE(bufoff, gbase, voff) do { _Pragma("unroll") for (int _i = 0; _i < 2; ++_i) \
;         __builtin_amdgcn_global_load_lds((const unsigned*)((const char*)(gbase) + (voff)[_i]), (PG8_LAS unsigned*)(lds + (bufoff) + ldsw + _i * 8192), 16, 0, 0); } while (0)
; #define PG8_LDA(dst, b, h) do { _Pragma("unroll") for (int m = 0; m < 4; ++m) _Pragma("unroll") for (int k = 0; k < 2; ++k) dst[m][k] = *(const PG8_LAS bf16x8*)(lds + PG8_SA(b, h) + aoff + m * 2048 + k * 1024); } while (0)
; #define PG8_LDB(dst, b, h) do { _Pragma("unroll") for (int n = 0; n < 2; ++n) _Pragma("unroll") for (int k = 0; k < 2; ++k) dst[n][k] = *(const PG8_LAS bf16x8*)(lds + PG8_SB(b, h) + boff + n * 2048 + k * 1024); } while (0)
; #define PG8_MMA(ai, bj, At, Bt) do { __builtin_amdgcn_s_setprio(1); _Pragma("unroll") for (int m = 0; m < 4; ++m) _Pragma("unroll") for (int n = 0; n < 2; ++n) _Pragma("unroll") for (int k = 0; k < 2; ++k) \
;         acc[ai][bj][m][n] = __builtin_amdgcn_mfma_f32_16x16x32_bf16(Bt[n][k], At[m][k], acc[ai][bj][m][n], 0, 0, 0); __builtin_amdgcn_s_setprio(0); } while (0)
; #define PG8_WAIT_V(n) asm volatile("s_waitcnt vmcnt(" #n ")" ::: "memory")
; #define PG8_WAIT_L(n) asm volatile("s_waitcnt lgkmcnt(" #n ")" ::: "memory")
; #define PG8_BAR __builtin_amdgcn_s_barrier()
; #define PG8_SCHED __builtin_amdgcn_sched_barrier(0)
; template <class Epi, class Sched, bool ALIGN_EPI = false, bool SP2 = false>
; __device__ __forceinline__ void gemm_phase(PG8_LAS unsigned char* lds, const Gemm g, const Sched& S, const Epi& E) {
;     ...
;             const bool last = (t == nt - 2);
;             const char* a1 = cA + (size_t)(t + 1) * kstep;
;             const char* a2 = last ? nA : cA + (size_t)(t + 2) * kstep; const char* b2 = last ? nB : cB + (size_t)(t + 2) * kstep;
;             const char* a3 = a2 + kstep; const char* b3 = b2 + kstep;
;     ...
;             PG8_LDB(B0, 0, 0); PG8_LDB(B1, 0, 1); PG8_SCHED; PG8_LDA(At, 0, 0); PG8_STAGE(PG8_SA(1, 1), a1 + hstep, voffA);
;             PG8_WAIT_V(8); PG8_WAIT_L(0); PG8_BAR; PG8_MMA(0, 0, At, B0); PG8_MMA(0, 1, At, B1); PG8_BAR; PG8_SCHED;
;             PG8_LDA(At, 0, 1); PG8_STAGE(PG8_SB(0, 0), b2, voffB); PG8_STAGE(PG8_SB(0, 1), b2 + hstep, voffB); PG8_STAGE(PG8_SA(0, 0), a2, voffA);
;             PG8_WAIT_V(8); PG8_WAIT_L(0); PG8_BAR; PG8_MMA(1, 0, At, B0); PG8_MMA(1, 1, At, B1); PG8_BAR; PG8_SCHED;
.LBB0_673:
	s_add_u32 s20, s22, 0xfff00080
	s_addc_u32 s21, s23, -1
	s_cmp_eq_u32 s35, 60
	s_cselect_b32 s25, s11, s21
	s_cselect_b32 s24, s52, s20
	s_cselect_b32 s21, s13, s34
	s_cselect_b32 s20, s53, s62
	s_add_i32 m0, s19, 0xc000
	s_nop 0
	global_load_lds_dwordx4 v138, s[22:23]
	s_add_i32 m0, s19, 0xe000
	s_nop 0
	global_load_lds_dwordx4 v140, s[22:23]
	ds_read_b128 v[148:151], v241 offset:0
	ds_read_b128 v[156:159], v241 offset:1024
	ds_read_b128 v[166:169], v241 offset:2048
	ds_read_b128 v[170:173], v241 offset:3072
	ds_read_b128 v[174:177], v241 offset:16384
	ds_read_b128 v[178:181], v241 offset:17408
	ds_read_b128 v[182:185], v241 offset:18432
	ds_read_b128 v[186:189], v241 offset:19456
	ds_read_b128 v[190:193], v161
	ds_read_b128 v[194:197], v161 offset:1024
	ds_read_b128 v[198:201], v161 offset:2048
	ds_read_b128 v[202:205], v161 offset:3072
	ds_read_b128 v[206:209], v161 offset:4096
	ds_read_b128 v[210:213], v161 offset:5120
	ds_read_b128 v[214:217], v161 offset:6144
	ds_read_b128 v[218:221], v161 offset:7168
	s_waitcnt vmcnt(8) lgkmcnt(0)
	s_barrier
	v_mfma_f32_16x16x32_bf16 v[118:121], v[148:151], v[190:193], v[118:121]
	v_mfma_f32_16x16x32_bf16 v[114:117], v[166:169], v[190:193], v[114:117]
	v_mfma_f32_16x16x32_bf16 v[102:105], v[148:151], v[198:201], v[102:105]
	v_mfma_f32_16x16x32_bf16 v[98:101], v[166:169], v[198:201], v[98:101]
	v_mfma_f32_16x16x32_bf16 v[86:89], v[148:151], v[206:209], v[86:89]
	v_mfma_f32_16x16x32_bf16 v[82:85], v[166:169], v[206:209], v[82:85]
	v_mfma_f32_16x16x32_bf16 v[70:73], v[148:151], v[214:217], v[70:73]
	v_mfma_f32_16x16x32_bf16 v[66:69], v[166:169], v[214:217], v[66:69]
	v_mfma_f32_16x16x32_bf16 v[118:121], v[156:159], v[194:197], v[118:121]
	v_mfma_f32_16x16x32_bf16 v[114:117], v[170:173], v[194:197], v[114:117]
	v_mfma_f32_16x16x32_bf16 v[102:105], v[156:159], v[202:205], v[102:105]
	v_mfma_f32_16x16x32_bf16 v[98:101], v[170:173], v[202:205], v[98:101]
	v_mfma_f32_16x16x32_bf16 v[86:89], v[156:159], v[210:213], v[86:89]
	v_mfma_f32_16x16x32_bf16 v[82:85], v[170:173], v[210:213], v[82:85]
	v_mfma_f32_16x16x32_bf16 v[70:73], v[156:159], v[218:221], v[70:73]
	v_mfma_f32_16x16x32_bf16 v[66:69], v[170:173], v[218:221], v[66:69]
	v_mfma_f32_16x16x32_bf16 v[126:129], v[174:177], v[190:193], v[126:129]
	v_mfma_f32_16x16x32_bf16 v[122:125], v[182:185], v[190:193], v[122:125]
	v_mfma_f32_16x16x32_bf16 v[110:113], v[174:177], v[198:201], v[110:113]
	v_mfma_f32_16x16x32_bf16 v[106:109], v[182:185], v[198:201], v[106:109]
	v_mfma_f32_16x16x32_bf16 v[94:97], v[174:177], v[206:209], v[94:97]
	v_mfma_f32_16x16x32_bf16 v[90:93], v[182:185], v[206:209], v[90:93]
	v_mfma_f32_16x16x32_bf16 v[78:81], v[174:177], v[214:217], v[78:81]
	v_mfma_f32_16x16x32_bf16 v[74:77], v[182:185], v[214:217], v[74:77]
	v_mfma_f32_16x16x32_bf16 v[126:129], v[178:181], v[194:197], v[126:129]
	v_mfma_f32_16x16x32_bf16 v[122:125], v[186:189], v[194:197], v[122:125]
	v_mfma_f32_16x16x32_bf16 v[110:113], v[178:181], v[202:205], v[110:113]
	v_mfma_f32_16x16x32_bf16 v[106:109], v[186:189], v[202:205], v[106:109]
	v_mfma_f32_16x16x32_bf16 v[94:97], v[178:181], v[210:213], v[94:97]
	v_mfma_f32_16x16x32_bf16 v[90:93], v[186:189], v[210:213], v[90:93]
	v_mfma_f32_16x16x32_bf16 v[78:81], v[178:181], v[218:221], v[78:81]
	v_mfma_f32_16x16x32_bf16 v[74:77], v[186:189], v[218:221], v[74:77]
	s_barrier
	s_add_i32 s63, s43, s26
	s_mov_b32 m0, s63
	s_nop 0
	global_load_lds_dwordx4 v132, s[20:21]
	s_add_i32 m0, s63, 0x2000
	s_add_u32 s64, s20, 0x100000
	s_addc_u32 s65, s21, 0
	s_add_i32 s63, s46, s26
	global_load_lds_dwordx4 v136, s[20:21]
	s_mov_b32 m0, s63
	s_add_u32 s100, s24, 0x80
	s_addc_u32 s101, s25, 0
	global_load_lds_dwordx4 v132, s[64:65]
	s_add_i32 m0, s63, 0x2000
	s_nop 0
	global_load_lds_dwordx4 v136, s[64:65]
	s_mov_b32 m0, s19
	s_nop 0
	global_load_lds_dwordx4 v130, s[24:25]
	s_mov_b32 m0, s29
	s_nop 0
	global_load_lds_dwordx4 v134, s[24:25]
	ds_read_b128 v[190:193], v161 offset:16384
	ds_read_b128 v[194:197], v161 offset:17408
	ds_read_b128 v[198:201], v161 offset:18432
	ds_read_b128 v[202:205], v161 offset:19456
	ds_read_b128 v[206:209], v161 offset:20480
	ds_read_b128 v[210:213], v161 offset:21504
	ds_read_b128 v[214:217], v161 offset:22528
	ds_read_b128 v[218:221], v161 offset:23552
	s_waitcnt vmcnt(8) lgkmcnt(0)
	s_barrier
	v_mfma_f32_16x16x32_bf16 v[54:57], v[148:151], v[190:193], v[54:57]
	v_mfma_f32_16x16x32_bf16 v[50:53], v[166:169], v[190:193], v[50:53]
	v_mfma_f32_16x16x32_bf16 v[38:41], v[148:151], v[198:201], v[38:41]
	v_mfma_f32_16x16x32_bf16 v[34:37], v[166:169], v[198:201], v[34:37]
	v_mfma_f32_16x16x32_bf16 v[22:25], v[148:151], v[206:209], v[22:25]
	v_mfma_f32_16x16x32_bf16 v[18:21], v[166:169], v[206:209], v[18:21]
	v_mfma_f32_16x16x32_bf16 v[6:9], v[148:151], v[214:217], v[6:9]
	v_mfma_f32_16x16x32_bf16 v[2:5], v[166:169], v[214:217], v[2:5]
	v_mfma_f32_16x16x32_bf16 v[54:57], v[156:159], v[194:197], v[54:57]
	v_mfma_f32_16x16x32_bf16 v[50:53], v[170:173], v[194:197], v[50:53]
	v_mfma_f32_16x16x32_bf16 v[38:41], v[156:159], v[202:205], v[38:41]
	v_mfma_f32_16x16x32_bf16 v[34:37], v[170:173], v[202:205], v[34:37]
	v_mfma_f32_16x16x32_bf16 v[22:25], v[156:159], v[210:213], v[22:25]
	v_mfma_f32_16x16x32_bf16 v[18:21], v[170:173], v[210:213], v[18:21]
	v_mfma_f32_16x16x32_bf16 v[6:9], v[156:159], v[218:221], v[6:9]
	v_mfma_f32_16x16x32_bf16 v[2:5], v[170:173], v[218:221], v[2:5]
	v_mfma_f32_16x16x32_bf16 v[62:65], v[174:177], v[190:193], v[62:65]
	v_mfma_f32_16x16x32_bf16 v[58:61], v[182:185], v[190:193], v[58:61]
	v_mfma_f32_16x16x32_bf16 v[46:49], v[174:177], v[198:201], v[46:49]
	v_mfma_f32_16x16x32_bf16 v[42:45], v[182:185], v[198:201], v[42:45]
	v_mfma_f32_16x16x32_bf16 v[30:33], v[174:177], v[206:209], v[30:33]
	v_mfma_f32_16x16x32_bf16 v[26:29], v[182:185], v[206:209], v[26:29]
	v_mfma_f32_16x16x32_bf16 v[10:13], v[174:177], v[214:217], v[10:13]
	v_mfma_f32_16x16x32_bf16 v[14:17], v[182:185], v[214:217], v[14:17]
	v_mfma_f32_16x16x32_bf16 v[62:65], v[178:181], v[194:197], v[62:65]
	v_mfma_f32_16x16x32_bf16 v[58:61], v[186:189], v[194:197], v[58:61]
	v_mfma_f32_16x16x32_bf16 v[46:49], v[178:181], v[202:205], v[46:49]
	v_mfma_f32_16x16x32_bf16 v[42:45], v[186:189], v[202:205], v[42:45]
	v_mfma_f32_16x16x32_bf16 v[30:33], v[178:181], v[210:213], v[30:33]
	v_mfma_f32_16x16x32_bf16 v[26:29], v[186:189], v[210:213], v[26:29]
	v_mfma_f32_16x16x32_bf16 v[10:13], v[178:181], v[218:221], v[10:13]
	v_mfma_f32_16x16x32_bf16 v[14:17], v[186:189], v[218:221], v[14:17]
	s_barrier
; #define PG8_STAGE(bufoff, gbase, voff) do { _Pragma("unroll") for (int _i = 0; _i < 2; ++_i) \
;         __builtin_amdgcn_global_load_lds((const unsigned*)((const char*)(gbase) + (voff)[_i]), (PG8_LAS unsigned*)(lds + (bufoff) + ldsw + _i * 8192), 16, 0, 0); } while (0)
; #define PG8_LDA(dst, b, h) do { _Pragma("unroll") for (int m = 0; m < 4; ++m) _Pragma("unroll") for (int k = 0; k < 2; ++k) dst[m][k] = *(const PG8_LAS bf16x8*)(lds + PG8_SA(b, h) + aoff + m * 2048 + k * 1024); } while (0)
; #define PG8_LDB(dst, b, h) do { _Pragma("unroll") for (int n = 0; n < 2; ++n) _Pragma("unroll") for (int k = 0; k < 2; ++k) dst[n][k] = *(const PG8_LAS bf16x8*)(lds + PG8_SB(b, h) + boff + n * 2048 + k * 1024); } while (0)
; #define PG8_MMA(ai, bj, At, Bt) do { __builtin_amdgcn_s_setprio(1); _Pragma("unroll") for (int m = 0; m < 4; ++m) _Pragma("unroll") for (int n = 0; n < 2; ++n) _Pragma("unroll") for (int k = 0; k < 2; ++k) \
;         acc[ai][bj][m][n] = __builtin_amdgcn_mfma_f32_16x16x32_bf16(Bt[n][k], At[m][k], acc[ai][bj][m][n], 0, 0, 0); __builtin_amdgcn_s_setprio(0); } while (0)
; #define PG8_WAIT_V(n) asm volatile("s_waitcnt vmcnt(" #n ")" ::: "memory")
; #define PG8_WAIT_L(n) asm volatile("s_waitcnt lgkmcnt(" #n ")" ::: "memory")
; template <class Epi, class Sched, bool ALIGN_EPI = false, bool SP2 = false>
; __device__ __forceinline__ void gemm_phase(PG8_LAS unsigned char* lds, const Gemm g, const Sched& S, const Epi& E) {
;     ...
;         for (int t = 0; t < nt; t += 2) {
;             const bool last = (t == nt - 2);
;             const char* a1 = cA + (size_t)(t + 1) * kstep;
;             const char* a2 = last ? nA : cA + (size_t)(t + 2) * kstep; const char* b2 = last ? nB : cB + (size_t)(t + 2) * kstep;
;             const char* a3 = a2 + kstep; const char* b3 = b2 + kstep;
;             if (last && has_next) S.a_ready(nxt);
;     ...
;             PG8_LDB(B0, 1, 0); PG8_LDB(B1, 1, 1); PG8_SCHED; PG8_LDA(At, 1, 0); PG8_STAGE(PG8_SA(0, 1), a2 + hstep, voffA);
;             PG8_WAIT_V(8); PG8_WAIT_L(0); PG8_BAR; PG8_MMA(0, 0, At, B0); PG8_MMA(0, 1, At, B1); PG8_BAR; PG8_SCHED;
;             PG8_LDA(At, 1, 1); PG8_STAGE(PG8_SB(1, 0), b3, voffB); PG8_STAGE(PG8_SB(1, 1), b3 + hstep, voffB); PG8_STAGE(PG8_SA(1, 0), a3, voffA);
;             PG8_WAIT_V(8); PG8_WAIT_L(0); PG8_BAR; PG8_MMA(1, 0, At, B0); PG8_MMA(1, 1, At, B1); PG8_BAR; PG8_SCHED;
	s_add_i32 s63, 0, 0x18000
	s_add_i32 s64, 0, 0x1c000
	s_add_u32 s24, s24, 0x100000
	s_addc_u32 s25, s25, 0
	s_mov_b32 m0, s30
	s_nop 0
	global_load_lds_dwordx4 v130, s[24:25]
	s_mov_b32 m0, s31
	s_nop 0
	global_load_lds_dwordx4 v134, s[24:25]
	ds_read_b128 v[148:151], v241 offset:32768
	ds_read_b128 v[156:159], v241 offset:33792
	ds_read_b128 v[166:169], v241 offset:34816
	ds_read_b128 v[170:173], v241 offset:35840
	ds_read_b128 v[174:177], v241 offset:49152
	ds_read_b128 v[178:181], v241 offset:50176
	ds_read_b128 v[182:185], v241 offset:51200
	ds_read_b128 v[186:189], v241 offset:52224
	ds_read_b128 v[190:193], v161 offset:32768
	ds_read_b128 v[194:197], v161 offset:33792
	ds_read_b128 v[198:201], v161 offset:34816
	ds_read_b128 v[202:205], v161 offset:35840
	ds_read_b128 v[206:209], v161 offset:36864
	ds_read_b128 v[210:213], v161 offset:37888
	ds_read_b128 v[214:217], v161 offset:38912
	ds_read_b128 v[218:221], v161 offset:39936
	s_waitcnt vmcnt(8) lgkmcnt(0)
	s_barrier
	v_mfma_f32_16x16x32_bf16 v[118:121], v[148:151], v[190:193], v[118:121]
	v_mfma_f32_16x16x32_bf16 v[114:117], v[166:169], v[190:193], v[114:117]
	v_mfma_f32_16x16x32_bf16 v[102:105], v[148:151], v[198:201], v[102:105]
	v_mfma_f32_16x16x32_bf16 v[98:101], v[166:169], v[198:201], v[98:101]
	v_mfma_f32_16x16x32_bf16 v[86:89], v[148:151], v[206:209], v[86:89]
	v_mfma_f32_16x16x32_bf16 v[82:85], v[166:169], v[206:209], v[82:85]
	v_mfma_f32_16x16x32_bf16 v[70:73], v[148:151], v[214:217], v[70:73]
	v_mfma_f32_16x16x32_bf16 v[66:69], v[166:169], v[214:217], v[66:69]
	v_mfma_f32_16x16x32_bf16 v[118:121], v[156:159], v[194:197], v[118:121]
	v_mfma_f32_16x16x32_bf16 v[114:117], v[170:173], v[194:197], v[114:117]
	v_mfma_f32_16x16x32_bf16 v[102:105], v[156:159], v[202:205], v[102:105]
	v_mfma_f32_16x16x32_bf16 v[98:101], v[170:173], v[202:205], v[98:101]
	v_mfma_f32_16x16x32_bf16 v[86:89], v[156:159], v[210:213], v[86:89]
	v_mfma_f32_16x16x32_bf16 v[82:85], v[170:173], v[210:213], v[82:85]
	v_mfma_f32_16x16x32_bf16 v[70:73], v[156:159], v[218:221], v[70:73]
	v_mfma_f32_16x16x32_bf16 v[66:69], v[170:173], v[218:221], v[66:69]
	v_mfma_f32_16x16x32_bf16 v[126:129], v[174:177], v[190:193], v[126:129]
	v_mfma_f32_16x16x32_bf16 v[122:125], v[182:185], v[190:193], v[122:125]
	v_mfma_f32_16x16x32_bf16 v[110:113], v[174:177], v[198:201], v[110:113]
	v_mfma_f32_16x16x32_bf16 v[106:109], v[182:185], v[198:201], v[106:109]
	v_mfma_f32_16x16x32_bf16 v[94:97], v[174:177], v[206:209], v[94:97]
	v_mfma_f32_16x16x32_bf16 v[90:93], v[182:185], v[206:209], v[90:93]
	v_mfma_f32_16x16x32_bf16 v[78:81], v[174:177], v[214:217], v[78:81]
	v_mfma_f32_16x16x32_bf16 v[74:77], v[182:185], v[214:217], v[74:77]
	v_mfma_f32_16x16x32_bf16 v[126:129], v[178:181], v[194:197], v[126:129]
	v_mfma_f32_16x16x32_bf16 v[122:125], v[186:189], v[194:197], v[122:125]
	v_mfma_f32_16x16x32_bf16 v[110:113], v[178:181], v[202:205], v[110:113]
	v_mfma_f32_16x16x32_bf16 v[106:109], v[186:189], v[202:205], v[106:109]
	v_mfma_f32_16x16x32_bf16 v[94:97], v[178:181], v[210:213], v[94:97]
	v_mfma_f32_16x16x32_bf16 v[90:93], v[186:189], v[210:213], v[90:93]
	v_mfma_f32_16x16x32_bf16 v[78:81], v[178:181], v[218:221], v[78:81]
	v_mfma_f32_16x16x32_bf16 v[74:77], v[186:189], v[218:221], v[74:77]
	s_barrier
	s_add_i32 s24, s63, s26
	s_add_i32 m0, s24, 0xffffff80
	s_nop 0
	global_load_lds_dwordx4 v132, s[20:21] offset:128
	s_add_i32 m0, s24, 0x1f80
	s_add_i32 s24, s64, s26
	global_load_lds_dwordx4 v136, s[20:21] offset:128
	s_add_u32 s20, s20, 0x100080
	s_addc_u32 s21, s21, 0
	s_mov_b32 m0, s24
	s_nop 0
	global_load_lds_dwordx4 v132, s[20:21]
	s_add_i32 m0, s24, 0x2000
	s_nop 0
	global_load_lds_dwordx4 v136, s[20:21]
	s_mov_b32 m0, s40
	s_nop 0
	global_load_lds_dwordx4 v130, s[100:101]
	s_mov_b32 m0, s41
	s_nop 0
	global_load_lds_dwordx4 v134, s[100:101]
	ds_read_b128 v[190:193], v161 offset:49152
	ds_read_b128 v[194:197], v161 offset:50176
	ds_read_b128 v[198:201], v161 offset:51200
	ds_read_b128 v[202:205], v161 offset:52224
	ds_read_b128 v[206:209], v161 offset:53248
	ds_read_b128 v[210:213], v161 offset:54272
	ds_read_b128 v[214:217], v161 offset:55296
	ds_read_b128 v[218:221], v161 offset:56320
	s_waitcnt vmcnt(8) lgkmcnt(0)
	s_barrier
	v_mfma_f32_16x16x32_bf16 v[54:57], v[148:151], v[190:193], v[54:57]
	v_mfma_f32_16x16x32_bf16 v[50:53], v[166:169], v[190:193], v[50:53]
	v_mfma_f32_16x16x32_bf16 v[38:41], v[148:151], v[198:201], v[38:41]
	v_mfma_f32_16x16x32_bf16 v[34:37], v[166:169], v[198:201], v[34:37]
	v_mfma_f32_16x16x32_bf16 v[22:25], v[148:151], v[206:209], v[22:25]
	v_mfma_f32_16x16x32_bf16 v[18:21], v[166:169], v[206:209], v[18:21]
	v_mfma_f32_16x16x32_bf16 v[6:9], v[148:151], v[214:217], v[6:9]
	v_mfma_f32_16x16x32_bf16 v[2:5], v[166:169], v[214:217], v[2:5]
	v_mfma_f32_16x16x32_bf16 v[54:57], v[156:159], v[194:197], v[54:57]
	v_mfma_f32_16x16x32_bf16 v[50:53], v[170:173], v[194:197], v[50:53]
	v_mfma_f32_16x16x32_bf16 v[38:41], v[156:159], v[202:205], v[38:41]
	v_mfma_f32_16x16x32_bf16 v[34:37], v[170:173], v[202:205], v[34:37]
	v_mfma_f32_16x16x32_bf16 v[22:25], v[156:159], v[210:213], v[22:25]
	v_mfma_f32_16x16x32_bf16 v[18:21], v[170:173], v[210:213], v[18:21]
	v_mfma_f32_16x16x32_bf16 v[6:9], v[156:159], v[218:221], v[6:9]
	v_mfma_f32_16x16x32_bf16 v[2:5], v[170:173], v[218:221], v[2:5]
	v_mfma_f32_16x16x32_bf16 v[62:65], v[174:177], v[190:193], v[62:65]
	v_mfma_f32_16x16x32_bf16 v[58:61], v[182:185], v[190:193], v[58:61]
	v_mfma_f32_16x16x32_bf16 v[46:49], v[174:177], v[198:201], v[46:49]
	v_mfma_f32_16x16x32_bf16 v[42:45], v[182:185], v[198:201], v[42:45]
	v_mfma_f32_16x16x32_bf16 v[30:33], v[174:177], v[206:209], v[30:33]
	v_mfma_f32_16x16x32_bf16 v[26:29], v[182:185], v[206:209], v[26:29]
	v_mfma_f32_16x16x32_bf16 v[10:13], v[174:177], v[214:217], v[10:13]
	v_mfma_f32_16x16x32_bf16 v[14:17], v[182:185], v[214:217], v[14:17]
	v_mfma_f32_16x16x32_bf16 v[62:65], v[178:181], v[194:197], v[62:65]
	v_mfma_f32_16x16x32_bf16 v[58:61], v[186:189], v[194:197], v[58:61]
	v_mfma_f32_16x16x32_bf16 v[46:49], v[178:181], v[202:205], v[46:49]
	v_mfma_f32_16x16x32_bf16 v[42:45], v[186:189], v[202:205], v[42:45]
	v_mfma_f32_16x16x32_bf16 v[30:33], v[178:181], v[210:213], v[30:33]
	v_mfma_f32_16x16x32_bf16 v[26:29], v[186:189], v[210:213], v[26:29]
	v_mfma_f32_16x16x32_bf16 v[10:13], v[178:181], v[218:221], v[10:13]
	v_mfma_f32_16x16x32_bf16 v[14:17], v[186:189], v[218:221], v[14:17]
	s_barrier
	s_add_i32 s35, s35, 2
	s_add_u32 s22, s22, 0x100
	s_addc_u32 s23, s23, 0
	s_add_u32 s62, s62, 0x100
	s_addc_u32 s34, s34, 0
	s_cmp_gt_u32 s35, 61
	s_cbranch_scc0 .LBB0_673
	s_and_b64 vcc, exec, s[8:9]
	s_cbranch_vccz .LBB0_676
	s_barrier

; #define PG8_STAGE(bufoff, gbase, voff) do { _Pragma("unroll") for (int _i = 0; _i < 2; ++_i) \
;         __builtin_amdgcn_global_load_lds((const unsigned*)((const char*)(gbase) + (voff)[_i]), (PG8_LAS unsigned*)(lds + (bufoff) + ldsw + _i * 8192), 16, 0, 0); } while (0)
; #define PG8_LDA(dst, b, h) do { _Pragma("unroll") for (int m = 0; m < 4; ++m) _Pragma("unroll") for (int k = 0; k < 2; ++k) dst[m][k] = *(const PG8_LAS bf16x8*)(lds + PG8_SA(b, h) + aoff + m * 2048 + k * 1024); } while (0)
; #define PG8_LDB(dst, b, h) do { _Pragma("unroll") for (int n = 0; n < 2; ++n) _Pragma("unroll") for (int k = 0; k < 2; ++k) dst[n][k] = *(const PG8_LAS bf16x8*)(lds + PG8_SB(b, h) + boff + n * 2048 + k * 1024); } while (0)
; #define PG8_MMA(ai, bj, At, Bt) do { __builtin_amdgcn_s_setprio(1); _Pragma("unroll") for (int m = 0; m < 4; ++m) _Pragma("unroll") for (int n = 0; n < 2; ++n) _Pragma("unroll") for (int k = 0; k < 2; ++k) \
;         acc[ai][bj][m][n] = __builtin_amdgcn_mfma_f32_16x16x32_bf16(Bt[n][k], At[m][k], acc[ai][bj][m][n], 0, 0, 0); __builtin_amdgcn_s_setprio(0); } while (0)
; #define PG8_WAIT_V(n) asm volatile("s_waitcnt vmcnt(" #n ")" ::: "memory")
; #define PG8_WAIT_L(n) asm volatile("s_waitcnt lgkmcnt(" #n ")" ::: "memory")
; #define PG8_BAR __builtin_amdgcn_s_barrier()
; #define PG8_SCHED __builtin_amdgcn_sched_barrier(0)
; template <class Epi, class Sched, bool ALIGN_EPI = false, bool SP2 = false>
; __device__ __forceinline__ void gemm_phase(PG8_LAS unsigned char* lds, const Gemm g, const Sched& S, const Epi& E) {
;     ...
;             const bool last = (t == nt - 2);
;             const char* a1 = cA + (size_t)(t + 1) * kstep;
;             const char* a2 = last ? nA : cA + (size_t)(t + 2) * kstep; const char* b2 = last ? nB : cB + (size_t)(t + 2) * kstep;
;             const char* a3 = a2 + kstep; const char* b3 = b2 + kstep;
;     ...
;             PG8_LDB(B0, 0, 0); PG8_LDB(B1, 0, 1); PG8_SCHED; PG8_LDA(At, 0, 0); PG8_STAGE(PG8_SA(1, 1), a1 + hstep, voffA);
;             PG8_WAIT_V(8); PG8_WAIT_L(0); PG8_BAR; PG8_MMA(0, 0, At, B0); PG8_MMA(0, 1, At, B1); PG8_BAR; PG8_SCHED;
;             PG8_LDA(At, 0, 1); PG8_STAGE(PG8_SB(0, 0), b2, voffB); PG8_STAGE(PG8_SB(0, 1), b2 + hstep, voffB); PG8_STAGE(PG8_SA(0, 0), a2, voffA);
;             PG8_WAIT_V(8); PG8_WAIT_L(0); PG8_BAR; PG8_MMA(1, 0, At, B0); PG8_MMA(1, 1, At, B1); PG8_BAR; PG8_SCHED;
.LBB0_1039:
	s_add_u32 s24, s26, 0xfff00080
	s_addc_u32 s25, s27, -1
	s_cmp_eq_u32 s68, 60
	s_cselect_b32 s29, s15, s25
	s_cselect_b32 s28, s21, s24
	s_cselect_b32 s25, s13, s67
	s_cselect_b32 s24, s65, s66
	s_add_i32 m0, s23, 0xc000
	s_nop 0
	global_load_lds_dwordx4 v162, s[26:27]
	s_add_i32 m0, s23, 0xe000
	s_nop 0
	global_load_lds_dwordx4 v166, s[26:27]
	ds_read_b128 v[130:133], v241 offset:0
	ds_read_b128 v[134:137], v241 offset:1024
	ds_read_b128 v[138:141], v241 offset:2048
	ds_read_b128 v[142:145], v241 offset:3072
	ds_read_b128 v[146:149], v241 offset:16384
	ds_read_b128 v[150:153], v241 offset:17408
	ds_read_b128 v[172:175], v241 offset:18432
	ds_read_b128 v[176:179], v241 offset:19456
	ds_read_b128 v[180:183], v185
	ds_read_b128 v[188:191], v185 offset:1024
	ds_read_b128 v[192:195], v185 offset:2048
	ds_read_b128 v[196:199], v185 offset:3072
	ds_read_b128 v[200:203], v185 offset:4096
	ds_read_b128 v[204:207], v185 offset:5120
	ds_read_b128 v[208:211], v185 offset:6144
	ds_read_b128 v[212:215], v185 offset:7168
	s_waitcnt vmcnt(8) lgkmcnt(0)
	s_barrier
	v_mfma_f32_16x16x32_bf16 v[114:117], v[130:133], v[180:183], v[114:117]
	v_mfma_f32_16x16x32_bf16 v[118:121], v[138:141], v[180:183], v[118:121]
	v_mfma_f32_16x16x32_bf16 v[106:109], v[130:133], v[192:195], v[106:109]
	v_mfma_f32_16x16x32_bf16 v[98:101], v[138:141], v[192:195], v[98:101]
	v_mfma_f32_16x16x32_bf16 v[90:93], v[130:133], v[200:203], v[90:93]
	v_mfma_f32_16x16x32_bf16 v[82:85], v[138:141], v[200:203], v[82:85]
	v_mfma_f32_16x16x32_bf16 v[74:77], v[130:133], v[208:211], v[74:77]
	v_mfma_f32_16x16x32_bf16 v[66:69], v[138:141], v[208:211], v[66:69]
	v_mfma_f32_16x16x32_bf16 v[114:117], v[134:137], v[188:191], v[114:117]
	v_mfma_f32_16x16x32_bf16 v[118:121], v[142:145], v[188:191], v[118:121]
	v_mfma_f32_16x16x32_bf16 v[106:109], v[134:137], v[196:199], v[106:109]
	v_mfma_f32_16x16x32_bf16 v[98:101], v[142:145], v[196:199], v[98:101]
	v_mfma_f32_16x16x32_bf16 v[90:93], v[134:137], v[204:207], v[90:93]
	v_mfma_f32_16x16x32_bf16 v[82:85], v[142:145], v[204:207], v[82:85]
	v_mfma_f32_16x16x32_bf16 v[74:77], v[134:137], v[212:215], v[74:77]
	v_mfma_f32_16x16x32_bf16 v[66:69], v[142:145], v[212:215], v[66:69]
	v_mfma_f32_16x16x32_bf16 v[122:125], v[146:149], v[180:183], v[122:125]
	v_mfma_f32_16x16x32_bf16 v[126:129], v[172:175], v[180:183], v[126:129]
	v_mfma_f32_16x16x32_bf16 v[110:113], v[146:149], v[192:195], v[110:113]
	v_mfma_f32_16x16x32_bf16 v[102:105], v[172:175], v[192:195], v[102:105]
	v_mfma_f32_16x16x32_bf16 v[94:97], v[146:149], v[200:203], v[94:97]
	v_mfma_f32_16x16x32_bf16 v[86:89], v[172:175], v[200:203], v[86:89]
	v_mfma_f32_16x16x32_bf16 v[78:81], v[146:149], v[208:211], v[78:81]
	v_mfma_f32_16x16x32_bf16 v[70:73], v[172:175], v[208:211], v[70:73]
	v_mfma_f32_16x16x32_bf16 v[122:125], v[150:153], v[188:191], v[122:125]
	v_mfma_f32_16x16x32_bf16 v[126:129], v[176:179], v[188:191], v[126:129]
	v_mfma_f32_16x16x32_bf16 v[110:113], v[150:153], v[196:199], v[110:113]
	v_mfma_f32_16x16x32_bf16 v[102:105], v[176:179], v[196:199], v[102:105]
	v_mfma_f32_16x16x32_bf16 v[94:97], v[150:153], v[204:207], v[94:97]
	v_mfma_f32_16x16x32_bf16 v[86:89], v[176:179], v[204:207], v[86:89]
	v_mfma_f32_16x16x32_bf16 v[78:81], v[150:153], v[212:215], v[78:81]
	v_mfma_f32_16x16x32_bf16 v[70:73], v[176:179], v[212:215], v[70:73]
	s_barrier
	s_add_i32 s33, s62, s36
	s_mov_b32 m0, s33
	s_nop 0
	global_load_lds_dwordx4 v156, s[24:25]
	s_add_i32 m0, s33, 0x2000
	s_add_u32 s72, s24, 0x100000
	s_addc_u32 s73, s25, 0
	s_add_i32 s33, s63, s36
	global_load_lds_dwordx4 v160, s[24:25]
	s_mov_b32 m0, s33
	s_add_u32 s100, s28, 0x80
	s_addc_u32 s101, s29, 0
	global_load_lds_dwordx4 v156, s[72:73]
	s_add_i32 m0, s33, 0x2000
	s_nop 0
	global_load_lds_dwordx4 v160, s[72:73]
	s_mov_b32 m0, s23
	s_nop 0
	global_load_lds_dwordx4 v154, s[28:29]
	s_mov_b32 m0, s37
	s_nop 0
	global_load_lds_dwordx4 v158, s[28:29]
	ds_read_b128 v[180:183], v185 offset:16384
	ds_read_b128 v[188:191], v185 offset:17408
	ds_read_b128 v[192:195], v185 offset:18432
	ds_read_b128 v[196:199], v185 offset:19456
	ds_read_b128 v[200:203], v185 offset:20480
	ds_read_b128 v[204:207], v185 offset:21504
	ds_read_b128 v[208:211], v185 offset:22528
	ds_read_b128 v[212:215], v185 offset:23552
	s_waitcnt vmcnt(8) lgkmcnt(0)
	s_barrier
	v_mfma_f32_16x16x32_bf16 v[58:61], v[130:133], v[180:183], v[58:61]
	v_mfma_f32_16x16x32_bf16 v[54:57], v[138:141], v[180:183], v[54:57]
	v_mfma_f32_16x16x32_bf16 v[42:45], v[130:133], v[192:195], v[42:45]
	v_mfma_f32_16x16x32_bf16 v[34:37], v[138:141], v[192:195], v[34:37]
	v_mfma_f32_16x16x32_bf16 v[26:29], v[130:133], v[200:203], v[26:29]
	v_mfma_f32_16x16x32_bf16 v[18:21], v[138:141], v[200:203], v[18:21]
	v_mfma_f32_16x16x32_bf16 v[6:9], v[130:133], v[208:211], v[6:9]
	v_mfma_f32_16x16x32_bf16 v[2:5], v[138:141], v[208:211], v[2:5]
	v_mfma_f32_16x16x32_bf16 v[58:61], v[134:137], v[188:191], v[58:61]
	v_mfma_f32_16x16x32_bf16 v[54:57], v[142:145], v[188:191], v[54:57]
	v_mfma_f32_16x16x32_bf16 v[42:45], v[134:137], v[196:199], v[42:45]
	v_mfma_f32_16x16x32_bf16 v[34:37], v[142:145], v[196:199], v[34:37]
	v_mfma_f32_16x16x32_bf16 v[26:29], v[134:137], v[204:207], v[26:29]
	v_mfma_f32_16x16x32_bf16 v[18:21], v[142:145], v[204:207], v[18:21]
	v_mfma_f32_16x16x32_bf16 v[6:9], v[134:137], v[212:215], v[6:9]
	v_mfma_f32_16x16x32_bf16 v[2:5], v[142:145], v[212:215], v[2:5]
	v_mfma_f32_16x16x32_bf16 v[62:65], v[146:149], v[180:183], v[62:65]
	v_mfma_f32_16x16x32_bf16 v[50:53], v[172:175], v[180:183], v[50:53]
	v_mfma_f32_16x16x32_bf16 v[46:49], v[146:149], v[192:195], v[46:49]
	v_mfma_f32_16x16x32_bf16 v[38:41], v[172:175], v[192:195], v[38:41]
	v_mfma_f32_16x16x32_bf16 v[30:33], v[146:149], v[200:203], v[30:33]
	v_mfma_f32_16x16x32_bf16 v[22:25], v[172:175], v[200:203], v[22:25]
	v_mfma_f32_16x16x32_bf16 v[10:13], v[146:149], v[208:211], v[10:13]
	v_mfma_f32_16x16x32_bf16 v[14:17], v[172:175], v[208:211], v[14:17]
	v_mfma_f32_16x16x32_bf16 v[62:65], v[150:153], v[188:191], v[62:65]
	v_mfma_f32_16x16x32_bf16 v[50:53], v[176:179], v[188:191], v[50:53]
	v_mfma_f32_16x16x32_bf16 v[46:49], v[150:153], v[196:199], v[46:49]
	v_mfma_f32_16x16x32_bf16 v[38:41], v[176:179], v[196:199], v[38:41]
	v_mfma_f32_16x16x32_bf16 v[30:33], v[150:153], v[204:207], v[30:33]
	v_mfma_f32_16x16x32_bf16 v[22:25], v[176:179], v[204:207], v[22:25]
	v_mfma_f32_16x16x32_bf16 v[10:13], v[150:153], v[212:215], v[10:13]
	v_mfma_f32_16x16x32_bf16 v[14:17], v[176:179], v[212:215], v[14:17]
	s_barrier
; #define PG8_STAGE(bufoff, gbase, voff) do { _Pragma("unroll") for (int _i = 0; _i < 2; ++_i) \
;         __builtin_amdgcn_global_load_lds((const unsigned*)((const char*)(gbase) + (voff)[_i]), (PG8_LAS unsigned*)(lds + (bufoff) + ldsw + _i * 8192), 16, 0, 0); } while (0)
; #define PG8_LDA(dst, b, h) do { _Pragma("unroll") for (int m = 0; m < 4; ++m) _Pragma("unroll") for (int k = 0; k < 2; ++k) dst[m][k] = *(const PG8_LAS bf16x8*)(lds + PG8_SA(b, h) + aoff + m * 2048 + k * 1024); } while (0)
; #define PG8_LDB(dst, b, h) do { _Pragma("unroll") for (int n = 0; n < 2; ++n) _Pragma("unroll") for (int k = 0; k < 2; ++k) dst[n][k] = *(const PG8_LAS bf16x8*)(lds + PG8_SB(b, h) + boff + n * 2048 + k * 1024); } while (0)
; #define PG8_MMA(ai, bj, At, Bt) do { __builtin_amdgcn_s_setprio(1); _Pragma("unroll") for (int m = 0; m < 4; ++m) _Pragma("unroll") for (int n = 0; n < 2; ++n) _Pragma("unroll") for (int k = 0; k < 2; ++k) \
;         acc[ai][bj][m][n] = __builtin_amdgcn_mfma_f32_16x16x32_bf16(Bt[n][k], At[m][k], acc[ai][bj][m][n], 0, 0, 0); __builtin_amdgcn_s_setprio(0); } while (0)
; #define PG8_WAIT_V(n) asm volatile("s_waitcnt vmcnt(" #n ")" ::: "memory")
; #define PG8_WAIT_L(n) asm volatile("s_waitcnt lgkmcnt(" #n ")" ::: "memory")
; template <class Epi, class Sched, bool ALIGN_EPI = false, bool SP2 = false>
; __device__ __forceinline__ void gemm_phase(PG8_LAS unsigned char* lds, const Gemm g, const Sched& S, const Epi& E) {
;     ...
;         for (int t = 0; t < nt; t += 2) {
;             const bool last = (t == nt - 2);
;             const char* a1 = cA + (size_t)(t + 1) * kstep;
;             const char* a2 = last ? nA : cA + (size_t)(t + 2) * kstep; const char* b2 = last ? nB : cB + (size_t)(t + 2) * kstep;
;             const char* a3 = a2 + kstep; const char* b3 = b2 + kstep;
;             if (last && has_next) S.a_ready(nxt);
;     ...
;             PG8_LDB(B0, 1, 0); PG8_LDB(B1, 1, 1); PG8_SCHED; PG8_LDA(At, 1, 0); PG8_STAGE(PG8_SA(0, 1), a2 + hstep, voffA);
;             PG8_WAIT_V(8); PG8_WAIT_L(0); PG8_BAR; PG8_MMA(0, 0, At, B0); PG8_MMA(0, 1, At, B1); PG8_BAR; PG8_SCHED;
;             PG8_LDA(At, 1, 1); PG8_STAGE(PG8_SB(1, 0), b3, voffB); PG8_STAGE(PG8_SB(1, 1), b3 + hstep, voffB); PG8_STAGE(PG8_SA(1, 0), a3, voffA);
;             PG8_WAIT_V(8); PG8_WAIT_L(0); PG8_BAR; PG8_MMA(1, 0, At, B0); PG8_MMA(1, 1, At, B1); PG8_BAR; PG8_SCHED;
	s_add_i32 s33, 0, 0x18000
	s_add_i32 s42, 0, 0x1c000
	s_add_u32 s28, s28, 0x100000
	s_addc_u32 s29, s29, 0
	s_mov_b32 m0, s40
	s_nop 0
	global_load_lds_dwordx4 v154, s[28:29]
	s_mov_b32 m0, s41
	s_nop 0
	global_load_lds_dwordx4 v158, s[28:29]
	ds_read_b128 v[130:133], v241 offset:32768
	ds_read_b128 v[134:137], v241 offset:33792
	ds_read_b128 v[138:141], v241 offset:34816
	ds_read_b128 v[142:145], v241 offset:35840
	ds_read_b128 v[146:149], v241 offset:49152
	ds_read_b128 v[150:153], v241 offset:50176
	ds_read_b128 v[172:175], v241 offset:51200
	ds_read_b128 v[176:179], v241 offset:52224
	ds_read_b128 v[180:183], v185 offset:32768
	ds_read_b128 v[188:191], v185 offset:33792
	ds_read_b128 v[192:195], v185 offset:34816
	ds_read_b128 v[196:199], v185 offset:35840
	ds_read_b128 v[200:203], v185 offset:36864
	ds_read_b128 v[204:207], v185 offset:37888
	ds_read_b128 v[208:211], v185 offset:38912
	ds_read_b128 v[212:215], v185 offset:39936
	s_waitcnt vmcnt(8) lgkmcnt(0)
	s_barrier
	v_mfma_f32_16x16x32_bf16 v[114:117], v[130:133], v[180:183], v[114:117]
	v_mfma_f32_16x16x32_bf16 v[118:121], v[138:141], v[180:183], v[118:121]
	v_mfma_f32_16x16x32_bf16 v[106:109], v[130:133], v[192:195], v[106:109]
	v_mfma_f32_16x16x32_bf16 v[98:101], v[138:141], v[192:195], v[98:101]
	v_mfma_f32_16x16x32_bf16 v[90:93], v[130:133], v[200:203], v[90:93]
	v_mfma_f32_16x16x32_bf16 v[82:85], v[138:141], v[200:203], v[82:85]
	v_mfma_f32_16x16x32_bf16 v[74:77], v[130:133], v[208:211], v[74:77]
	v_mfma_f32_16x16x32_bf16 v[66:69], v[138:141], v[208:211], v[66:69]
	v_mfma_f32_16x16x32_bf16 v[114:117], v[134:137], v[188:191], v[114:117]
	v_mfma_f32_16x16x32_bf16 v[118:121], v[142:145], v[188:191], v[118:121]
	v_mfma_f32_16x16x32_bf16 v[106:109], v[134:137], v[196:199], v[106:109]
	v_mfma_f32_16x16x32_bf16 v[98:101], v[142:145], v[196:199], v[98:101]
	v_mfma_f32_16x16x32_bf16 v[90:93], v[134:137], v[204:207], v[90:93]
	v_mfma_f32_16x16x32_bf16 v[82:85], v[142:145], v[204:207], v[82:85]
	v_mfma_f32_16x16x32_bf16 v[74:77], v[134:137], v[212:215], v[74:77]
	v_mfma_f32_16x16x32_bf16 v[66:69], v[142:145], v[212:215], v[66:69]
	v_mfma_f32_16x16x32_bf16 v[122:125], v[146:149], v[180:183], v[122:125]
	v_mfma_f32_16x16x32_bf16 v[126:129], v[172:175], v[180:183], v[126:129]
	v_mfma_f32_16x16x32_bf16 v[110:113], v[146:149], v[192:195], v[110:113]
	v_mfma_f32_16x16x32_bf16 v[102:105], v[172:175], v[192:195], v[102:105]
	v_mfma_f32_16x16x32_bf16 v[94:97], v[146:149], v[200:203], v[94:97]
	v_mfma_f32_16x16x32_bf16 v[86:89], v[172:175], v[200:203], v[86:89]
	v_mfma_f32_16x16x32_bf16 v[78:81], v[146:149], v[208:211], v[78:81]
	v_mfma_f32_16x16x32_bf16 v[70:73], v[172:175], v[208:211], v[70:73]
	v_mfma_f32_16x16x32_bf16 v[122:125], v[150:153], v[188:191], v[122:125]
	v_mfma_f32_16x16x32_bf16 v[126:129], v[176:179], v[188:191], v[126:129]
	v_mfma_f32_16x16x32_bf16 v[110:113], v[150:153], v[196:199], v[110:113]
	v_mfma_f32_16x16x32_bf16 v[102:105], v[176:179], v[196:199], v[102:105]
	v_mfma_f32_16x16x32_bf16 v[94:97], v[150:153], v[204:207], v[94:97]
	v_mfma_f32_16x16x32_bf16 v[86:89], v[176:179], v[204:207], v[86:89]
	v_mfma_f32_16x16x32_bf16 v[78:81], v[150:153], v[212:215], v[78:81]
	v_mfma_f32_16x16x32_bf16 v[70:73], v[176:179], v[212:215], v[70:73]
	s_barrier
	s_add_i32 s28, s33, s36
	s_add_i32 m0, s28, 0xffffff80
	s_nop 0
	global_load_lds_dwordx4 v156, s[24:25] offset:128
	s_add_i32 m0, s28, 0x1f80
	s_add_i32 s28, s42, s36
	global_load_lds_dwordx4 v160, s[24:25] offset:128
	s_add_u32 s24, s24, 0x100080
	s_addc_u32 s25, s25, 0
	s_mov_b32 m0, s28
	s_nop 0
	global_load_lds_dwordx4 v156, s[24:25]
	s_add_i32 m0, s28, 0x2000
	s_nop 0
	global_load_lds_dwordx4 v160, s[24:25]
	s_mov_b32 m0, s46
	s_nop 0
	global_load_lds_dwordx4 v154, s[100:101]
	s_mov_b32 m0, s47
	s_nop 0
	global_load_lds_dwordx4 v158, s[100:101]
	ds_read_b128 v[180:183], v185 offset:49152
	ds_read_b128 v[188:191], v185 offset:50176
	ds_read_b128 v[192:195], v185 offset:51200
	ds_read_b128 v[196:199], v185 offset:52224
	ds_read_b128 v[200:203], v185 offset:53248
	ds_read_b128 v[204:207], v185 offset:54272
	ds_read_b128 v[208:211], v185 offset:55296
	ds_read_b128 v[212:215], v185 offset:56320
	s_waitcnt vmcnt(8) lgkmcnt(0)
	s_barrier
	v_mfma_f32_16x16x32_bf16 v[58:61], v[130:133], v[180:183], v[58:61]
	v_mfma_f32_16x16x32_bf16 v[54:57], v[138:141], v[180:183], v[54:57]
	v_mfma_f32_16x16x32_bf16 v[42:45], v[130:133], v[192:195], v[42:45]
	v_mfma_f32_16x16x32_bf16 v[34:37], v[138:141], v[192:195], v[34:37]
	v_mfma_f32_16x16x32_bf16 v[26:29], v[130:133], v[200:203], v[26:29]
	v_mfma_f32_16x16x32_bf16 v[18:21], v[138:141], v[200:203], v[18:21]
	v_mfma_f32_16x16x32_bf16 v[6:9], v[130:133], v[208:211], v[6:9]
	v_mfma_f32_16x16x32_bf16 v[2:5], v[138:141], v[208:211], v[2:5]
	v_mfma_f32_16x16x32_bf16 v[58:61], v[134:137], v[188:191], v[58:61]
	v_mfma_f32_16x16x32_bf16 v[54:57], v[142:145], v[188:191], v[54:57]
	v_mfma_f32_16x16x32_bf16 v[42:45], v[134:137], v[196:199], v[42:45]
	v_mfma_f32_16x16x32_bf16 v[34:37], v[142:145], v[196:199], v[34:37]
	v_mfma_f32_16x16x32_bf16 v[26:29], v[134:137], v[204:207], v[26:29]
	v_mfma_f32_16x16x32_bf16 v[18:21], v[142:145], v[204:207], v[18:21]
	v_mfma_f32_16x16x32_bf16 v[6:9], v[134:137], v[212:215], v[6:9]
	v_mfma_f32_16x16x32_bf16 v[2:5], v[142:145], v[212:215], v[2:5]
	v_mfma_f32_16x16x32_bf16 v[62:65], v[146:149], v[180:183], v[62:65]
	v_mfma_f32_16x16x32_bf16 v[50:53], v[172:175], v[180:183], v[50:53]
	v_mfma_f32_16x16x32_bf16 v[46:49], v[146:149], v[192:195], v[46:49]
	v_mfma_f32_16x16x32_bf16 v[38:41], v[172:175], v[192:195], v[38:41]
	v_mfma_f32_16x16x32_bf16 v[30:33], v[146:149], v[200:203], v[30:33]
	v_mfma_f32_16x16x32_bf16 v[22:25], v[172:175], v[200:203], v[22:25]
	v_mfma_f32_16x16x32_bf16 v[10:13], v[146:149], v[208:211], v[10:13]
	v_mfma_f32_16x16x32_bf16 v[14:17], v[172:175], v[208:211], v[14:17]
	v_mfma_f32_16x16x32_bf16 v[62:65], v[150:153], v[188:191], v[62:65]
	v_mfma_f32_16x16x32_bf16 v[50:53], v[176:179], v[188:191], v[50:53]
	v_mfma_f32_16x16x32_bf16 v[46:49], v[150:153], v[196:199], v[46:49]
	v_mfma_f32_16x16x32_bf16 v[38:41], v[176:179], v[196:199], v[38:41]
	v_mfma_f32_16x16x32_bf16 v[30:33], v[150:153], v[204:207], v[30:33]
	v_mfma_f32_16x16x32_bf16 v[22:25], v[176:179], v[204:207], v[22:25]
	v_mfma_f32_16x16x32_bf16 v[10:13], v[150:153], v[212:215], v[10:13]
	v_mfma_f32_16x16x32_bf16 v[14:17], v[176:179], v[212:215], v[14:17]
	s_barrier
	s_add_i32 s68, s68, 2
	s_add_u32 s26, s26, 0x100
	s_addc_u32 s27, s27, 0
	s_add_u32 s66, s66, 0x100
	s_addc_u32 s67, s67, 0
	s_cmp_gt_u32 s68, 61
	s_cbranch_scc0 .LBB0_1039
	s_and_b64 vcc, exec, s[10:11]
	s_cbranch_vccz .LBB0_1042
	s_barrier

; #define PG8_STAGE(bufoff, gbase, voff) do { _Pragma("unroll") for (int _i = 0; _i < 2; ++_i) \
;         __builtin_amdgcn_global_load_lds((const unsigned*)((const char*)(gbase) + (voff)[_i]), (PG8_LAS unsigned*)(lds + (bufoff) + ldsw + _i * 8192), 16, 0, 0); } while (0)
; #define PG8_LDA(dst, b, h) do { _Pragma("unroll") for (int m = 0; m < 4; ++m) _Pragma("unroll") for (int k = 0; k < 2; ++k) dst[m][k] = *(const PG8_LAS bf16x8*)(lds + PG8_SA(b, h) + aoff + m * 2048 + k * 1024); } while (0)
; #define PG8_LDB(dst, b, h) do { _Pragma("unroll") for (int n = 0; n < 2; ++n) _Pragma("unroll") for (int k = 0; k < 2; ++k) dst[n][k] = *(const PG8_LAS bf16x8*)(lds + PG8_SB(b, h) + boff + n * 2048 + k * 1024); } while (0)
; #define PG8_MMA(ai, bj, At, Bt) do { __builtin_amdgcn_s_setprio(1); _Pragma("unroll") for (int m = 0; m < 4; ++m) _Pragma("unroll") for (int n = 0; n < 2; ++n) _Pragma("unroll") for (int k = 0; k < 2; ++k) \
;         acc[ai][bj][m][n] = __builtin_amdgcn_mfma_f32_16x16x32_bf16(Bt[n][k], At[m][k], acc[ai][bj][m][n], 0, 0, 0); __builtin_amdgcn_s_setprio(0); } while (0)
; #define PG8_WAIT_V(n) asm volatile("s_waitcnt vmcnt(" #n ")" ::: "memory")
; #define PG8_WAIT_L(n) asm volatile("s_waitcnt lgkmcnt(" #n ")" ::: "memory")
; #define PG8_BAR __builtin_amdgcn_s_barrier()
; #define PG8_SCHED __builtin_amdgcn_sched_barrier(0)
; template <class Epi, class Sched, bool ALIGN_EPI = false, bool SP2 = false>
; __device__ __forceinline__ void gemm_phase(PG8_LAS unsigned char* lds, const Gemm g, const Sched& S, const Epi& E) {
;     ...
;             const bool last = (t == nt - 2);
;             const char* a1 = cA + (size_t)(t + 1) * kstep;
;             const char* a2 = last ? nA : cA + (size_t)(t + 2) * kstep; const char* b2 = last ? nB : cB + (size_t)(t + 2) * kstep;
;             const char* a3 = a2 + kstep; const char* b3 = b2 + kstep;
;     ...
;             PG8_LDB(B0, 0, 0); PG8_LDB(B1, 0, 1); PG8_SCHED; PG8_LDA(At, 0, 0); PG8_STAGE(PG8_SA(1, 1), a1 + hstep, voffA);
;             PG8_WAIT_V(8); PG8_WAIT_L(0); PG8_BAR; PG8_MMA(0, 0, At, B0); PG8_MMA(0, 1, At, B1); PG8_BAR; PG8_SCHED;
;             PG8_LDA(At, 0, 1); PG8_STAGE(PG8_SB(0, 0), b2, voffB); PG8_STAGE(PG8_SB(0, 1), b2 + hstep, voffB); PG8_STAGE(PG8_SA(0, 0), a2, voffA);
;             PG8_WAIT_V(8); PG8_WAIT_L(0); PG8_BAR; PG8_MMA(1, 0, At, B0); PG8_MMA(1, 1, At, B1); PG8_BAR; PG8_SCHED;
.LBB0_1126:
	s_add_u32 s22, s24, 0xfff00080
	s_addc_u32 s23, s25, -1
	s_cmp_eq_u32 s68, 60
	s_cselect_b32 s27, s15, s23
	s_cselect_b32 s26, s64, s22
	s_cselect_b32 s23, s13, s67
	s_cselect_b32 s22, s65, s66
	s_add_i32 m0, s21, 0xc000
	s_nop 0
	global_load_lds_dwordx4 v138, s[24:25]
	s_add_i32 m0, s21, 0xe000
	s_nop 0
	global_load_lds_dwordx4 v140, s[24:25]
	ds_read_b128 v[160:163], v241 offset:0
	ds_read_b128 v[166:169], v241 offset:1024
	ds_read_b128 v[170:173], v241 offset:2048
	ds_read_b128 v[174:177], v241 offset:3072
	ds_read_b128 v[178:181], v241 offset:16384
	ds_read_b128 v[182:185], v241 offset:17408
	ds_read_b128 v[186:189], v241 offset:18432
	ds_read_b128 v[190:193], v241 offset:19456
	ds_read_b128 v[194:197], v155
	ds_read_b128 v[198:201], v155 offset:1024
	ds_read_b128 v[202:205], v155 offset:2048
	ds_read_b128 v[206:209], v155 offset:3072
	ds_read_b128 v[210:213], v155 offset:4096
	ds_read_b128 v[214:217], v155 offset:5120
	ds_read_b128 v[218:221], v155 offset:6144
	ds_read_b128 v[222:225], v155 offset:7168
	s_waitcnt vmcnt(8) lgkmcnt(0)
	s_barrier
	v_mfma_f32_16x16x32_bf16 v[122:125], v[160:163], v[194:197], v[122:125]
	v_mfma_f32_16x16x32_bf16 v[114:117], v[170:173], v[194:197], v[114:117]
	v_mfma_f32_16x16x32_bf16 v[106:109], v[160:163], v[202:205], v[106:109]
	v_mfma_f32_16x16x32_bf16 v[98:101], v[170:173], v[202:205], v[98:101]
	v_mfma_f32_16x16x32_bf16 v[90:93], v[160:163], v[210:213], v[90:93]
	v_mfma_f32_16x16x32_bf16 v[82:85], v[170:173], v[210:213], v[82:85]
	v_mfma_f32_16x16x32_bf16 v[74:77], v[160:163], v[218:221], v[74:77]
	v_mfma_f32_16x16x32_bf16 v[62:65], v[170:173], v[218:221], v[62:65]
	v_mfma_f32_16x16x32_bf16 v[122:125], v[166:169], v[198:201], v[122:125]
	v_mfma_f32_16x16x32_bf16 v[114:117], v[174:177], v[198:201], v[114:117]
	v_mfma_f32_16x16x32_bf16 v[106:109], v[166:169], v[206:209], v[106:109]
	v_mfma_f32_16x16x32_bf16 v[98:101], v[174:177], v[206:209], v[98:101]
	v_mfma_f32_16x16x32_bf16 v[90:93], v[166:169], v[214:217], v[90:93]
	v_mfma_f32_16x16x32_bf16 v[82:85], v[174:177], v[214:217], v[82:85]
	v_mfma_f32_16x16x32_bf16 v[74:77], v[166:169], v[222:225], v[74:77]
	v_mfma_f32_16x16x32_bf16 v[62:65], v[174:177], v[222:225], v[62:65]
	v_mfma_f32_16x16x32_bf16 v[126:129], v[178:181], v[194:197], v[126:129]
	v_mfma_f32_16x16x32_bf16 v[118:121], v[186:189], v[194:197], v[118:121]
	v_mfma_f32_16x16x32_bf16 v[110:113], v[178:181], v[202:205], v[110:113]
	v_mfma_f32_16x16x32_bf16 v[102:105], v[186:189], v[202:205], v[102:105]
	v_mfma_f32_16x16x32_bf16 v[94:97], v[178:181], v[210:213], v[94:97]
	v_mfma_f32_16x16x32_bf16 v[86:89], v[186:189], v[210:213], v[86:89]
	v_mfma_f32_16x16x32_bf16 v[78:81], v[178:181], v[218:221], v[78:81]
	v_mfma_f32_16x16x32_bf16 v[70:73], v[186:189], v[218:221], v[70:73]
	v_mfma_f32_16x16x32_bf16 v[126:129], v[182:185], v[198:201], v[126:129]
	v_mfma_f32_16x16x32_bf16 v[118:121], v[190:193], v[198:201], v[118:121]
	v_mfma_f32_16x16x32_bf16 v[110:113], v[182:185], v[206:209], v[110:113]
	v_mfma_f32_16x16x32_bf16 v[102:105], v[190:193], v[206:209], v[102:105]
	v_mfma_f32_16x16x32_bf16 v[94:97], v[182:185], v[214:217], v[94:97]
	v_mfma_f32_16x16x32_bf16 v[86:89], v[190:193], v[214:217], v[86:89]
	v_mfma_f32_16x16x32_bf16 v[78:81], v[182:185], v[222:225], v[78:81]
	v_mfma_f32_16x16x32_bf16 v[70:73], v[190:193], v[222:225], v[70:73]
	s_barrier
	s_add_i32 s33, s52, s29
	s_mov_b32 m0, s33
	s_nop 0
	global_load_lds_dwordx4 v132, s[22:23]
	s_add_i32 m0, s33, 0x2000
	s_add_u32 s72, s22, 0x100000
	s_addc_u32 s73, s23, 0
	s_add_i32 s33, s53, s29
	global_load_lds_dwordx4 v136, s[22:23]
	s_mov_b32 m0, s33
	s_add_u32 s100, s26, 0x80
	s_addc_u32 s101, s27, 0
	global_load_lds_dwordx4 v132, s[72:73]
	s_add_i32 m0, s33, 0x2000
	s_nop 0
	global_load_lds_dwordx4 v136, s[72:73]
	s_mov_b32 m0, s21
	s_nop 0
	global_load_lds_dwordx4 v130, s[26:27]
	s_mov_b32 m0, s36
	s_nop 0
	global_load_lds_dwordx4 v134, s[26:27]
	ds_read_b128 v[194:197], v155 offset:16384
	ds_read_b128 v[198:201], v155 offset:17408
	ds_read_b128 v[202:205], v155 offset:18432
	ds_read_b128 v[206:209], v155 offset:19456
	ds_read_b128 v[210:213], v155 offset:20480
	ds_read_b128 v[214:217], v155 offset:21504
	ds_read_b128 v[218:221], v155 offset:22528
	ds_read_b128 v[222:225], v155 offset:23552
	s_waitcnt vmcnt(8) lgkmcnt(0)
	s_barrier
	v_mfma_f32_16x16x32_bf16 v[58:61], v[160:163], v[194:197], v[58:61]
	v_mfma_f32_16x16x32_bf16 v[50:53], v[170:173], v[194:197], v[50:53]
	v_mfma_f32_16x16x32_bf16 v[42:45], v[160:163], v[202:205], v[42:45]
	v_mfma_f32_16x16x32_bf16 v[34:37], v[170:173], v[202:205], v[34:37]
	v_mfma_f32_16x16x32_bf16 v[26:29], v[160:163], v[210:213], v[26:29]
	v_mfma_f32_16x16x32_bf16 v[18:21], v[170:173], v[210:213], v[18:21]
	v_mfma_f32_16x16x32_bf16 v[10:13], v[160:163], v[218:221], v[10:13]
	v_mfma_f32_16x16x32_bf16 v[2:5], v[170:173], v[218:221], v[2:5]
	v_mfma_f32_16x16x32_bf16 v[58:61], v[166:169], v[198:201], v[58:61]
	v_mfma_f32_16x16x32_bf16 v[50:53], v[174:177], v[198:201], v[50:53]
	v_mfma_f32_16x16x32_bf16 v[42:45], v[166:169], v[206:209], v[42:45]
	v_mfma_f32_16x16x32_bf16 v[34:37], v[174:177], v[206:209], v[34:37]
	v_mfma_f32_16x16x32_bf16 v[26:29], v[166:169], v[214:217], v[26:29]
	v_mfma_f32_16x16x32_bf16 v[18:21], v[174:177], v[214:217], v[18:21]
	v_mfma_f32_16x16x32_bf16 v[10:13], v[166:169], v[222:225], v[10:13]
	v_mfma_f32_16x16x32_bf16 v[2:5], v[174:177], v[222:225], v[2:5]
	v_mfma_f32_16x16x32_bf16 v[66:69], v[178:181], v[194:197], v[66:69]
	v_mfma_f32_16x16x32_bf16 v[54:57], v[186:189], v[194:197], v[54:57]
	v_mfma_f32_16x16x32_bf16 v[46:49], v[178:181], v[202:205], v[46:49]
	v_mfma_f32_16x16x32_bf16 v[38:41], v[186:189], v[202:205], v[38:41]
	v_mfma_f32_16x16x32_bf16 v[30:33], v[178:181], v[210:213], v[30:33]
	v_mfma_f32_16x16x32_bf16 v[22:25], v[186:189], v[210:213], v[22:25]
	v_mfma_f32_16x16x32_bf16 v[14:17], v[178:181], v[218:221], v[14:17]
	v_mfma_f32_16x16x32_bf16 v[6:9], v[186:189], v[218:221], v[6:9]
	v_mfma_f32_16x16x32_bf16 v[66:69], v[182:185], v[198:201], v[66:69]
	v_mfma_f32_16x16x32_bf16 v[54:57], v[190:193], v[198:201], v[54:57]
	v_mfma_f32_16x16x32_bf16 v[46:49], v[182:185], v[206:209], v[46:49]
	v_mfma_f32_16x16x32_bf16 v[38:41], v[190:193], v[206:209], v[38:41]
	v_mfma_f32_16x16x32_bf16 v[30:33], v[182:185], v[214:217], v[30:33]
	v_mfma_f32_16x16x32_bf16 v[22:25], v[190:193], v[214:217], v[22:25]
	v_mfma_f32_16x16x32_bf16 v[14:17], v[182:185], v[222:225], v[14:17]
	v_mfma_f32_16x16x32_bf16 v[6:9], v[190:193], v[222:225], v[6:9]
	s_barrier
; #define PG8_STAGE(bufoff, gbase, voff) do { _Pragma("unroll") for (int _i = 0; _i < 2; ++_i) \
;         __builtin_amdgcn_global_load_lds((const unsigned*)((const char*)(gbase) + (voff)[_i]), (PG8_LAS unsigned*)(lds + (bufoff) + ldsw + _i * 8192), 16, 0, 0); } while (0)
; #define PG8_LDA(dst, b, h) do { _Pragma("unroll") for (int m = 0; m < 4; ++m) _Pragma("unroll") for (int k = 0; k < 2; ++k) dst[m][k] = *(const PG8_LAS bf16x8*)(lds + PG8_SA(b, h) + aoff + m * 2048 + k * 1024); } while (0)
; #define PG8_LDB(dst, b, h) do { _Pragma("unroll") for (int n = 0; n < 2; ++n) _Pragma("unroll") for (int k = 0; k < 2; ++k) dst[n][k] = *(const PG8_LAS bf16x8*)(lds + PG8_SB(b, h) + boff + n * 2048 + k * 1024); } while (0)
; #define PG8_MMA(ai, bj, At, Bt) do { __builtin_amdgcn_s_setprio(1); _Pragma("unroll") for (int m = 0; m < 4; ++m) _Pragma("unroll") for (int n = 0; n < 2; ++n) _Pragma("unroll") for (int k = 0; k < 2; ++k) \
;         acc[ai][bj][m][n] = __builtin_amdgcn_mfma_f32_16x16x32_bf16(Bt[n][k], At[m][k], acc[ai][bj][m][n], 0, 0, 0); __builtin_amdgcn_s_setprio(0); } while (0)
; #define PG8_WAIT_V(n) asm volatile("s_waitcnt vmcnt(" #n ")" ::: "memory")
; #define PG8_WAIT_L(n) asm volatile("s_waitcnt lgkmcnt(" #n ")" ::: "memory")
; template <class Epi, class Sched, bool ALIGN_EPI = false, bool SP2 = false>
; __device__ __forceinline__ void gemm_phase(PG8_LAS unsigned char* lds, const Gemm g, const Sched& S, const Epi& E) {
;     ...
;         for (int t = 0; t < nt; t += 2) {
;             const bool last = (t == nt - 2);
;             const char* a1 = cA + (size_t)(t + 1) * kstep;
;             const char* a2 = last ? nA : cA + (size_t)(t + 2) * kstep; const char* b2 = last ? nB : cB + (size_t)(t + 2) * kstep;
;             const char* a3 = a2 + kstep; const char* b3 = b2 + kstep;
;             if (last && has_next) S.a_ready(nxt);
;     ...
;             PG8_LDB(B0, 1, 0); PG8_LDB(B1, 1, 1); PG8_SCHED; PG8_LDA(At, 1, 0); PG8_STAGE(PG8_SA(0, 1), a2 + hstep, voffA);
;             PG8_WAIT_V(8); PG8_WAIT_L(0); PG8_BAR; PG8_MMA(0, 0, At, B0); PG8_MMA(0, 1, At, B1); PG8_BAR; PG8_SCHED;
;             PG8_LDA(At, 1, 1); PG8_STAGE(PG8_SB(1, 0), b3, voffB); PG8_STAGE(PG8_SB(1, 1), b3 + hstep, voffB); PG8_STAGE(PG8_SA(1, 0), a3, voffA);
;             PG8_WAIT_V(8); PG8_WAIT_L(0); PG8_BAR; PG8_MMA(1, 0, At, B0); PG8_MMA(1, 1, At, B1); PG8_BAR; PG8_SCHED;
	s_add_i32 s33, 0, 0x18000
	s_add_i32 s42, 0, 0x1c000
	s_add_u32 s26, s26, 0x100000
	s_addc_u32 s27, s27, 0
	s_mov_b32 m0, s37
	s_nop 0
	global_load_lds_dwordx4 v130, s[26:27]
	s_mov_b32 m0, s40
	s_nop 0
	global_load_lds_dwordx4 v134, s[26:27]
	ds_read_b128 v[160:163], v241 offset:32768
	ds_read_b128 v[166:169], v241 offset:33792
	ds_read_b128 v[170:173], v241 offset:34816
	ds_read_b128 v[174:177], v241 offset:35840
	ds_read_b128 v[178:181], v241 offset:49152
	ds_read_b128 v[182:185], v241 offset:50176
	ds_read_b128 v[186:189], v241 offset:51200
	ds_read_b128 v[190:193], v241 offset:52224
	ds_read_b128 v[194:197], v155 offset:32768
	ds_read_b128 v[198:201], v155 offset:33792
	ds_read_b128 v[202:205], v155 offset:34816
	ds_read_b128 v[206:209], v155 offset:35840
	ds_read_b128 v[210:213], v155 offset:36864
	ds_read_b128 v[214:217], v155 offset:37888
	ds_read_b128 v[218:221], v155 offset:38912
	ds_read_b128 v[222:225], v155 offset:39936
	s_waitcnt vmcnt(8) lgkmcnt(0)
	s_barrier
	v_mfma_f32_16x16x32_bf16 v[122:125], v[160:163], v[194:197], v[122:125]
	v_mfma_f32_16x16x32_bf16 v[114:117], v[170:173], v[194:197], v[114:117]
	v_mfma_f32_16x16x32_bf16 v[106:109], v[160:163], v[202:205], v[106:109]
	v_mfma_f32_16x16x32_bf16 v[98:101], v[170:173], v[202:205], v[98:101]
	v_mfma_f32_16x16x32_bf16 v[90:93], v[160:163], v[210:213], v[90:93]
	v_mfma_f32_16x16x32_bf16 v[82:85], v[170:173], v[210:213], v[82:85]
	v_mfma_f32_16x16x32_bf16 v[74:77], v[160:163], v[218:221], v[74:77]
	v_mfma_f32_16x16x32_bf16 v[62:65], v[170:173], v[218:221], v[62:65]
	v_mfma_f32_16x16x32_bf16 v[122:125], v[166:169], v[198:201], v[122:125]
	v_mfma_f32_16x16x32_bf16 v[114:117], v[174:177], v[198:201], v[114:117]
	v_mfma_f32_16x16x32_bf16 v[106:109], v[166:169], v[206:209], v[106:109]
	v_mfma_f32_16x16x32_bf16 v[98:101], v[174:177], v[206:209], v[98:101]
	v_mfma_f32_16x16x32_bf16 v[90:93], v[166:169], v[214:217], v[90:93]
	v_mfma_f32_16x16x32_bf16 v[82:85], v[174:177], v[214:217], v[82:85]
	v_mfma_f32_16x16x32_bf16 v[74:77], v[166:169], v[222:225], v[74:77]
	v_mfma_f32_16x16x32_bf16 v[62:65], v[174:177], v[222:225], v[62:65]
	v_mfma_f32_16x16x32_bf16 v[126:129], v[178:181], v[194:197], v[126:129]
	v_mfma_f32_16x16x32_bf16 v[118:121], v[186:189], v[194:197], v[118:121]
	v_mfma_f32_16x16x32_bf16 v[110:113], v[178:181], v[202:205], v[110:113]
	v_mfma_f32_16x16x32_bf16 v[102:105], v[186:189], v[202:205], v[102:105]
	v_mfma_f32_16x16x32_bf16 v[94:97], v[178:181], v[210:213], v[94:97]
	v_mfma_f32_16x16x32_bf16 v[86:89], v[186:189], v[210:213], v[86:89]
	v_mfma_f32_16x16x32_bf16 v[78:81], v[178:181], v[218:221], v[78:81]
	v_mfma_f32_16x16x32_bf16 v[70:73], v[186:189], v[218:221], v[70:73]
	v_mfma_f32_16x16x32_bf16 v[126:129], v[182:185], v[198:201], v[126:129]
	v_mfma_f32_16x16x32_bf16 v[118:121], v[190:193], v[198:201], v[118:121]
	v_mfma_f32_16x16x32_bf16 v[110:113], v[182:185], v[206:209], v[110:113]
	v_mfma_f32_16x16x32_bf16 v[102:105], v[190:193], v[206:209], v[102:105]
	v_mfma_f32_16x16x32_bf16 v[94:97], v[182:185], v[214:217], v[94:97]
	v_mfma_f32_16x16x32_bf16 v[86:89], v[190:193], v[214:217], v[86:89]
	v_mfma_f32_16x16x32_bf16 v[78:81], v[182:185], v[222:225], v[78:81]
	v_mfma_f32_16x16x32_bf16 v[70:73], v[190:193], v[222:225], v[70:73]
	s_barrier
	s_add_i32 s26, s33, s29
	s_add_i32 m0, s26, 0xffffff80
	s_nop 0
	global_load_lds_dwordx4 v132, s[22:23] offset:128
	s_add_i32 m0, s26, 0x1f80
	s_add_i32 s26, s42, s29
	global_load_lds_dwordx4 v136, s[22:23] offset:128
	s_add_u32 s22, s22, 0x100080
	s_addc_u32 s23, s23, 0
	s_mov_b32 m0, s26
	s_nop 0
	global_load_lds_dwordx4 v132, s[22:23]
	s_add_i32 m0, s26, 0x2000
	s_nop 0
	global_load_lds_dwordx4 v136, s[22:23]
	s_mov_b32 m0, s46
	s_nop 0
	global_load_lds_dwordx4 v130, s[100:101]
	s_mov_b32 m0, s47
	s_nop 0
	global_load_lds_dwordx4 v134, s[100:101]
	ds_read_b128 v[194:197], v155 offset:49152
	ds_read_b128 v[198:201], v155 offset:50176
	ds_read_b128 v[202:205], v155 offset:51200
	ds_read_b128 v[206:209], v155 offset:52224
	ds_read_b128 v[210:213], v155 offset:53248
	ds_read_b128 v[214:217], v155 offset:54272
	ds_read_b128 v[218:221], v155 offset:55296
	ds_read_b128 v[222:225], v155 offset:56320
	s_waitcnt vmcnt(8) lgkmcnt(0)
	s_barrier
	v_mfma_f32_16x16x32_bf16 v[58:61], v[160:163], v[194:197], v[58:61]
	v_mfma_f32_16x16x32_bf16 v[50:53], v[170:173], v[194:197], v[50:53]
	v_mfma_f32_16x16x32_bf16 v[42:45], v[160:163], v[202:205], v[42:45]
	v_mfma_f32_16x16x32_bf16 v[34:37], v[170:173], v[202:205], v[34:37]
	v_mfma_f32_16x16x32_bf16 v[26:29], v[160:163], v[210:213], v[26:29]
	v_mfma_f32_16x16x32_bf16 v[18:21], v[170:173], v[210:213], v[18:21]
	v_mfma_f32_16x16x32_bf16 v[10:13], v[160:163], v[218:221], v[10:13]
	v_mfma_f32_16x16x32_bf16 v[2:5], v[170:173], v[218:221], v[2:5]
	v_mfma_f32_16x16x32_bf16 v[58:61], v[166:169], v[198:201], v[58:61]
	v_mfma_f32_16x16x32_bf16 v[50:53], v[174:177], v[198:201], v[50:53]
	v_mfma_f32_16x16x32_bf16 v[42:45], v[166:169], v[206:209], v[42:45]
	v_mfma_f32_16x16x32_bf16 v[34:37], v[174:177], v[206:209], v[34:37]
	v_mfma_f32_16x16x32_bf16 v[26:29], v[166:169], v[214:217], v[26:29]
	v_mfma_f32_16x16x32_bf16 v[18:21], v[174:177], v[214:217], v[18:21]
	v_mfma_f32_16x16x32_bf16 v[10:13], v[166:169], v[222:225], v[10:13]
	v_mfma_f32_16x16x32_bf16 v[2:5], v[174:177], v[222:225], v[2:5]
	v_mfma_f32_16x16x32_bf16 v[66:69], v[178:181], v[194:197], v[66:69]
	v_mfma_f32_16x16x32_bf16 v[54:57], v[186:189], v[194:197], v[54:57]
	v_mfma_f32_16x16x32_bf16 v[46:49], v[178:181], v[202:205], v[46:49]
	v_mfma_f32_16x16x32_bf16 v[38:41], v[186:189], v[202:205], v[38:41]
	v_mfma_f32_16x16x32_bf16 v[30:33], v[178:181], v[210:213], v[30:33]
	v_mfma_f32_16x16x32_bf16 v[22:25], v[186:189], v[210:213], v[22:25]
	v_mfma_f32_16x16x32_bf16 v[14:17], v[178:181], v[218:221], v[14:17]
	v_mfma_f32_16x16x32_bf16 v[6:9], v[186:189], v[218:221], v[6:9]
	v_mfma_f32_16x16x32_bf16 v[66:69], v[182:185], v[198:201], v[66:69]
	v_mfma_f32_16x16x32_bf16 v[54:57], v[190:193], v[198:201], v[54:57]
	v_mfma_f32_16x16x32_bf16 v[46:49], v[182:185], v[206:209], v[46:49]
	v_mfma_f32_16x16x32_bf16 v[38:41], v[190:193], v[206:209], v[38:41]
	v_mfma_f32_16x16x32_bf16 v[30:33], v[182:185], v[214:217], v[30:33]
	v_mfma_f32_16x16x32_bf16 v[22:25], v[190:193], v[214:217], v[22:25]
	v_mfma_f32_16x16x32_bf16 v[14:17], v[182:185], v[222:225], v[14:17]
	v_mfma_f32_16x16x32_bf16 v[6:9], v[190:193], v[222:225], v[6:9]
	s_barrier
	s_add_i32 s68, s68, 2
	s_add_u32 s24, s24, 0x100
	s_addc_u32 s25, s25, 0
	s_add_u32 s66, s66, 0x100
	s_addc_u32 s67, s67, 0
	s_cmp_gt_u32 s68, 61
	s_cbranch_scc0 .LBB0_1126
	s_and_b64 vcc, exec, s[8:9]
	s_cbranch_vccz .LBB0_1129
	s_barrier

; #define PG8_STAGE(bufoff, gbase, voff) do { _Pragma("unroll") for (int _i = 0; _i < 2; ++_i) \
;         __builtin_amdgcn_global_load_lds((const unsigned*)((const char*)(gbase) + (voff)[_i]), (PG8_LAS unsigned*)(lds + (bufoff) + ldsw + _i * 8192), 16, 0, 0); } while (0)
; #define PG8_LDA(dst, b, h) do { _Pragma("unroll") for (int m = 0; m < 4; ++m) _Pragma("unroll") for (int k = 0; k < 2; ++k) dst[m][k] = *(const PG8_LAS bf16x8*)(lds + PG8_SA(b, h) + aoff + m * 2048 + k * 1024); } while (0)
; #define PG8_LDB(dst, b, h) do { _Pragma("unroll") for (int n = 0; n < 2; ++n) _Pragma("unroll") for (int k = 0; k < 2; ++k) dst[n][k] = *(const PG8_LAS bf16x8*)(lds + PG8_SB(b, h) + boff + n * 2048 + k * 1024); } while (0)
; #define PG8_MMA(ai, bj, At, Bt) do { __builtin_amdgcn_s_setprio(1); _Pragma("unroll") for (int m = 0; m < 4; ++m) _Pragma("unroll") for (int n = 0; n < 2; ++n) _Pragma("unroll") for (int k = 0; k < 2; ++k) \
;         acc[ai][bj][m][n] = __builtin_amdgcn_mfma_f32_16x16x32_bf16(Bt[n][k], At[m][k], acc[ai][bj][m][n], 0, 0, 0); __builtin_amdgcn_s_setprio(0); } while (0)
; #define PG8_WAIT_V(n) asm volatile("s_waitcnt vmcnt(" #n ")" ::: "memory")
; #define PG8_WAIT_L(n) asm volatile("s_waitcnt lgkmcnt(" #n ")" ::: "memory")
; #define PG8_BAR __builtin_amdgcn_s_barrier()
; #define PG8_SCHED __builtin_amdgcn_sched_barrier(0)
; template <class Epi, class Sched, bool ALIGN_EPI = false, bool SP2 = false>
; __device__ __forceinline__ void gemm_phase(PG8_LAS unsigned char* lds, const Gemm g, const Sched& S, const Epi& E) {
;     ...
;             PG8_LDB(B0, 0, 0); PG8_LDB(B1, 0, 1); PG8_SCHED; PG8_LDA(At, 0, 0); PG8_STAGE(PG8_SA(1, 1), a1 + hstep, voffA);
;             PG8_WAIT_V(8); PG8_WAIT_L(0); PG8_BAR; PG8_MMA(0, 0, At, B0); PG8_MMA(0, 1, At, B1); PG8_BAR; PG8_SCHED;
;             PG8_LDA(At, 0, 1); PG8_STAGE(PG8_SB(0, 0), b2, voffB); PG8_STAGE(PG8_SB(0, 1), b2 + hstep, voffB); PG8_STAGE(PG8_SA(0, 0), a2, voffA);
;             PG8_WAIT_V(8); PG8_WAIT_L(0); PG8_BAR; PG8_MMA(1, 0, At, B0); PG8_MMA(1, 1, At, B1); PG8_BAR; PG8_SCHED;
.LBB0_1245:
	s_add_u32 s16, s18, 0xffd50080
	s_addc_u32 s17, s19, -1
	s_cmpk_eq_i32 s64, 0xa8
	s_cselect_b32 s21, s5, s17
	s_cselect_b32 s20, s4, s16
	s_cselect_b32 s17, s15, s63
	s_cselect_b32 s16, s14, s62
	s_add_i32 m0, s25, 0xc000
	s_nop 0
	global_load_lds_dwordx4 v162, s[18:19]
	s_add_i32 m0, s25, 0xe000
	s_nop 0
	global_load_lds_dwordx4 v166, s[18:19]
	ds_read_b128 v[130:133], v241 offset:0
	ds_read_b128 v[134:137], v241 offset:1024
	ds_read_b128 v[138:141], v241 offset:2048
	ds_read_b128 v[142:145], v241 offset:3072
	ds_read_b128 v[146:149], v241 offset:16384
	ds_read_b128 v[150:153], v241 offset:17408
	ds_read_b128 v[172:175], v241 offset:18432
	ds_read_b128 v[176:179], v241 offset:19456
	ds_read_b128 v[180:183], v185
	ds_read_b128 v[188:191], v185 offset:1024
	ds_read_b128 v[192:195], v185 offset:2048
	ds_read_b128 v[196:199], v185 offset:3072
	ds_read_b128 v[200:203], v185 offset:4096
	ds_read_b128 v[204:207], v185 offset:5120
	ds_read_b128 v[208:211], v185 offset:6144
	ds_read_b128 v[212:215], v185 offset:7168
	s_waitcnt vmcnt(8) lgkmcnt(0)
	s_barrier
	v_mfma_f32_16x16x32_bf16 v[114:117], v[130:133], v[180:183], v[114:117]
	v_mfma_f32_16x16x32_bf16 v[118:121], v[138:141], v[180:183], v[118:121]
	v_mfma_f32_16x16x32_bf16 v[106:109], v[130:133], v[192:195], v[106:109]
	v_mfma_f32_16x16x32_bf16 v[98:101], v[138:141], v[192:195], v[98:101]
	v_mfma_f32_16x16x32_bf16 v[90:93], v[130:133], v[200:203], v[90:93]
	v_mfma_f32_16x16x32_bf16 v[82:85], v[138:141], v[200:203], v[82:85]
	v_mfma_f32_16x16x32_bf16 v[74:77], v[130:133], v[208:211], v[74:77]
	v_mfma_f32_16x16x32_bf16 v[66:69], v[138:141], v[208:211], v[66:69]
	v_mfma_f32_16x16x32_bf16 v[114:117], v[134:137], v[188:191], v[114:117]
	v_mfma_f32_16x16x32_bf16 v[118:121], v[142:145], v[188:191], v[118:121]
	v_mfma_f32_16x16x32_bf16 v[106:109], v[134:137], v[196:199], v[106:109]
	v_mfma_f32_16x16x32_bf16 v[98:101], v[142:145], v[196:199], v[98:101]
	v_mfma_f32_16x16x32_bf16 v[90:93], v[134:137], v[204:207], v[90:93]
	v_mfma_f32_16x16x32_bf16 v[82:85], v[142:145], v[204:207], v[82:85]
	v_mfma_f32_16x16x32_bf16 v[74:77], v[134:137], v[212:215], v[74:77]
	v_mfma_f32_16x16x32_bf16 v[66:69], v[142:145], v[212:215], v[66:69]
	v_mfma_f32_16x16x32_bf16 v[122:125], v[146:149], v[180:183], v[122:125]
	v_mfma_f32_16x16x32_bf16 v[126:129], v[172:175], v[180:183], v[126:129]
	v_mfma_f32_16x16x32_bf16 v[110:113], v[146:149], v[192:195], v[110:113]
	v_mfma_f32_16x16x32_bf16 v[102:105], v[172:175], v[192:195], v[102:105]
	v_mfma_f32_16x16x32_bf16 v[94:97], v[146:149], v[200:203], v[94:97]
	v_mfma_f32_16x16x32_bf16 v[86:89], v[172:175], v[200:203], v[86:89]
	v_mfma_f32_16x16x32_bf16 v[78:81], v[146:149], v[208:211], v[78:81]
	v_mfma_f32_16x16x32_bf16 v[70:73], v[172:175], v[208:211], v[70:73]
	v_mfma_f32_16x16x32_bf16 v[122:125], v[150:153], v[188:191], v[122:125]
	v_mfma_f32_16x16x32_bf16 v[126:129], v[176:179], v[188:191], v[126:129]
	v_mfma_f32_16x16x32_bf16 v[110:113], v[150:153], v[196:199], v[110:113]
	v_mfma_f32_16x16x32_bf16 v[102:105], v[176:179], v[196:199], v[102:105]
	v_mfma_f32_16x16x32_bf16 v[94:97], v[150:153], v[204:207], v[94:97]
	v_mfma_f32_16x16x32_bf16 v[86:89], v[176:179], v[204:207], v[86:89]
	v_mfma_f32_16x16x32_bf16 v[78:81], v[150:153], v[212:215], v[78:81]
	v_mfma_f32_16x16x32_bf16 v[70:73], v[176:179], v[212:215], v[70:73]
	s_barrier
	s_add_i32 s33, s40, s24
	s_mov_b32 m0, s33
	s_nop 0
	global_load_lds_dwordx4 v156, s[16:17]
	s_add_i32 m0, s33, 0x2000
	s_add_u32 s66, s16, 0x2b0000
	s_addc_u32 s67, s17, 0
	s_add_i32 s33, s41, s24
	global_load_lds_dwordx4 v160, s[16:17]
	s_mov_b32 m0, s33
	s_add_u32 s100, s20, 0x80
	s_addc_u32 s101, s21, 0
	global_load_lds_dwordx4 v156, s[66:67]
	s_add_i32 m0, s33, 0x2000
	s_nop 0
	global_load_lds_dwordx4 v160, s[66:67]
	s_mov_b32 m0, s25
	s_nop 0
	global_load_lds_dwordx4 v154, s[20:21]
	s_mov_b32 m0, s26
	s_nop 0
	global_load_lds_dwordx4 v158, s[20:21]
	ds_read_b128 v[180:183], v185 offset:16384
	ds_read_b128 v[188:191], v185 offset:17408
	ds_read_b128 v[192:195], v185 offset:18432
	ds_read_b128 v[196:199], v185 offset:19456
	ds_read_b128 v[200:203], v185 offset:20480
	ds_read_b128 v[204:207], v185 offset:21504
	ds_read_b128 v[208:211], v185 offset:22528
	ds_read_b128 v[212:215], v185 offset:23552
	s_waitcnt vmcnt(8) lgkmcnt(0)
	s_barrier
	v_mfma_f32_16x16x32_bf16 v[58:61], v[130:133], v[180:183], v[58:61]
	v_mfma_f32_16x16x32_bf16 v[54:57], v[138:141], v[180:183], v[54:57]
	v_mfma_f32_16x16x32_bf16 v[42:45], v[130:133], v[192:195], v[42:45]
	v_mfma_f32_16x16x32_bf16 v[34:37], v[138:141], v[192:195], v[34:37]
	v_mfma_f32_16x16x32_bf16 v[26:29], v[130:133], v[200:203], v[26:29]
	v_mfma_f32_16x16x32_bf16 v[18:21], v[138:141], v[200:203], v[18:21]
	v_mfma_f32_16x16x32_bf16 v[6:9], v[130:133], v[208:211], v[6:9]
	v_mfma_f32_16x16x32_bf16 v[2:5], v[138:141], v[208:211], v[2:5]
	v_mfma_f32_16x16x32_bf16 v[58:61], v[134:137], v[188:191], v[58:61]
	v_mfma_f32_16x16x32_bf16 v[54:57], v[142:145], v[188:191], v[54:57]
	v_mfma_f32_16x16x32_bf16 v[42:45], v[134:137], v[196:199], v[42:45]
	v_mfma_f32_16x16x32_bf16 v[34:37], v[142:145], v[196:199], v[34:37]
	v_mfma_f32_16x16x32_bf16 v[26:29], v[134:137], v[204:207], v[26:29]
	v_mfma_f32_16x16x32_bf16 v[18:21], v[142:145], v[204:207], v[18:21]
	v_mfma_f32_16x16x32_bf16 v[6:9], v[134:137], v[212:215], v[6:9]
	v_mfma_f32_16x16x32_bf16 v[2:5], v[142:145], v[212:215], v[2:5]
	v_mfma_f32_16x16x32_bf16 v[62:65], v[146:149], v[180:183], v[62:65]
	v_mfma_f32_16x16x32_bf16 v[50:53], v[172:175], v[180:183], v[50:53]
	v_mfma_f32_16x16x32_bf16 v[46:49], v[146:149], v[192:195], v[46:49]
	v_mfma_f32_16x16x32_bf16 v[38:41], v[172:175], v[192:195], v[38:41]
	v_mfma_f32_16x16x32_bf16 v[30:33], v[146:149], v[200:203], v[30:33]
	v_mfma_f32_16x16x32_bf16 v[22:25], v[172:175], v[200:203], v[22:25]
	v_mfma_f32_16x16x32_bf16 v[10:13], v[146:149], v[208:211], v[10:13]
	v_mfma_f32_16x16x32_bf16 v[14:17], v[172:175], v[208:211], v[14:17]
	v_mfma_f32_16x16x32_bf16 v[62:65], v[150:153], v[188:191], v[62:65]
	v_mfma_f32_16x16x32_bf16 v[50:53], v[176:179], v[188:191], v[50:53]
	v_mfma_f32_16x16x32_bf16 v[46:49], v[150:153], v[196:199], v[46:49]
	v_mfma_f32_16x16x32_bf16 v[38:41], v[176:179], v[196:199], v[38:41]
	v_mfma_f32_16x16x32_bf16 v[30:33], v[150:153], v[204:207], v[30:33]
	v_mfma_f32_16x16x32_bf16 v[22:25], v[176:179], v[204:207], v[22:25]
	v_mfma_f32_16x16x32_bf16 v[10:13], v[150:153], v[212:215], v[10:13]
	v_mfma_f32_16x16x32_bf16 v[14:17], v[176:179], v[212:215], v[14:17]
	s_barrier
; #define PG8_STAGE(bufoff, gbase, voff) do { _Pragma("unroll") for (int _i = 0; _i < 2; ++_i) \
;         __builtin_amdgcn_global_load_lds((const unsigned*)((const char*)(gbase) + (voff)[_i]), (PG8_LAS unsigned*)(lds + (bufoff) + ldsw + _i * 8192), 16, 0, 0); } while (0)
; #define PG8_LDA(dst, b, h) do { _Pragma("unroll") for (int m = 0; m < 4; ++m) _Pragma("unroll") for (int k = 0; k < 2; ++k) dst[m][k] = *(const PG8_LAS bf16x8*)(lds + PG8_SA(b, h) + aoff + m * 2048 + k * 1024); } while (0)
; #define PG8_LDB(dst, b, h) do { _Pragma("unroll") for (int n = 0; n < 2; ++n) _Pragma("unroll") for (int k = 0; k < 2; ++k) dst[n][k] = *(const PG8_LAS bf16x8*)(lds + PG8_SB(b, h) + boff + n * 2048 + k * 1024); } while (0)
; #define PG8_MMA(ai, bj, At, Bt) do { __builtin_amdgcn_s_setprio(1); _Pragma("unroll") for (int m = 0; m < 4; ++m) _Pragma("unroll") for (int n = 0; n < 2; ++n) _Pragma("unroll") for (int k = 0; k < 2; ++k) \
;         acc[ai][bj][m][n] = __builtin_amdgcn_mfma_f32_16x16x32_bf16(Bt[n][k], At[m][k], acc[ai][bj][m][n], 0, 0, 0); __builtin_amdgcn_s_setprio(0); } while (0)
; #define PG8_WAIT_V(n) asm volatile("s_waitcnt vmcnt(" #n ")" ::: "memory")
; #define PG8_WAIT_L(n) asm volatile("s_waitcnt lgkmcnt(" #n ")" ::: "memory")
; #define PG8_BAR __builtin_amdgcn_s_barrier()
; #define PG8_SCHED __builtin_amdgcn_sched_barrier(0)
; template <class Epi, class Sched, bool ALIGN_EPI = false, bool SP2 = false>
; __device__ __forceinline__ void gemm_phase(PG8_LAS unsigned char* lds, const Gemm g, const Sched& S, const Epi& E) {
;     ...
;             PG8_LDB(B0, 1, 0); PG8_LDB(B1, 1, 1); PG8_SCHED; PG8_LDA(At, 1, 0); PG8_STAGE(PG8_SA(0, 1), a2 + hstep, voffA);
;             PG8_WAIT_V(8); PG8_WAIT_L(0); PG8_BAR; PG8_MMA(0, 0, At, B0); PG8_MMA(0, 1, At, B1); PG8_BAR; PG8_SCHED;
;             PG8_LDA(At, 1, 1); PG8_STAGE(PG8_SB(1, 0), b3, voffB); PG8_STAGE(PG8_SB(1, 1), b3 + hstep, voffB); PG8_STAGE(PG8_SA(1, 0), a3, voffA);
;             PG8_WAIT_V(8); PG8_WAIT_L(0); PG8_BAR; PG8_MMA(1, 0, At, B0); PG8_MMA(1, 1, At, B1); PG8_BAR; PG8_SCHED;
;     ...
;         if constexpr (ALIGN_EPI) { if (wr == 0) PG8_BAR; }
	s_add_i32 s33, 0, 0x18000
	s_add_i32 s42, 0, 0x1c000
	s_add_u32 s20, s20, 0x2b0000
	s_addc_u32 s21, s21, 0
	s_mov_b32 m0, s27
	s_nop 0
	global_load_lds_dwordx4 v154, s[20:21]
	s_mov_b32 m0, s28
	s_nop 0
	global_load_lds_dwordx4 v158, s[20:21]
	ds_read_b128 v[130:133], v241 offset:32768
	ds_read_b128 v[134:137], v241 offset:33792
	ds_read_b128 v[138:141], v241 offset:34816
	ds_read_b128 v[142:145], v241 offset:35840
	ds_read_b128 v[146:149], v241 offset:49152
	ds_read_b128 v[150:153], v241 offset:50176
	ds_read_b128 v[172:175], v241 offset:51200
	ds_read_b128 v[176:179], v241 offset:52224
	ds_read_b128 v[180:183], v185 offset:32768
	ds_read_b128 v[188:191], v185 offset:33792
	ds_read_b128 v[192:195], v185 offset:34816
	ds_read_b128 v[196:199], v185 offset:35840
	ds_read_b128 v[200:203], v185 offset:36864
	ds_read_b128 v[204:207], v185 offset:37888
	ds_read_b128 v[208:211], v185 offset:38912
	ds_read_b128 v[212:215], v185 offset:39936
	s_waitcnt vmcnt(8) lgkmcnt(0)
	s_barrier
	v_mfma_f32_16x16x32_bf16 v[114:117], v[130:133], v[180:183], v[114:117]
	v_mfma_f32_16x16x32_bf16 v[118:121], v[138:141], v[180:183], v[118:121]
	v_mfma_f32_16x16x32_bf16 v[106:109], v[130:133], v[192:195], v[106:109]
	v_mfma_f32_16x16x32_bf16 v[98:101], v[138:141], v[192:195], v[98:101]
	v_mfma_f32_16x16x32_bf16 v[90:93], v[130:133], v[200:203], v[90:93]
	v_mfma_f32_16x16x32_bf16 v[82:85], v[138:141], v[200:203], v[82:85]
	v_mfma_f32_16x16x32_bf16 v[74:77], v[130:133], v[208:211], v[74:77]
	v_mfma_f32_16x16x32_bf16 v[66:69], v[138:141], v[208:211], v[66:69]
	v_mfma_f32_16x16x32_bf16 v[114:117], v[134:137], v[188:191], v[114:117]
	v_mfma_f32_16x16x32_bf16 v[118:121], v[142:145], v[188:191], v[118:121]
	v_mfma_f32_16x16x32_bf16 v[106:109], v[134:137], v[196:199], v[106:109]
	v_mfma_f32_16x16x32_bf16 v[98:101], v[142:145], v[196:199], v[98:101]
	v_mfma_f32_16x16x32_bf16 v[90:93], v[134:137], v[204:207], v[90:93]
	v_mfma_f32_16x16x32_bf16 v[82:85], v[142:145], v[204:207], v[82:85]
	v_mfma_f32_16x16x32_bf16 v[74:77], v[134:137], v[212:215], v[74:77]
	v_mfma_f32_16x16x32_bf16 v[66:69], v[142:145], v[212:215], v[66:69]
	v_mfma_f32_16x16x32_bf16 v[122:125], v[146:149], v[180:183], v[122:125]
	v_mfma_f32_16x16x32_bf16 v[126:129], v[172:175], v[180:183], v[126:129]
	v_mfma_f32_16x16x32_bf16 v[110:113], v[146:149], v[192:195], v[110:113]
	v_mfma_f32_16x16x32_bf16 v[102:105], v[172:175], v[192:195], v[102:105]
	v_mfma_f32_16x16x32_bf16 v[94:97], v[146:149], v[200:203], v[94:97]
	v_mfma_f32_16x16x32_bf16 v[86:89], v[172:175], v[200:203], v[86:89]
	v_mfma_f32_16x16x32_bf16 v[78:81], v[146:149], v[208:211], v[78:81]
	v_mfma_f32_16x16x32_bf16 v[70:73], v[172:175], v[208:211], v[70:73]
	v_mfma_f32_16x16x32_bf16 v[122:125], v[150:153], v[188:191], v[122:125]
	v_mfma_f32_16x16x32_bf16 v[126:129], v[176:179], v[188:191], v[126:129]
	v_mfma_f32_16x16x32_bf16 v[110:113], v[150:153], v[196:199], v[110:113]
	v_mfma_f32_16x16x32_bf16 v[102:105], v[176:179], v[196:199], v[102:105]
	v_mfma_f32_16x16x32_bf16 v[94:97], v[150:153], v[204:207], v[94:97]
	v_mfma_f32_16x16x32_bf16 v[86:89], v[176:179], v[204:207], v[86:89]
	v_mfma_f32_16x16x32_bf16 v[78:81], v[150:153], v[212:215], v[78:81]
	v_mfma_f32_16x16x32_bf16 v[70:73], v[176:179], v[212:215], v[70:73]
	s_barrier
	s_add_i32 s20, s33, s24
	s_add_i32 m0, s20, 0xffffff80
	s_nop 0
	global_load_lds_dwordx4 v156, s[16:17] offset:128
	s_add_i32 m0, s20, 0x1f80
	s_add_i32 s20, s42, s24
	global_load_lds_dwordx4 v160, s[16:17] offset:128
	s_add_u32 s16, s16, 0x2b0080
	s_addc_u32 s17, s17, 0
	s_mov_b32 m0, s20
	s_nop 0
	global_load_lds_dwordx4 v156, s[16:17]
	s_add_i32 m0, s20, 0x2000
	s_nop 0
	global_load_lds_dwordx4 v160, s[16:17]
	s_mov_b32 m0, s34
	s_nop 0
	global_load_lds_dwordx4 v154, s[100:101]
	s_mov_b32 m0, s35
	s_nop 0
	global_load_lds_dwordx4 v158, s[100:101]
	ds_read_b128 v[180:183], v185 offset:49152
	ds_read_b128 v[188:191], v185 offset:50176
	ds_read_b128 v[192:195], v185 offset:51200
	ds_read_b128 v[196:199], v185 offset:52224
	ds_read_b128 v[200:203], v185 offset:53248
	ds_read_b128 v[204:207], v185 offset:54272
	ds_read_b128 v[208:211], v185 offset:55296
	ds_read_b128 v[212:215], v185 offset:56320
	s_waitcnt vmcnt(8) lgkmcnt(0)
	s_barrier
	v_mfma_f32_16x16x32_bf16 v[58:61], v[130:133], v[180:183], v[58:61]
	v_mfma_f32_16x16x32_bf16 v[54:57], v[138:141], v[180:183], v[54:57]
	v_mfma_f32_16x16x32_bf16 v[42:45], v[130:133], v[192:195], v[42:45]
	v_mfma_f32_16x16x32_bf16 v[34:37], v[138:141], v[192:195], v[34:37]
	v_mfma_f32_16x16x32_bf16 v[26:29], v[130:133], v[200:203], v[26:29]
	v_mfma_f32_16x16x32_bf16 v[18:21], v[138:141], v[200:203], v[18:21]
	v_mfma_f32_16x16x32_bf16 v[6:9], v[130:133], v[208:211], v[6:9]
	v_mfma_f32_16x16x32_bf16 v[2:5], v[138:141], v[208:211], v[2:5]
	v_mfma_f32_16x16x32_bf16 v[58:61], v[134:137], v[188:191], v[58:61]
	v_mfma_f32_16x16x32_bf16 v[54:57], v[142:145], v[188:191], v[54:57]
	v_mfma_f32_16x16x32_bf16 v[42:45], v[134:137], v[196:199], v[42:45]
	v_mfma_f32_16x16x32_bf16 v[34:37], v[142:145], v[196:199], v[34:37]
	v_mfma_f32_16x16x32_bf16 v[26:29], v[134:137], v[204:207], v[26:29]
	v_mfma_f32_16x16x32_bf16 v[18:21], v[142:145], v[204:207], v[18:21]
	v_mfma_f32_16x16x32_bf16 v[6:9], v[134:137], v[212:215], v[6:9]
	v_mfma_f32_16x16x32_bf16 v[2:5], v[142:145], v[212:215], v[2:5]
	v_mfma_f32_16x16x32_bf16 v[62:65], v[146:149], v[180:183], v[62:65]
	v_mfma_f32_16x16x32_bf16 v[50:53], v[172:175], v[180:183], v[50:53]
	v_mfma_f32_16x16x32_bf16 v[46:49], v[146:149], v[192:195], v[46:49]
	v_mfma_f32_16x16x32_bf16 v[38:41], v[172:175], v[192:195], v[38:41]
	v_mfma_f32_16x16x32_bf16 v[30:33], v[146:149], v[200:203], v[30:33]
	v_mfma_f32_16x16x32_bf16 v[22:25], v[172:175], v[200:203], v[22:25]
	v_mfma_f32_16x16x32_bf16 v[10:13], v[146:149], v[208:211], v[10:13]
	v_mfma_f32_16x16x32_bf16 v[14:17], v[172:175], v[208:211], v[14:17]
	v_mfma_f32_16x16x32_bf16 v[62:65], v[150:153], v[188:191], v[62:65]
	v_mfma_f32_16x16x32_bf16 v[50:53], v[176:179], v[188:191], v[50:53]
	v_mfma_f32_16x16x32_bf16 v[46:49], v[150:153], v[196:199], v[46:49]
	v_mfma_f32_16x16x32_bf16 v[38:41], v[176:179], v[196:199], v[38:41]
	v_mfma_f32_16x16x32_bf16 v[30:33], v[150:153], v[204:207], v[30:33]
	v_mfma_f32_16x16x32_bf16 v[22:25], v[176:179], v[204:207], v[22:25]
	v_mfma_f32_16x16x32_bf16 v[10:13], v[150:153], v[212:215], v[10:13]
	v_mfma_f32_16x16x32_bf16 v[14:17], v[176:179], v[212:215], v[14:17]
	s_barrier
	s_add_i32 s64, s64, 2
	s_add_u32 s18, s18, 0x100
	s_addc_u32 s19, s19, 0
	s_add_u32 s62, s62, 0x100
	s_addc_u32 s63, s63, 0
	s_cmpk_gt_u32 s64, 0xa9
	s_cbranch_scc0 .LBB0_1245
	s_and_b64 vcc, exec, s[12:13]
	s_cbranch_vccz .LBB0_1248
	s_barrier

; #define PG8_STAGE(bufoff, gbase, voff) do { _Pragma("unroll") for (int _i = 0; _i < 2; ++_i) \
;         __builtin_amdgcn_global_load_lds((const unsigned*)((const char*)(gbase) + (voff)[_i]), (PG8_LAS unsigned*)(lds + (bufoff) + ldsw + _i * 8192), 16, 0, 0); } while (0)
; #define PG8_LDA(dst, b, h) do { _Pragma("unroll") for (int m = 0; m < 4; ++m) _Pragma("unroll") for (int k = 0; k < 2; ++k) dst[m][k] = *(const PG8_LAS bf16x8*)(lds + PG8_SA(b, h) + aoff + m * 2048 + k * 1024); } while (0)
; #define PG8_LDB(dst, b, h) do { _Pragma("unroll") for (int n = 0; n < 2; ++n) _Pragma("unroll") for (int k = 0; k < 2; ++k) dst[n][k] = *(const PG8_LAS bf16x8*)(lds + PG8_SB(b, h) + boff + n * 2048 + k * 1024); } while (0)
; #define PG8_MMA(ai, bj, At, Bt) do { __builtin_amdgcn_s_setprio(1); _Pragma("unroll") for (int m = 0; m < 4; ++m) _Pragma("unroll") for (int n = 0; n < 2; ++n) _Pragma("unroll") for (int k = 0; k < 2; ++k) \
;         acc[ai][bj][m][n] = __builtin_amdgcn_mfma_f32_16x16x32_bf16(Bt[n][k], At[m][k], acc[ai][bj][m][n], 0, 0, 0); __builtin_amdgcn_s_setprio(0); } while (0)
; #define PG8_WAIT_V(n) asm volatile("s_waitcnt vmcnt(" #n ")" ::: "memory")
; #define PG8_WAIT_L(n) asm volatile("s_waitcnt lgkmcnt(" #n ")" ::: "memory")
; #define PG8_BAR __builtin_amdgcn_s_barrier()
; #define PG8_SCHED __builtin_amdgcn_sched_barrier(0)
; template <class Epi, class Sched, bool ALIGN_EPI = false, bool SP2 = false>
; __device__ __forceinline__ void gemm_phase(PG8_LAS unsigned char* lds, const Gemm g, const Sched& S, const Epi& E) {
;     ...
;             PG8_LDB(B0, 0, 0); PG8_LDB(B1, 0, 1); PG8_SCHED; PG8_LDA(At, 0, 0); PG8_STAGE(PG8_SA(1, 1), a1 + hstep, voffA);
;             PG8_WAIT_V(8); PG8_WAIT_L(0); PG8_BAR; PG8_MMA(0, 0, At, B0); PG8_MMA(0, 1, At, B1); PG8_BAR; PG8_SCHED;
;             PG8_LDA(At, 0, 1); PG8_STAGE(PG8_SB(0, 0), b2, voffB); PG8_STAGE(PG8_SB(0, 1), b2 + hstep, voffB); PG8_STAGE(PG8_SA(0, 0), a2, voffA);
;             PG8_WAIT_V(8); PG8_WAIT_L(0); PG8_BAR; PG8_MMA(1, 0, At, B0); PG8_MMA(1, 1, At, B1); PG8_BAR; PG8_SCHED;
.LBB0_1332:
	s_add_u32 s20, s22, 0xfff00080
	s_addc_u32 s21, s23, -1
	s_cmp_eq_u32 s67, 60
	s_cselect_b32 s25, s13, s21
	s_cselect_b32 s24, s63, s20
	s_cselect_b32 s21, s11, s66
	s_cselect_b32 s20, s64, s65
	s_add_i32 m0, s19, 0xc000
	s_nop 0
	global_load_lds_dwordx4 v138, s[22:23]
	s_add_i32 m0, s19, 0xe000
	s_nop 0
	global_load_lds_dwordx4 v140, s[22:23]
	ds_read_b128 v[148:151], v241 offset:0
	ds_read_b128 v[156:159], v241 offset:1024
	ds_read_b128 v[166:169], v241 offset:2048
	ds_read_b128 v[170:173], v241 offset:3072
	ds_read_b128 v[174:177], v241 offset:16384
	ds_read_b128 v[178:181], v241 offset:17408
	ds_read_b128 v[182:185], v241 offset:18432
	ds_read_b128 v[186:189], v241 offset:19456
	ds_read_b128 v[190:193], v155
	ds_read_b128 v[194:197], v155 offset:1024
	ds_read_b128 v[198:201], v155 offset:2048
	ds_read_b128 v[202:205], v155 offset:3072
	ds_read_b128 v[206:209], v155 offset:4096
	ds_read_b128 v[210:213], v155 offset:5120
	ds_read_b128 v[214:217], v155 offset:6144
	ds_read_b128 v[218:221], v155 offset:7168
	s_waitcnt vmcnt(8) lgkmcnt(0)
	s_barrier
	v_mfma_f32_16x16x32_bf16 v[118:121], v[148:151], v[190:193], v[118:121]
	v_mfma_f32_16x16x32_bf16 v[114:117], v[166:169], v[190:193], v[114:117]
	v_mfma_f32_16x16x32_bf16 v[102:105], v[148:151], v[198:201], v[102:105]
	v_mfma_f32_16x16x32_bf16 v[98:101], v[166:169], v[198:201], v[98:101]
	v_mfma_f32_16x16x32_bf16 v[86:89], v[148:151], v[206:209], v[86:89]
	v_mfma_f32_16x16x32_bf16 v[82:85], v[166:169], v[206:209], v[82:85]
	v_mfma_f32_16x16x32_bf16 v[70:73], v[148:151], v[214:217], v[70:73]
	v_mfma_f32_16x16x32_bf16 v[66:69], v[166:169], v[214:217], v[66:69]
	v_mfma_f32_16x16x32_bf16 v[118:121], v[156:159], v[194:197], v[118:121]
	v_mfma_f32_16x16x32_bf16 v[114:117], v[170:173], v[194:197], v[114:117]
	v_mfma_f32_16x16x32_bf16 v[102:105], v[156:159], v[202:205], v[102:105]
	v_mfma_f32_16x16x32_bf16 v[98:101], v[170:173], v[202:205], v[98:101]
	v_mfma_f32_16x16x32_bf16 v[86:89], v[156:159], v[210:213], v[86:89]
	v_mfma_f32_16x16x32_bf16 v[82:85], v[170:173], v[210:213], v[82:85]
	v_mfma_f32_16x16x32_bf16 v[70:73], v[156:159], v[218:221], v[70:73]
	v_mfma_f32_16x16x32_bf16 v[66:69], v[170:173], v[218:221], v[66:69]
	v_mfma_f32_16x16x32_bf16 v[126:129], v[174:177], v[190:193], v[126:129]
	v_mfma_f32_16x16x32_bf16 v[122:125], v[182:185], v[190:193], v[122:125]
	v_mfma_f32_16x16x32_bf16 v[110:113], v[174:177], v[198:201], v[110:113]
	v_mfma_f32_16x16x32_bf16 v[106:109], v[182:185], v[198:201], v[106:109]
	v_mfma_f32_16x16x32_bf16 v[94:97], v[174:177], v[206:209], v[94:97]
	v_mfma_f32_16x16x32_bf16 v[90:93], v[182:185], v[206:209], v[90:93]
	v_mfma_f32_16x16x32_bf16 v[78:81], v[174:177], v[214:217], v[78:81]
	v_mfma_f32_16x16x32_bf16 v[74:77], v[182:185], v[214:217], v[74:77]
	v_mfma_f32_16x16x32_bf16 v[126:129], v[178:181], v[194:197], v[126:129]
	v_mfma_f32_16x16x32_bf16 v[122:125], v[186:189], v[194:197], v[122:125]
	v_mfma_f32_16x16x32_bf16 v[110:113], v[178:181], v[202:205], v[110:113]
	v_mfma_f32_16x16x32_bf16 v[106:109], v[186:189], v[202:205], v[106:109]
	v_mfma_f32_16x16x32_bf16 v[94:97], v[178:181], v[210:213], v[94:97]
	v_mfma_f32_16x16x32_bf16 v[90:93], v[186:189], v[210:213], v[90:93]
	v_mfma_f32_16x16x32_bf16 v[78:81], v[178:181], v[218:221], v[78:81]
	v_mfma_f32_16x16x32_bf16 v[74:77], v[186:189], v[218:221], v[74:77]
	s_barrier
	s_add_i32 s33, s47, s28
	s_mov_b32 m0, s33
	s_nop 0
	global_load_lds_dwordx4 v132, s[20:21]
	s_add_i32 m0, s33, 0x2000
	s_add_u32 s68, s20, 0x100000
	s_addc_u32 s69, s21, 0
	s_add_i32 s33, s52, s28
	global_load_lds_dwordx4 v136, s[20:21]
	s_mov_b32 m0, s33
	s_add_u32 s100, s24, 0x80
	s_addc_u32 s101, s25, 0
	global_load_lds_dwordx4 v132, s[68:69]
	s_add_i32 m0, s33, 0x2000
	s_nop 0
	global_load_lds_dwordx4 v136, s[68:69]
	s_mov_b32 m0, s19
	s_nop 0
	global_load_lds_dwordx4 v130, s[24:25]
	s_mov_b32 m0, s35
	s_nop 0
	global_load_lds_dwordx4 v134, s[24:25]
	ds_read_b128 v[190:193], v155 offset:16384
	ds_read_b128 v[194:197], v155 offset:17408
	ds_read_b128 v[198:201], v155 offset:18432
	ds_read_b128 v[202:205], v155 offset:19456
	ds_read_b128 v[206:209], v155 offset:20480
	ds_read_b128 v[210:213], v155 offset:21504
	ds_read_b128 v[214:217], v155 offset:22528
	ds_read_b128 v[218:221], v155 offset:23552
	s_waitcnt vmcnt(8) lgkmcnt(0)
	s_barrier
	v_mfma_f32_16x16x32_bf16 v[54:57], v[148:151], v[190:193], v[54:57]
	v_mfma_f32_16x16x32_bf16 v[50:53], v[166:169], v[190:193], v[50:53]
	v_mfma_f32_16x16x32_bf16 v[38:41], v[148:151], v[198:201], v[38:41]
	v_mfma_f32_16x16x32_bf16 v[34:37], v[166:169], v[198:201], v[34:37]
	v_mfma_f32_16x16x32_bf16 v[22:25], v[148:151], v[206:209], v[22:25]
	v_mfma_f32_16x16x32_bf16 v[18:21], v[166:169], v[206:209], v[18:21]
	v_mfma_f32_16x16x32_bf16 v[6:9], v[148:151], v[214:217], v[6:9]
	v_mfma_f32_16x16x32_bf16 v[2:5], v[166:169], v[214:217], v[2:5]
	v_mfma_f32_16x16x32_bf16 v[54:57], v[156:159], v[194:197], v[54:57]
	v_mfma_f32_16x16x32_bf16 v[50:53], v[170:173], v[194:197], v[50:53]
	v_mfma_f32_16x16x32_bf16 v[38:41], v[156:159], v[202:205], v[38:41]
	v_mfma_f32_16x16x32_bf16 v[34:37], v[170:173], v[202:205], v[34:37]
	v_mfma_f32_16x16x32_bf16 v[22:25], v[156:159], v[210:213], v[22:25]
	v_mfma_f32_16x16x32_bf16 v[18:21], v[170:173], v[210:213], v[18:21]
	v_mfma_f32_16x16x32_bf16 v[6:9], v[156:159], v[218:221], v[6:9]
	v_mfma_f32_16x16x32_bf16 v[2:5], v[170:173], v[218:221], v[2:5]
	v_mfma_f32_16x16x32_bf16 v[62:65], v[174:177], v[190:193], v[62:65]
	v_mfma_f32_16x16x32_bf16 v[58:61], v[182:185], v[190:193], v[58:61]
	v_mfma_f32_16x16x32_bf16 v[46:49], v[174:177], v[198:201], v[46:49]
	v_mfma_f32_16x16x32_bf16 v[42:45], v[182:185], v[198:201], v[42:45]
	v_mfma_f32_16x16x32_bf16 v[30:33], v[174:177], v[206:209], v[30:33]
	v_mfma_f32_16x16x32_bf16 v[26:29], v[182:185], v[206:209], v[26:29]
	v_mfma_f32_16x16x32_bf16 v[10:13], v[174:177], v[214:217], v[10:13]
	v_mfma_f32_16x16x32_bf16 v[14:17], v[182:185], v[214:217], v[14:17]
	v_mfma_f32_16x16x32_bf16 v[62:65], v[178:181], v[194:197], v[62:65]
	v_mfma_f32_16x16x32_bf16 v[58:61], v[186:189], v[194:197], v[58:61]
	v_mfma_f32_16x16x32_bf16 v[46:49], v[178:181], v[202:205], v[46:49]
	v_mfma_f32_16x16x32_bf16 v[42:45], v[186:189], v[202:205], v[42:45]
	v_mfma_f32_16x16x32_bf16 v[30:33], v[178:181], v[210:213], v[30:33]
	v_mfma_f32_16x16x32_bf16 v[26:29], v[186:189], v[210:213], v[26:29]
	v_mfma_f32_16x16x32_bf16 v[10:13], v[178:181], v[218:221], v[10:13]
	v_mfma_f32_16x16x32_bf16 v[14:17], v[186:189], v[218:221], v[14:17]
	s_barrier
; #define PG8_STAGE(bufoff, gbase, voff) do { _Pragma("unroll") for (int _i = 0; _i < 2; ++_i) \
;         __builtin_amdgcn_global_load_lds((const unsigned*)((const char*)(gbase) + (voff)[_i]), (PG8_LAS unsigned*)(lds + (bufoff) + ldsw + _i * 8192), 16, 0, 0); } while (0)
; #define PG8_LDA(dst, b, h) do { _Pragma("unroll") for (int m = 0; m < 4; ++m) _Pragma("unroll") for (int k = 0; k < 2; ++k) dst[m][k] = *(const PG8_LAS bf16x8*)(lds + PG8_SA(b, h) + aoff + m * 2048 + k * 1024); } while (0)
; #define PG8_LDB(dst, b, h) do { _Pragma("unroll") for (int n = 0; n < 2; ++n) _Pragma("unroll") for (int k = 0; k < 2; ++k) dst[n][k] = *(const PG8_LAS bf16x8*)(lds + PG8_SB(b, h) + boff + n * 2048 + k * 1024); } while (0)
; #define PG8_MMA(ai, bj, At, Bt) do { __builtin_amdgcn_s_setprio(1); _Pragma("unroll") for (int m = 0; m < 4; ++m) _Pragma("unroll") for (int n = 0; n < 2; ++n) _Pragma("unroll") for (int k = 0; k < 2; ++k) \
;         acc[ai][bj][m][n] = __builtin_amdgcn_mfma_f32_16x16x32_bf16(Bt[n][k], At[m][k], acc[ai][bj][m][n], 0, 0, 0); __builtin_amdgcn_s_setprio(0); } while (0)
; #define PG8_WAIT_V(n) asm volatile("s_waitcnt vmcnt(" #n ")" ::: "memory")
; #define PG8_WAIT_L(n) asm volatile("s_waitcnt lgkmcnt(" #n ")" ::: "memory")
; #define PG8_BAR __builtin_amdgcn_s_barrier()
; #define PG8_SCHED __builtin_amdgcn_sched_barrier(0)
; template <class Epi, class Sched, bool ALIGN_EPI = false, bool SP2 = false>
; __device__ __forceinline__ void gemm_phase(PG8_LAS unsigned char* lds, const Gemm g, const Sched& S, const Epi& E) {
;     ...
;             PG8_LDB(B0, 1, 0); PG8_LDB(B1, 1, 1); PG8_SCHED; PG8_LDA(At, 1, 0); PG8_STAGE(PG8_SA(0, 1), a2 + hstep, voffA);
;             PG8_WAIT_V(8); PG8_WAIT_L(0); PG8_BAR; PG8_MMA(0, 0, At, B0); PG8_MMA(0, 1, At, B1); PG8_BAR; PG8_SCHED;
;             PG8_LDA(At, 1, 1); PG8_STAGE(PG8_SB(1, 0), b3, voffB); PG8_STAGE(PG8_SB(1, 1), b3 + hstep, voffB); PG8_STAGE(PG8_SA(1, 0), a3, voffA);
;             PG8_WAIT_V(8); PG8_WAIT_L(0); PG8_BAR; PG8_MMA(1, 0, At, B0); PG8_MMA(1, 1, At, B1); PG8_BAR; PG8_SCHED;
;     ...
;         if constexpr (ALIGN_EPI) { if (wr == 0) PG8_BAR; }
	s_add_i32 s33, 0, 0x18000
	s_add_i32 s42, 0, 0x1c000
	s_add_u32 s24, s24, 0x100000
	s_addc_u32 s25, s25, 0
	s_mov_b32 m0, s36
	s_nop 0
	global_load_lds_dwordx4 v130, s[24:25]
	s_mov_b32 m0, s37
	s_nop 0
	global_load_lds_dwordx4 v134, s[24:25]
	ds_read_b128 v[148:151], v241 offset:32768
	ds_read_b128 v[156:159], v241 offset:33792
	ds_read_b128 v[166:169], v241 offset:34816
	ds_read_b128 v[170:173], v241 offset:35840
	ds_read_b128 v[174:177], v241 offset:49152
	ds_read_b128 v[178:181], v241 offset:50176
	ds_read_b128 v[182:185], v241 offset:51200
	ds_read_b128 v[186:189], v241 offset:52224
	ds_read_b128 v[190:193], v155 offset:32768
	ds_read_b128 v[194:197], v155 offset:33792
	ds_read_b128 v[198:201], v155 offset:34816
	ds_read_b128 v[202:205], v155 offset:35840
	ds_read_b128 v[206:209], v155 offset:36864
	ds_read_b128 v[210:213], v155 offset:37888
	ds_read_b128 v[214:217], v155 offset:38912
	ds_read_b128 v[218:221], v155 offset:39936
	s_waitcnt vmcnt(8) lgkmcnt(0)
	s_barrier
	v_mfma_f32_16x16x32_bf16 v[118:121], v[148:151], v[190:193], v[118:121]
	v_mfma_f32_16x16x32_bf16 v[114:117], v[166:169], v[190:193], v[114:117]
	v_mfma_f32_16x16x32_bf16 v[102:105], v[148:151], v[198:201], v[102:105]
	v_mfma_f32_16x16x32_bf16 v[98:101], v[166:169], v[198:201], v[98:101]
	v_mfma_f32_16x16x32_bf16 v[86:89], v[148:151], v[206:209], v[86:89]
	v_mfma_f32_16x16x32_bf16 v[82:85], v[166:169], v[206:209], v[82:85]
	v_mfma_f32_16x16x32_bf16 v[70:73], v[148:151], v[214:217], v[70:73]
	v_mfma_f32_16x16x32_bf16 v[66:69], v[166:169], v[214:217], v[66:69]
	v_mfma_f32_16x16x32_bf16 v[118:121], v[156:159], v[194:197], v[118:121]
	v_mfma_f32_16x16x32_bf16 v[114:117], v[170:173], v[194:197], v[114:117]
	v_mfma_f32_16x16x32_bf16 v[102:105], v[156:159], v[202:205], v[102:105]
	v_mfma_f32_16x16x32_bf16 v[98:101], v[170:173], v[202:205], v[98:101]
	v_mfma_f32_16x16x32_bf16 v[86:89], v[156:159], v[210:213], v[86:89]
	v_mfma_f32_16x16x32_bf16 v[82:85], v[170:173], v[210:213], v[82:85]
	v_mfma_f32_16x16x32_bf16 v[70:73], v[156:159], v[218:221], v[70:73]
	v_mfma_f32_16x16x32_bf16 v[66:69], v[170:173], v[218:221], v[66:69]
	v_mfma_f32_16x16x32_bf16 v[126:129], v[174:177], v[190:193], v[126:129]
	v_mfma_f32_16x16x32_bf16 v[122:125], v[182:185], v[190:193], v[122:125]
	v_mfma_f32_16x16x32_bf16 v[110:113], v[174:177], v[198:201], v[110:113]
	v_mfma_f32_16x16x32_bf16 v[106:109], v[182:185], v[198:201], v[106:109]
	v_mfma_f32_16x16x32_bf16 v[94:97], v[174:177], v[206:209], v[94:97]
	v_mfma_f32_16x16x32_bf16 v[90:93], v[182:185], v[206:209], v[90:93]
	v_mfma_f32_16x16x32_bf16 v[78:81], v[174:177], v[214:217], v[78:81]
	v_mfma_f32_16x16x32_bf16 v[74:77], v[182:185], v[214:217], v[74:77]
	v_mfma_f32_16x16x32_bf16 v[126:129], v[178:181], v[194:197], v[126:129]
	v_mfma_f32_16x16x32_bf16 v[122:125], v[186:189], v[194:197], v[122:125]
	v_mfma_f32_16x16x32_bf16 v[110:113], v[178:181], v[202:205], v[110:113]
	v_mfma_f32_16x16x32_bf16 v[106:109], v[186:189], v[202:205], v[106:109]
	v_mfma_f32_16x16x32_bf16 v[94:97], v[178:181], v[210:213], v[94:97]
	v_mfma_f32_16x16x32_bf16 v[90:93], v[186:189], v[210:213], v[90:93]
	v_mfma_f32_16x16x32_bf16 v[78:81], v[178:181], v[218:221], v[78:81]
	v_mfma_f32_16x16x32_bf16 v[74:77], v[186:189], v[218:221], v[74:77]
	s_barrier
	s_add_i32 s24, s33, s28
	s_add_i32 m0, s24, 0xffffff80
	s_nop 0
	global_load_lds_dwordx4 v132, s[20:21] offset:128
	s_add_i32 m0, s24, 0x1f80
	s_add_i32 s24, s42, s28
	global_load_lds_dwordx4 v136, s[20:21] offset:128
	s_add_u32 s20, s20, 0x100080
	s_addc_u32 s21, s21, 0
	s_mov_b32 m0, s24
	s_nop 0
	global_load_lds_dwordx4 v132, s[20:21]
	s_add_i32 m0, s24, 0x2000
	s_nop 0
	global_load_lds_dwordx4 v136, s[20:21]
	s_mov_b32 m0, s43
	s_nop 0
	global_load_lds_dwordx4 v130, s[100:101]
	s_mov_b32 m0, s46
	s_nop 0
	global_load_lds_dwordx4 v134, s[100:101]
	ds_read_b128 v[190:193], v155 offset:49152
	ds_read_b128 v[194:197], v155 offset:50176
	ds_read_b128 v[198:201], v155 offset:51200
	ds_read_b128 v[202:205], v155 offset:52224
	ds_read_b128 v[206:209], v155 offset:53248
	ds_read_b128 v[210:213], v155 offset:54272
	ds_read_b128 v[214:217], v155 offset:55296
	ds_read_b128 v[218:221], v155 offset:56320
	s_waitcnt vmcnt(8) lgkmcnt(0)
	s_barrier
	v_mfma_f32_16x16x32_bf16 v[54:57], v[148:151], v[190:193], v[54:57]
	v_mfma_f32_16x16x32_bf16 v[50:53], v[166:169], v[190:193], v[50:53]
	v_mfma_f32_16x16x32_bf16 v[38:41], v[148:151], v[198:201], v[38:41]
	v_mfma_f32_16x16x32_bf16 v[34:37], v[166:169], v[198:201], v[34:37]
	v_mfma_f32_16x16x32_bf16 v[22:25], v[148:151], v[206:209], v[22:25]
	v_mfma_f32_16x16x32_bf16 v[18:21], v[166:169], v[206:209], v[18:21]
	v_mfma_f32_16x16x32_bf16 v[6:9], v[148:151], v[214:217], v[6:9]
	v_mfma_f32_16x16x32_bf16 v[2:5], v[166:169], v[214:217], v[2:5]
	v_mfma_f32_16x16x32_bf16 v[54:57], v[156:159], v[194:197], v[54:57]
	v_mfma_f32_16x16x32_bf16 v[50:53], v[170:173], v[194:197], v[50:53]
	v_mfma_f32_16x16x32_bf16 v[38:41], v[156:159], v[202:205], v[38:41]
	v_mfma_f32_16x16x32_bf16 v[34:37], v[170:173], v[202:205], v[34:37]
	v_mfma_f32_16x16x32_bf16 v[22:25], v[156:159], v[210:213], v[22:25]
	v_mfma_f32_16x16x32_bf16 v[18:21], v[170:173], v[210:213], v[18:21]
	v_mfma_f32_16x16x32_bf16 v[6:9], v[156:159], v[218:221], v[6:9]
	v_mfma_f32_16x16x32_bf16 v[2:5], v[170:173], v[218:221], v[2:5]
	v_mfma_f32_16x16x32_bf16 v[62:65], v[174:177], v[190:193], v[62:65]
	v_mfma_f32_16x16x32_bf16 v[58:61], v[182:185], v[190:193], v[58:61]
	v_mfma_f32_16x16x32_bf16 v[46:49], v[174:177], v[198:201], v[46:49]
	v_mfma_f32_16x16x32_bf16 v[42:45], v[182:185], v[198:201], v[42:45]
	v_mfma_f32_16x16x32_bf16 v[30:33], v[174:177], v[206:209], v[30:33]
	v_mfma_f32_16x16x32_bf16 v[26:29], v[182:185], v[206:209], v[26:29]
	v_mfma_f32_16x16x32_bf16 v[10:13], v[174:177], v[214:217], v[10:13]
	v_mfma_f32_16x16x32_bf16 v[14:17], v[182:185], v[214:217], v[14:17]
	v_mfma_f32_16x16x32_bf16 v[62:65], v[178:181], v[194:197], v[62:65]
	v_mfma_f32_16x16x32_bf16 v[58:61], v[186:189], v[194:197], v[58:61]
	v_mfma_f32_16x16x32_bf16 v[46:49], v[178:181], v[202:205], v[46:49]
	v_mfma_f32_16x16x32_bf16 v[42:45], v[186:189], v[202:205], v[42:45]
	v_mfma_f32_16x16x32_bf16 v[30:33], v[178:181], v[210:213], v[30:33]
	v_mfma_f32_16x16x32_bf16 v[26:29], v[186:189], v[210:213], v[26:29]
	v_mfma_f32_16x16x32_bf16 v[10:13], v[178:181], v[218:221], v[10:13]
	v_mfma_f32_16x16x32_bf16 v[14:17], v[186:189], v[218:221], v[14:17]
	s_barrier
	s_add_i32 s67, s67, 2
	s_add_u32 s22, s22, 0x100
	s_addc_u32 s23, s23, 0
	s_add_u32 s65, s65, 0x100
	s_addc_u32 s66, s66, 0
	s_cmp_gt_u32 s67, 61
	s_cbranch_scc0 .LBB0_1332
	s_and_b64 vcc, exec, s[8:9]
	s_cbranch_vccz .LBB0_1335
	s_barrier

; #define PG8_STAGE(bufoff, gbase, voff) do { _Pragma("unroll") for (int _i = 0; _i < 2; ++_i) \
;         __builtin_amdgcn_global_load_lds((const unsigned*)((const char*)(gbase) + (voff)[_i]), (PG8_LAS unsigned*)(lds + (bufoff) + ldsw + _i * 8192), 16, 0, 0); } while (0)
; #define PG8_LDA(dst, b, h) do { _Pragma("unroll") for (int m = 0; m < 4; ++m) _Pragma("unroll") for (int k = 0; k < 2; ++k) dst[m][k] = *(const PG8_LAS bf16x8*)(lds + PG8_SA(b, h) + aoff + m * 2048 + k * 1024); } while (0)
; #define PG8_LDB(dst, b, h) do { _Pragma("unroll") for (int n = 0; n < 2; ++n) _Pragma("unroll") for (int k = 0; k < 2; ++k) dst[n][k] = *(const PG8_LAS bf16x8*)(lds + PG8_SB(b, h) + boff + n * 2048 + k * 1024); } while (0)
; #define PG8_MMA(ai, bj, At, Bt) do { __builtin_amdgcn_s_setprio(1); _Pragma("unroll") for (int m = 0; m < 4; ++m) _Pragma("unroll") for (int n = 0; n < 2; ++n) _Pragma("unroll") for (int k = 0; k < 2; ++k) \
;         acc[ai][bj][m][n] = __builtin_amdgcn_mfma_f32_16x16x32_bf16(Bt[n][k], At[m][k], acc[ai][bj][m][n], 0, 0, 0); __builtin_amdgcn_s_setprio(0); } while (0)
; #define PG8_WAIT_V(n) asm volatile("s_waitcnt vmcnt(" #n ")" ::: "memory")
; #define PG8_WAIT_L(n) asm volatile("s_waitcnt lgkmcnt(" #n ")" ::: "memory")
; #define PG8_BAR __builtin_amdgcn_s_barrier()
; #define PG8_SCHED __builtin_amdgcn_sched_barrier(0)
; template <class Epi, class Sched, bool ALIGN_EPI = false, bool SP2 = false>
; __device__ __forceinline__ void gemm_phase(PG8_LAS unsigned char* lds, const Gemm g, const Sched& S, const Epi& E) {
;     ...
;             PG8_LDB(B0, 0, 0); PG8_LDB(B1, 0, 1); PG8_SCHED; PG8_LDA(At, 0, 0); PG8_STAGE(PG8_SA(1, 1), a1 + hstep, voffA);
;             PG8_WAIT_V(8); PG8_WAIT_L(0); PG8_BAR; PG8_MMA(0, 0, At, B0); PG8_MMA(0, 1, At, B1); PG8_BAR; PG8_SCHED;
;             PG8_LDA(At, 0, 1); PG8_STAGE(PG8_SB(0, 0), b2, voffB); PG8_STAGE(PG8_SB(0, 1), b2 + hstep, voffB); PG8_STAGE(PG8_SA(0, 0), a2, voffA);
;             PG8_WAIT_V(8); PG8_WAIT_L(0); PG8_BAR; PG8_MMA(1, 0, At, B0); PG8_MMA(1, 1, At, B1); PG8_BAR; PG8_SCHED;
.LBB0_1595:
	s_add_u32 s24, s26, 0xfff00080
	s_addc_u32 s25, s27, -1
	s_cmp_eq_u32 s62, 60
	s_cselect_b32 s29, s15, s25
	s_cselect_b32 s28, s21, s24
	s_cselect_b32 s25, s13, s53
	s_cselect_b32 s24, s51, s52
	s_add_i32 m0, s23, 0xc000
	s_nop 0
	global_load_lds_dwordx4 v162, s[26:27]
	s_add_i32 m0, s23, 0xe000
	s_nop 0
	global_load_lds_dwordx4 v166, s[26:27]
	ds_read_b128 v[130:133], v241 offset:0
	ds_read_b128 v[134:137], v241 offset:1024
	ds_read_b128 v[138:141], v241 offset:2048
	ds_read_b128 v[142:145], v241 offset:3072
	ds_read_b128 v[146:149], v241 offset:16384
	ds_read_b128 v[150:153], v241 offset:17408
	ds_read_b128 v[172:175], v241 offset:18432
	ds_read_b128 v[176:179], v241 offset:19456
	ds_read_b128 v[180:183], v185
	ds_read_b128 v[188:191], v185 offset:1024
	ds_read_b128 v[192:195], v185 offset:2048
	ds_read_b128 v[196:199], v185 offset:3072
	ds_read_b128 v[200:203], v185 offset:4096
	ds_read_b128 v[204:207], v185 offset:5120
	ds_read_b128 v[208:211], v185 offset:6144
	ds_read_b128 v[212:215], v185 offset:7168
	s_waitcnt vmcnt(8) lgkmcnt(0)
	s_barrier
	v_mfma_f32_16x16x32_bf16 v[114:117], v[130:133], v[180:183], v[114:117]
	v_mfma_f32_16x16x32_bf16 v[118:121], v[138:141], v[180:183], v[118:121]
	v_mfma_f32_16x16x32_bf16 v[106:109], v[130:133], v[192:195], v[106:109]
	v_mfma_f32_16x16x32_bf16 v[98:101], v[138:141], v[192:195], v[98:101]
	v_mfma_f32_16x16x32_bf16 v[90:93], v[130:133], v[200:203], v[90:93]
	v_mfma_f32_16x16x32_bf16 v[82:85], v[138:141], v[200:203], v[82:85]
	v_mfma_f32_16x16x32_bf16 v[74:77], v[130:133], v[208:211], v[74:77]
	v_mfma_f32_16x16x32_bf16 v[66:69], v[138:141], v[208:211], v[66:69]
	v_mfma_f32_16x16x32_bf16 v[114:117], v[134:137], v[188:191], v[114:117]
	v_mfma_f32_16x16x32_bf16 v[118:121], v[142:145], v[188:191], v[118:121]
	v_mfma_f32_16x16x32_bf16 v[106:109], v[134:137], v[196:199], v[106:109]
	v_mfma_f32_16x16x32_bf16 v[98:101], v[142:145], v[196:199], v[98:101]
	v_mfma_f32_16x16x32_bf16 v[90:93], v[134:137], v[204:207], v[90:93]
	v_mfma_f32_16x16x32_bf16 v[82:85], v[142:145], v[204:207], v[82:85]
	v_mfma_f32_16x16x32_bf16 v[74:77], v[134:137], v[212:215], v[74:77]
	v_mfma_f32_16x16x32_bf16 v[66:69], v[142:145], v[212:215], v[66:69]
	v_mfma_f32_16x16x32_bf16 v[122:125], v[146:149], v[180:183], v[122:125]
	v_mfma_f32_16x16x32_bf16 v[126:129], v[172:175], v[180:183], v[126:129]
	v_mfma_f32_16x16x32_bf16 v[110:113], v[146:149], v[192:195], v[110:113]
	v_mfma_f32_16x16x32_bf16 v[102:105], v[172:175], v[192:195], v[102:105]
	v_mfma_f32_16x16x32_bf16 v[94:97], v[146:149], v[200:203], v[94:97]
	v_mfma_f32_16x16x32_bf16 v[86:89], v[172:175], v[200:203], v[86:89]
	v_mfma_f32_16x16x32_bf16 v[78:81], v[146:149], v[208:211], v[78:81]
	v_mfma_f32_16x16x32_bf16 v[70:73], v[172:175], v[208:211], v[70:73]
	v_mfma_f32_16x16x32_bf16 v[122:125], v[150:153], v[188:191], v[122:125]
	v_mfma_f32_16x16x32_bf16 v[126:129], v[176:179], v[188:191], v[126:129]
	v_mfma_f32_16x16x32_bf16 v[110:113], v[150:153], v[196:199], v[110:113]
	v_mfma_f32_16x16x32_bf16 v[102:105], v[176:179], v[196:199], v[102:105]
	v_mfma_f32_16x16x32_bf16 v[94:97], v[150:153], v[204:207], v[94:97]
	v_mfma_f32_16x16x32_bf16 v[86:89], v[176:179], v[204:207], v[86:89]
	v_mfma_f32_16x16x32_bf16 v[78:81], v[150:153], v[212:215], v[78:81]
	v_mfma_f32_16x16x32_bf16 v[70:73], v[176:179], v[212:215], v[70:73]
	s_barrier
	s_add_i32 s33, s48, s36
	s_mov_b32 m0, s33
	s_nop 0
	global_load_lds_dwordx4 v156, s[24:25]
	s_add_i32 m0, s33, 0x2000
	s_add_u32 s64, s24, 0x100000
	s_addc_u32 s65, s25, 0
	s_add_i32 s33, s49, s36
	global_load_lds_dwordx4 v160, s[24:25]
	s_mov_b32 m0, s33
	s_add_u32 s100, s28, 0x80
	s_addc_u32 s101, s29, 0
	global_load_lds_dwordx4 v156, s[64:65]
	s_add_i32 m0, s33, 0x2000
	s_nop 0
	global_load_lds_dwordx4 v160, s[64:65]
	s_mov_b32 m0, s23
	s_nop 0
	global_load_lds_dwordx4 v154, s[28:29]
	s_mov_b32 m0, s37
	s_nop 0
	global_load_lds_dwordx4 v158, s[28:29]
	ds_read_b128 v[180:183], v185 offset:16384
	ds_read_b128 v[188:191], v185 offset:17408
	ds_read_b128 v[192:195], v185 offset:18432
	ds_read_b128 v[196:199], v185 offset:19456
	ds_read_b128 v[200:203], v185 offset:20480
	ds_read_b128 v[204:207], v185 offset:21504
	ds_read_b128 v[208:211], v185 offset:22528
	ds_read_b128 v[212:215], v185 offset:23552
	s_waitcnt vmcnt(8) lgkmcnt(0)
	s_barrier
	v_mfma_f32_16x16x32_bf16 v[58:61], v[130:133], v[180:183], v[58:61]
	v_mfma_f32_16x16x32_bf16 v[54:57], v[138:141], v[180:183], v[54:57]
	v_mfma_f32_16x16x32_bf16 v[42:45], v[130:133], v[192:195], v[42:45]
	v_mfma_f32_16x16x32_bf16 v[34:37], v[138:141], v[192:195], v[34:37]
	v_mfma_f32_16x16x32_bf16 v[26:29], v[130:133], v[200:203], v[26:29]
	v_mfma_f32_16x16x32_bf16 v[18:21], v[138:141], v[200:203], v[18:21]
	v_mfma_f32_16x16x32_bf16 v[6:9], v[130:133], v[208:211], v[6:9]
	v_mfma_f32_16x16x32_bf16 v[2:5], v[138:141], v[208:211], v[2:5]
	v_mfma_f32_16x16x32_bf16 v[58:61], v[134:137], v[188:191], v[58:61]
	v_mfma_f32_16x16x32_bf16 v[54:57], v[142:145], v[188:191], v[54:57]
	v_mfma_f32_16x16x32_bf16 v[42:45], v[134:137], v[196:199], v[42:45]
	v_mfma_f32_16x16x32_bf16 v[34:37], v[142:145], v[196:199], v[34:37]
	v_mfma_f32_16x16x32_bf16 v[26:29], v[134:137], v[204:207], v[26:29]
	v_mfma_f32_16x16x32_bf16 v[18:21], v[142:145], v[204:207], v[18:21]
	v_mfma_f32_16x16x32_bf16 v[6:9], v[134:137], v[212:215], v[6:9]
	v_mfma_f32_16x16x32_bf16 v[2:5], v[142:145], v[212:215], v[2:5]
	v_mfma_f32_16x16x32_bf16 v[62:65], v[146:149], v[180:183], v[62:65]
	v_mfma_f32_16x16x32_bf16 v[50:53], v[172:175], v[180:183], v[50:53]
	v_mfma_f32_16x16x32_bf16 v[46:49], v[146:149], v[192:195], v[46:49]
	v_mfma_f32_16x16x32_bf16 v[38:41], v[172:175], v[192:195], v[38:41]
	v_mfma_f32_16x16x32_bf16 v[30:33], v[146:149], v[200:203], v[30:33]
	v_mfma_f32_16x16x32_bf16 v[22:25], v[172:175], v[200:203], v[22:25]
	v_mfma_f32_16x16x32_bf16 v[10:13], v[146:149], v[208:211], v[10:13]
	v_mfma_f32_16x16x32_bf16 v[14:17], v[172:175], v[208:211], v[14:17]
	v_mfma_f32_16x16x32_bf16 v[62:65], v[150:153], v[188:191], v[62:65]
	v_mfma_f32_16x16x32_bf16 v[50:53], v[176:179], v[188:191], v[50:53]
	v_mfma_f32_16x16x32_bf16 v[46:49], v[150:153], v[196:199], v[46:49]
	v_mfma_f32_16x16x32_bf16 v[38:41], v[176:179], v[196:199], v[38:41]
	v_mfma_f32_16x16x32_bf16 v[30:33], v[150:153], v[204:207], v[30:33]
	v_mfma_f32_16x16x32_bf16 v[22:25], v[176:179], v[204:207], v[22:25]
	v_mfma_f32_16x16x32_bf16 v[10:13], v[150:153], v[212:215], v[10:13]
	v_mfma_f32_16x16x32_bf16 v[14:17], v[176:179], v[212:215], v[14:17]
	s_barrier
; #define PG8_STAGE(bufoff, gbase, voff) do { _Pragma("unroll") for (int _i = 0; _i < 2; ++_i) \
;         __builtin_amdgcn_global_load_lds((const unsigned*)((const char*)(gbase) + (voff)[_i]), (PG8_LAS unsigned*)(lds + (bufoff) + ldsw + _i * 8192), 16, 0, 0); } while (0)
; #define PG8_LDA(dst, b, h) do { _Pragma("unroll") for (int m = 0; m < 4; ++m) _Pragma("unroll") for (int k = 0; k < 2; ++k) dst[m][k] = *(const PG8_LAS bf16x8*)(lds + PG8_SA(b, h) + aoff + m * 2048 + k * 1024); } while (0)
; #define PG8_LDB(dst, b, h) do { _Pragma("unroll") for (int n = 0; n < 2; ++n) _Pragma("unroll") for (int k = 0; k < 2; ++k) dst[n][k] = *(const PG8_LAS bf16x8*)(lds + PG8_SB(b, h) + boff + n * 2048 + k * 1024); } while (0)
; #define PG8_MMA(ai, bj, At, Bt) do { __builtin_amdgcn_s_setprio(1); _Pragma("unroll") for (int m = 0; m < 4; ++m) _Pragma("unroll") for (int n = 0; n < 2; ++n) _Pragma("unroll") for (int k = 0; k < 2; ++k) \
;         acc[ai][bj][m][n] = __builtin_amdgcn_mfma_f32_16x16x32_bf16(Bt[n][k], At[m][k], acc[ai][bj][m][n], 0, 0, 0); __builtin_amdgcn_s_setprio(0); } while (0)
; #define PG8_WAIT_V(n) asm volatile("s_waitcnt vmcnt(" #n ")" ::: "memory")
; #define PG8_WAIT_L(n) asm volatile("s_waitcnt lgkmcnt(" #n ")" ::: "memory")
; #define PG8_BAR __builtin_amdgcn_s_barrier()
; #define PG8_SCHED __builtin_amdgcn_sched_barrier(0)
; template <class Epi, class Sched, bool ALIGN_EPI = false, bool SP2 = false>
; __device__ __forceinline__ void gemm_phase(PG8_LAS unsigned char* lds, const Gemm g, const Sched& S, const Epi& E) {
;     ...
;             PG8_LDB(B0, 1, 0); PG8_LDB(B1, 1, 1); PG8_SCHED; PG8_LDA(At, 1, 0); PG8_STAGE(PG8_SA(0, 1), a2 + hstep, voffA);
;             PG8_WAIT_V(8); PG8_WAIT_L(0); PG8_BAR; PG8_MMA(0, 0, At, B0); PG8_MMA(0, 1, At, B1); PG8_BAR; PG8_SCHED;
;             PG8_LDA(At, 1, 1); PG8_STAGE(PG8_SB(1, 0), b3, voffB); PG8_STAGE(PG8_SB(1, 1), b3 + hstep, voffB); PG8_STAGE(PG8_SA(1, 0), a3, voffA);
;             PG8_WAIT_V(8); PG8_WAIT_L(0); PG8_BAR; PG8_MMA(1, 0, At, B0); PG8_MMA(1, 1, At, B1); PG8_BAR; PG8_SCHED;
;     ...
;         if constexpr (ALIGN_EPI) { if (wr == 0) PG8_BAR; }
	s_add_i32 s33, 0, 0x18000
	s_add_i32 s42, 0, 0x1c000
	s_add_u32 s28, s28, 0x100000
	s_addc_u32 s29, s29, 0
	s_mov_b32 m0, s40
	s_nop 0
	global_load_lds_dwordx4 v154, s[28:29]
	s_mov_b32 m0, s41
	s_nop 0
	global_load_lds_dwordx4 v158, s[28:29]
	ds_read_b128 v[130:133], v241 offset:32768
	ds_read_b128 v[134:137], v241 offset:33792
	ds_read_b128 v[138:141], v241 offset:34816
	ds_read_b128 v[142:145], v241 offset:35840
	ds_read_b128 v[146:149], v241 offset:49152
	ds_read_b128 v[150:153], v241 offset:50176
	ds_read_b128 v[172:175], v241 offset:51200
	ds_read_b128 v[176:179], v241 offset:52224
	ds_read_b128 v[180:183], v185 offset:32768
	ds_read_b128 v[188:191], v185 offset:33792
	ds_read_b128 v[192:195], v185 offset:34816
	ds_read_b128 v[196:199], v185 offset:35840
	ds_read_b128 v[200:203], v185 offset:36864
	ds_read_b128 v[204:207], v185 offset:37888
	ds_read_b128 v[208:211], v185 offset:38912
	ds_read_b128 v[212:215], v185 offset:39936
	s_waitcnt vmcnt(8) lgkmcnt(0)
	s_barrier
	v_mfma_f32_16x16x32_bf16 v[114:117], v[130:133], v[180:183], v[114:117]
	v_mfma_f32_16x16x32_bf16 v[118:121], v[138:141], v[180:183], v[118:121]
	v_mfma_f32_16x16x32_bf16 v[106:109], v[130:133], v[192:195], v[106:109]
	v_mfma_f32_16x16x32_bf16 v[98:101], v[138:141], v[192:195], v[98:101]
	v_mfma_f32_16x16x32_bf16 v[90:93], v[130:133], v[200:203], v[90:93]
	v_mfma_f32_16x16x32_bf16 v[82:85], v[138:141], v[200:203], v[82:85]
	v_mfma_f32_16x16x32_bf16 v[74:77], v[130:133], v[208:211], v[74:77]
	v_mfma_f32_16x16x32_bf16 v[66:69], v[138:141], v[208:211], v[66:69]
	v_mfma_f32_16x16x32_bf16 v[114:117], v[134:137], v[188:191], v[114:117]
	v_mfma_f32_16x16x32_bf16 v[118:121], v[142:145], v[188:191], v[118:121]
	v_mfma_f32_16x16x32_bf16 v[106:109], v[134:137], v[196:199], v[106:109]
	v_mfma_f32_16x16x32_bf16 v[98:101], v[142:145], v[196:199], v[98:101]
	v_mfma_f32_16x16x32_bf16 v[90:93], v[134:137], v[204:207], v[90:93]
	v_mfma_f32_16x16x32_bf16 v[82:85], v[142:145], v[204:207], v[82:85]
	v_mfma_f32_16x16x32_bf16 v[74:77], v[134:137], v[212:215], v[74:77]
	v_mfma_f32_16x16x32_bf16 v[66:69], v[142:145], v[212:215], v[66:69]
	v_mfma_f32_16x16x32_bf16 v[122:125], v[146:149], v[180:183], v[122:125]
	v_mfma_f32_16x16x32_bf16 v[126:129], v[172:175], v[180:183], v[126:129]
	v_mfma_f32_16x16x32_bf16 v[110:113], v[146:149], v[192:195], v[110:113]
	v_mfma_f32_16x16x32_bf16 v[102:105], v[172:175], v[192:195], v[102:105]
	v_mfma_f32_16x16x32_bf16 v[94:97], v[146:149], v[200:203], v[94:97]
	v_mfma_f32_16x16x32_bf16 v[86:89], v[172:175], v[200:203], v[86:89]
	v_mfma_f32_16x16x32_bf16 v[78:81], v[146:149], v[208:211], v[78:81]
	v_mfma_f32_16x16x32_bf16 v[70:73], v[172:175], v[208:211], v[70:73]
	v_mfma_f32_16x16x32_bf16 v[122:125], v[150:153], v[188:191], v[122:125]
	v_mfma_f32_16x16x32_bf16 v[126:129], v[176:179], v[188:191], v[126:129]
	v_mfma_f32_16x16x32_bf16 v[110:113], v[150:153], v[196:199], v[110:113]
	v_mfma_f32_16x16x32_bf16 v[102:105], v[176:179], v[196:199], v[102:105]
	v_mfma_f32_16x16x32_bf16 v[94:97], v[150:153], v[204:207], v[94:97]
	v_mfma_f32_16x16x32_bf16 v[86:89], v[176:179], v[204:207], v[86:89]
	v_mfma_f32_16x16x32_bf16 v[78:81], v[150:153], v[212:215], v[78:81]
	v_mfma_f32_16x16x32_bf16 v[70:73], v[176:179], v[212:215], v[70:73]
	s_barrier
	s_add_i32 s28, s33, s36
	s_add_i32 m0, s28, 0xffffff80
	s_nop 0
	global_load_lds_dwordx4 v156, s[24:25] offset:128
	s_add_i32 m0, s28, 0x1f80
	s_add_i32 s28, s42, s36
	global_load_lds_dwordx4 v160, s[24:25] offset:128
	s_add_u32 s24, s24, 0x100080
	s_addc_u32 s25, s25, 0
	s_mov_b32 m0, s28
	s_nop 0
	global_load_lds_dwordx4 v156, s[24:25]
	s_add_i32 m0, s28, 0x2000
	s_nop 0
	global_load_lds_dwordx4 v160, s[24:25]
	s_mov_b32 m0, s44
	s_nop 0
	global_load_lds_dwordx4 v154, s[100:101]
	s_mov_b32 m0, s45
	s_nop 0
	global_load_lds_dwordx4 v158, s[100:101]
	ds_read_b128 v[180:183], v185 offset:49152
	ds_read_b128 v[188:191], v185 offset:50176
	ds_read_b128 v[192:195], v185 offset:51200
	ds_read_b128 v[196:199], v185 offset:52224
	ds_read_b128 v[200:203], v185 offset:53248
	ds_read_b128 v[204:207], v185 offset:54272
	ds_read_b128 v[208:211], v185 offset:55296
	ds_read_b128 v[212:215], v185 offset:56320
	s_waitcnt vmcnt(8) lgkmcnt(0)
	s_barrier
	v_mfma_f32_16x16x32_bf16 v[58:61], v[130:133], v[180:183], v[58:61]
	v_mfma_f32_16x16x32_bf16 v[54:57], v[138:141], v[180:183], v[54:57]
	v_mfma_f32_16x16x32_bf16 v[42:45], v[130:133], v[192:195], v[42:45]
	v_mfma_f32_16x16x32_bf16 v[34:37], v[138:141], v[192:195], v[34:37]
	v_mfma_f32_16x16x32_bf16 v[26:29], v[130:133], v[200:203], v[26:29]
	v_mfma_f32_16x16x32_bf16 v[18:21], v[138:141], v[200:203], v[18:21]
	v_mfma_f32_16x16x32_bf16 v[6:9], v[130:133], v[208:211], v[6:9]
	v_mfma_f32_16x16x32_bf16 v[2:5], v[138:141], v[208:211], v[2:5]
	v_mfma_f32_16x16x32_bf16 v[58:61], v[134:137], v[188:191], v[58:61]
	v_mfma_f32_16x16x32_bf16 v[54:57], v[142:145], v[188:191], v[54:57]
	v_mfma_f32_16x16x32_bf16 v[42:45], v[134:137], v[196:199], v[42:45]
	v_mfma_f32_16x16x32_bf16 v[34:37], v[142:145], v[196:199], v[34:37]
	v_mfma_f32_16x16x32_bf16 v[26:29], v[134:137], v[204:207], v[26:29]
	v_mfma_f32_16x16x32_bf16 v[18:21], v[142:145], v[204:207], v[18:21]
	v_mfma_f32_16x16x32_bf16 v[6:9], v[134:137], v[212:215], v[6:9]
	v_mfma_f32_16x16x32_bf16 v[2:5], v[142:145], v[212:215], v[2:5]
	v_mfma_f32_16x16x32_bf16 v[62:65], v[146:149], v[180:183], v[62:65]
	v_mfma_f32_16x16x32_bf16 v[50:53], v[172:175], v[180:183], v[50:53]
	v_mfma_f32_16x16x32_bf16 v[46:49], v[146:149], v[192:195], v[46:49]
	v_mfma_f32_16x16x32_bf16 v[38:41], v[172:175], v[192:195], v[38:41]
	v_mfma_f32_16x16x32_bf16 v[30:33], v[146:149], v[200:203], v[30:33]
	v_mfma_f32_16x16x32_bf16 v[22:25], v[172:175], v[200:203], v[22:25]
	v_mfma_f32_16x16x32_bf16 v[10:13], v[146:149], v[208:211], v[10:13]
	v_mfma_f32_16x16x32_bf16 v[14:17], v[172:175], v[208:211], v[14:17]
	v_mfma_f32_16x16x32_bf16 v[62:65], v[150:153], v[188:191], v[62:65]
	v_mfma_f32_16x16x32_bf16 v[50:53], v[176:179], v[188:191], v[50:53]
	v_mfma_f32_16x16x32_bf16 v[46:49], v[150:153], v[196:199], v[46:49]
	v_mfma_f32_16x16x32_bf16 v[38:41], v[176:179], v[196:199], v[38:41]
	v_mfma_f32_16x16x32_bf16 v[30:33], v[150:153], v[204:207], v[30:33]
	v_mfma_f32_16x16x32_bf16 v[22:25], v[176:179], v[204:207], v[22:25]
	v_mfma_f32_16x16x32_bf16 v[10:13], v[150:153], v[212:215], v[10:13]
	v_mfma_f32_16x16x32_bf16 v[14:17], v[176:179], v[212:215], v[14:17]
	s_barrier
	s_add_i32 s62, s62, 2
	s_add_u32 s26, s26, 0x100
	s_addc_u32 s27, s27, 0
	s_add_u32 s52, s52, 0x100
	s_addc_u32 s53, s53, 0
	s_cmp_gt_u32 s62, 61
	s_cbranch_scc0 .LBB0_1595
	s_and_b64 vcc, exec, s[10:11]
	s_cbranch_vccz .LBB0_1598
	s_barrier

; #define PG8_STAGE(bufoff, gbase, voff) do { _Pragma("unroll") for (int _i = 0; _i < 2; ++_i) \
;         __builtin_amdgcn_global_load_lds((const unsigned*)((const char*)(gbase) + (voff)[_i]), (PG8_LAS unsigned*)(lds + (bufoff) + ldsw + _i * 8192), 16, 0, 0); } while (0)
; #define PG8_LDA(dst, b, h) do { _Pragma("unroll") for (int m = 0; m < 4; ++m) _Pragma("unroll") for (int k = 0; k < 2; ++k) dst[m][k] = *(const PG8_LAS bf16x8*)(lds + PG8_SA(b, h) + aoff + m * 2048 + k * 1024); } while (0)
; #define PG8_LDB(dst, b, h) do { _Pragma("unroll") for (int n = 0; n < 2; ++n) _Pragma("unroll") for (int k = 0; k < 2; ++k) dst[n][k] = *(const PG8_LAS bf16x8*)(lds + PG8_SB(b, h) + boff + n * 2048 + k * 1024); } while (0)
; #define PG8_MMA(ai, bj, At, Bt) do { __builtin_amdgcn_s_setprio(1); _Pragma("unroll") for (int m = 0; m < 4; ++m) _Pragma("unroll") for (int n = 0; n < 2; ++n) _Pragma("unroll") for (int k = 0; k < 2; ++k) \
;         acc[ai][bj][m][n] = __builtin_amdgcn_mfma_f32_16x16x32_bf16(Bt[n][k], At[m][k], acc[ai][bj][m][n], 0, 0, 0); __builtin_amdgcn_s_setprio(0); } while (0)
; #define PG8_WAIT_V(n) asm volatile("s_waitcnt vmcnt(" #n ")" ::: "memory")
; #define PG8_WAIT_L(n) asm volatile("s_waitcnt lgkmcnt(" #n ")" ::: "memory")
; #define PG8_BAR __builtin_amdgcn_s_barrier()
; #define PG8_SCHED __builtin_amdgcn_sched_barrier(0)
; template <class Epi, class Sched, bool ALIGN_EPI = false, bool SP2 = false>
; __device__ __forceinline__ void gemm_phase(PG8_LAS unsigned char* lds, const Gemm g, const Sched& S, const Epi& E) {
;     ...
;             PG8_LDB(B0, 0, 0); PG8_LDB(B1, 0, 1); PG8_SCHED; PG8_LDA(At, 0, 0); PG8_STAGE(PG8_SA(1, 1), a1 + hstep, voffA);
;             PG8_WAIT_V(8); PG8_WAIT_L(0); PG8_BAR; PG8_MMA(0, 0, At, B0); PG8_MMA(0, 1, At, B1); PG8_BAR; PG8_SCHED;
;             PG8_LDA(At, 0, 1); PG8_STAGE(PG8_SB(0, 0), b2, voffB); PG8_STAGE(PG8_SB(0, 1), b2 + hstep, voffB); PG8_STAGE(PG8_SA(0, 0), a2, voffA);
;             PG8_WAIT_V(8); PG8_WAIT_L(0); PG8_BAR; PG8_MMA(1, 0, At, B0); PG8_MMA(1, 1, At, B1); PG8_BAR; PG8_SCHED;
.LBB0_1681:
	s_add_u32 s22, s24, 0xfff00080
	s_addc_u32 s23, s25, -1
	s_cmp_eq_u32 s52, 60
	s_cselect_b32 s27, s15, s23
	s_cselect_b32 s26, s48, s22
	s_cselect_b32 s23, s13, s51
	s_cselect_b32 s22, s49, s50
	s_add_i32 m0, s21, 0xc000
	s_nop 0
	global_load_lds_dwordx4 v138, s[24:25]
	s_add_i32 m0, s21, 0xe000
	s_nop 0
	global_load_lds_dwordx4 v140, s[24:25]
	ds_read_b128 v[160:163], v241 offset:0
	ds_read_b128 v[166:169], v241 offset:1024
	ds_read_b128 v[170:173], v241 offset:2048
	ds_read_b128 v[174:177], v241 offset:3072
	ds_read_b128 v[178:181], v241 offset:16384
	ds_read_b128 v[182:185], v241 offset:17408
	ds_read_b128 v[186:189], v241 offset:18432
	ds_read_b128 v[190:193], v241 offset:19456
	ds_read_b128 v[194:197], v155
	ds_read_b128 v[198:201], v155 offset:1024
	ds_read_b128 v[202:205], v155 offset:2048
	ds_read_b128 v[206:209], v155 offset:3072
	ds_read_b128 v[210:213], v155 offset:4096
	ds_read_b128 v[214:217], v155 offset:5120
	ds_read_b128 v[218:221], v155 offset:6144
	ds_read_b128 v[222:225], v155 offset:7168
	s_waitcnt vmcnt(8) lgkmcnt(0)
	s_barrier
	v_mfma_f32_16x16x32_bf16 v[122:125], v[160:163], v[194:197], v[122:125]
	v_mfma_f32_16x16x32_bf16 v[114:117], v[170:173], v[194:197], v[114:117]
	v_mfma_f32_16x16x32_bf16 v[106:109], v[160:163], v[202:205], v[106:109]
	v_mfma_f32_16x16x32_bf16 v[98:101], v[170:173], v[202:205], v[98:101]
	v_mfma_f32_16x16x32_bf16 v[90:93], v[160:163], v[210:213], v[90:93]
	v_mfma_f32_16x16x32_bf16 v[82:85], v[170:173], v[210:213], v[82:85]
	v_mfma_f32_16x16x32_bf16 v[74:77], v[160:163], v[218:221], v[74:77]
	v_mfma_f32_16x16x32_bf16 v[62:65], v[170:173], v[218:221], v[62:65]
	v_mfma_f32_16x16x32_bf16 v[122:125], v[166:169], v[198:201], v[122:125]
	v_mfma_f32_16x16x32_bf16 v[114:117], v[174:177], v[198:201], v[114:117]
	v_mfma_f32_16x16x32_bf16 v[106:109], v[166:169], v[206:209], v[106:109]
	v_mfma_f32_16x16x32_bf16 v[98:101], v[174:177], v[206:209], v[98:101]
	v_mfma_f32_16x16x32_bf16 v[90:93], v[166:169], v[214:217], v[90:93]
	v_mfma_f32_16x16x32_bf16 v[82:85], v[174:177], v[214:217], v[82:85]
	v_mfma_f32_16x16x32_bf16 v[74:77], v[166:169], v[222:225], v[74:77]
	v_mfma_f32_16x16x32_bf16 v[62:65], v[174:177], v[222:225], v[62:65]
	v_mfma_f32_16x16x32_bf16 v[126:129], v[178:181], v[194:197], v[126:129]
	v_mfma_f32_16x16x32_bf16 v[118:121], v[186:189], v[194:197], v[118:121]
	v_mfma_f32_16x16x32_bf16 v[110:113], v[178:181], v[202:205], v[110:113]
	v_mfma_f32_16x16x32_bf16 v[102:105], v[186:189], v[202:205], v[102:105]
	v_mfma_f32_16x16x32_bf16 v[94:97], v[178:181], v[210:213], v[94:97]
	v_mfma_f32_16x16x32_bf16 v[86:89], v[186:189], v[210:213], v[86:89]
	v_mfma_f32_16x16x32_bf16 v[78:81], v[178:181], v[218:221], v[78:81]
	v_mfma_f32_16x16x32_bf16 v[70:73], v[186:189], v[218:221], v[70:73]
	v_mfma_f32_16x16x32_bf16 v[126:129], v[182:185], v[198:201], v[126:129]
	v_mfma_f32_16x16x32_bf16 v[118:121], v[190:193], v[198:201], v[118:121]
	v_mfma_f32_16x16x32_bf16 v[110:113], v[182:185], v[206:209], v[110:113]
	v_mfma_f32_16x16x32_bf16 v[102:105], v[190:193], v[206:209], v[102:105]
	v_mfma_f32_16x16x32_bf16 v[94:97], v[182:185], v[214:217], v[94:97]
	v_mfma_f32_16x16x32_bf16 v[86:89], v[190:193], v[214:217], v[86:89]
	v_mfma_f32_16x16x32_bf16 v[78:81], v[182:185], v[222:225], v[78:81]
	v_mfma_f32_16x16x32_bf16 v[70:73], v[190:193], v[222:225], v[70:73]
	s_barrier
	s_add_i32 s33, s44, s29
	s_mov_b32 m0, s33
	s_nop 0
	global_load_lds_dwordx4 v132, s[22:23]
	s_add_i32 m0, s33, 0x2000
	s_add_u32 s62, s22, 0x100000
	s_addc_u32 s63, s23, 0
	s_add_i32 s33, s45, s29
	global_load_lds_dwordx4 v136, s[22:23]
	s_mov_b32 m0, s33
	s_add_u32 s100, s26, 0x80
	s_addc_u32 s101, s27, 0
	global_load_lds_dwordx4 v132, s[62:63]
	s_add_i32 m0, s33, 0x2000
	s_nop 0
	global_load_lds_dwordx4 v136, s[62:63]
	s_mov_b32 m0, s21
	s_nop 0
	global_load_lds_dwordx4 v130, s[26:27]
	s_mov_b32 m0, s34
	s_nop 0
	global_load_lds_dwordx4 v134, s[26:27]
	ds_read_b128 v[194:197], v155 offset:16384
	ds_read_b128 v[198:201], v155 offset:17408
	ds_read_b128 v[202:205], v155 offset:18432
	ds_read_b128 v[206:209], v155 offset:19456
	ds_read_b128 v[210:213], v155 offset:20480
	ds_read_b128 v[214:217], v155 offset:21504
	ds_read_b128 v[218:221], v155 offset:22528
	ds_read_b128 v[222:225], v155 offset:23552
	s_waitcnt vmcnt(8) lgkmcnt(0)
	s_barrier
	v_mfma_f32_16x16x32_bf16 v[58:61], v[160:163], v[194:197], v[58:61]
	v_mfma_f32_16x16x32_bf16 v[50:53], v[170:173], v[194:197], v[50:53]
	v_mfma_f32_16x16x32_bf16 v[42:45], v[160:163], v[202:205], v[42:45]
	v_mfma_f32_16x16x32_bf16 v[34:37], v[170:173], v[202:205], v[34:37]
	v_mfma_f32_16x16x32_bf16 v[26:29], v[160:163], v[210:213], v[26:29]
	v_mfma_f32_16x16x32_bf16 v[18:21], v[170:173], v[210:213], v[18:21]
	v_mfma_f32_16x16x32_bf16 v[10:13], v[160:163], v[218:221], v[10:13]
	v_mfma_f32_16x16x32_bf16 v[2:5], v[170:173], v[218:221], v[2:5]
	v_mfma_f32_16x16x32_bf16 v[58:61], v[166:169], v[198:201], v[58:61]
	v_mfma_f32_16x16x32_bf16 v[50:53], v[174:177], v[198:201], v[50:53]
	v_mfma_f32_16x16x32_bf16 v[42:45], v[166:169], v[206:209], v[42:45]
	v_mfma_f32_16x16x32_bf16 v[34:37], v[174:177], v[206:209], v[34:37]
	v_mfma_f32_16x16x32_bf16 v[26:29], v[166:169], v[214:217], v[26:29]
	v_mfma_f32_16x16x32_bf16 v[18:21], v[174:177], v[214:217], v[18:21]
	v_mfma_f32_16x16x32_bf16 v[10:13], v[166:169], v[222:225], v[10:13]
	v_mfma_f32_16x16x32_bf16 v[2:5], v[174:177], v[222:225], v[2:5]
	v_mfma_f32_16x16x32_bf16 v[66:69], v[178:181], v[194:197], v[66:69]
	v_mfma_f32_16x16x32_bf16 v[54:57], v[186:189], v[194:197], v[54:57]
	v_mfma_f32_16x16x32_bf16 v[46:49], v[178:181], v[202:205], v[46:49]
	v_mfma_f32_16x16x32_bf16 v[38:41], v[186:189], v[202:205], v[38:41]
	v_mfma_f32_16x16x32_bf16 v[30:33], v[178:181], v[210:213], v[30:33]
	v_mfma_f32_16x16x32_bf16 v[22:25], v[186:189], v[210:213], v[22:25]
	v_mfma_f32_16x16x32_bf16 v[14:17], v[178:181], v[218:221], v[14:17]
	v_mfma_f32_16x16x32_bf16 v[6:9], v[186:189], v[218:221], v[6:9]
	v_mfma_f32_16x16x32_bf16 v[66:69], v[182:185], v[198:201], v[66:69]
	v_mfma_f32_16x16x32_bf16 v[54:57], v[190:193], v[198:201], v[54:57]
	v_mfma_f32_16x16x32_bf16 v[46:49], v[182:185], v[206:209], v[46:49]
	v_mfma_f32_16x16x32_bf16 v[38:41], v[190:193], v[206:209], v[38:41]
	v_mfma_f32_16x16x32_bf16 v[30:33], v[182:185], v[214:217], v[30:33]
	v_mfma_f32_16x16x32_bf16 v[22:25], v[190:193], v[214:217], v[22:25]
	v_mfma_f32_16x16x32_bf16 v[14:17], v[182:185], v[222:225], v[14:17]
	v_mfma_f32_16x16x32_bf16 v[6:9], v[190:193], v[222:225], v[6:9]
	s_barrier
; #define PG8_STAGE(bufoff, gbase, voff) do { _Pragma("unroll") for (int _i = 0; _i < 2; ++_i) \
;         __builtin_amdgcn_global_load_lds((const unsigned*)((const char*)(gbase) + (voff)[_i]), (PG8_LAS unsigned*)(lds + (bufoff) + ldsw + _i * 8192), 16, 0, 0); } while (0)
; #define PG8_LDA(dst, b, h) do { _Pragma("unroll") for (int m = 0; m < 4; ++m) _Pragma("unroll") for (int k = 0; k < 2; ++k) dst[m][k] = *(const PG8_LAS bf16x8*)(lds + PG8_SA(b, h) + aoff + m * 2048 + k * 1024); } while (0)
; #define PG8_LDB(dst, b, h) do { _Pragma("unroll") for (int n = 0; n < 2; ++n) _Pragma("unroll") for (int k = 0; k < 2; ++k) dst[n][k] = *(const PG8_LAS bf16x8*)(lds + PG8_SB(b, h) + boff + n * 2048 + k * 1024); } while (0)
; #define PG8_MMA(ai, bj, At, Bt) do { __builtin_amdgcn_s_setprio(1); _Pragma("unroll") for (int m = 0; m < 4; ++m) _Pragma("unroll") for (int n = 0; n < 2; ++n) _Pragma("unroll") for (int k = 0; k < 2; ++k) \
;         acc[ai][bj][m][n] = __builtin_amdgcn_mfma_f32_16x16x32_bf16(Bt[n][k], At[m][k], acc[ai][bj][m][n], 0, 0, 0); __builtin_amdgcn_s_setprio(0); } while (0)
; #define PG8_WAIT_V(n) asm volatile("s_waitcnt vmcnt(" #n ")" ::: "memory")
; #define PG8_WAIT_L(n) asm volatile("s_waitcnt lgkmcnt(" #n ")" ::: "memory")
; #define PG8_BAR __builtin_amdgcn_s_barrier()
; #define PG8_SCHED __builtin_amdgcn_sched_barrier(0)
; template <class Epi, class Sched, bool ALIGN_EPI = false, bool SP2 = false>
; __device__ __forceinline__ void gemm_phase(PG8_LAS unsigned char* lds, const Gemm g, const Sched& S, const Epi& E) {
;     ...
;             PG8_LDB(B0, 1, 0); PG8_LDB(B1, 1, 1); PG8_SCHED; PG8_LDA(At, 1, 0); PG8_STAGE(PG8_SA(0, 1), a2 + hstep, voffA);
;             PG8_WAIT_V(8); PG8_WAIT_L(0); PG8_BAR; PG8_MMA(0, 0, At, B0); PG8_MMA(0, 1, At, B1); PG8_BAR; PG8_SCHED;
;             PG8_LDA(At, 1, 1); PG8_STAGE(PG8_SB(1, 0), b3, voffB); PG8_STAGE(PG8_SB(1, 1), b3 + hstep, voffB); PG8_STAGE(PG8_SA(1, 0), a3, voffA);
;             PG8_WAIT_V(8); PG8_WAIT_L(0); PG8_BAR; PG8_MMA(1, 0, At, B0); PG8_MMA(1, 1, At, B1); PG8_BAR; PG8_SCHED;
;     ...
;         if constexpr (ALIGN_EPI) { if (wr == 0) PG8_BAR; }
	s_add_i32 s33, 0, 0x18000
	s_add_i32 s42, 0, 0x1c000
	s_add_u32 s26, s26, 0x100000
	s_addc_u32 s27, s27, 0
	s_mov_b32 m0, s35
	s_nop 0
	global_load_lds_dwordx4 v130, s[26:27]
	s_mov_b32 m0, s36
	s_nop 0
	global_load_lds_dwordx4 v134, s[26:27]
	ds_read_b128 v[160:163], v241 offset:32768
	ds_read_b128 v[166:169], v241 offset:33792
	ds_read_b128 v[170:173], v241 offset:34816
	ds_read_b128 v[174:177], v241 offset:35840
	ds_read_b128 v[178:181], v241 offset:49152
	ds_read_b128 v[182:185], v241 offset:50176
	ds_read_b128 v[186:189], v241 offset:51200
	ds_read_b128 v[190:193], v241 offset:52224
	ds_read_b128 v[194:197], v155 offset:32768
	ds_read_b128 v[198:201], v155 offset:33792
	ds_read_b128 v[202:205], v155 offset:34816
	ds_read_b128 v[206:209], v155 offset:35840
	ds_read_b128 v[210:213], v155 offset:36864
	ds_read_b128 v[214:217], v155 offset:37888
	ds_read_b128 v[218:221], v155 offset:38912
	ds_read_b128 v[222:225], v155 offset:39936
	s_waitcnt vmcnt(8) lgkmcnt(0)
	s_barrier
	v_mfma_f32_16x16x32_bf16 v[122:125], v[160:163], v[194:197], v[122:125]
	v_mfma_f32_16x16x32_bf16 v[114:117], v[170:173], v[194:197], v[114:117]
	v_mfma_f32_16x16x32_bf16 v[106:109], v[160:163], v[202:205], v[106:109]
	v_mfma_f32_16x16x32_bf16 v[98:101], v[170:173], v[202:205], v[98:101]
	v_mfma_f32_16x16x32_bf16 v[90:93], v[160:163], v[210:213], v[90:93]
	v_mfma_f32_16x16x32_bf16 v[82:85], v[170:173], v[210:213], v[82:85]
	v_mfma_f32_16x16x32_bf16 v[74:77], v[160:163], v[218:221], v[74:77]
	v_mfma_f32_16x16x32_bf16 v[62:65], v[170:173], v[218:221], v[62:65]
	v_mfma_f32_16x16x32_bf16 v[122:125], v[166:169], v[198:201], v[122:125]
	v_mfma_f32_16x16x32_bf16 v[114:117], v[174:177], v[198:201], v[114:117]
	v_mfma_f32_16x16x32_bf16 v[106:109], v[166:169], v[206:209], v[106:109]
	v_mfma_f32_16x16x32_bf16 v[98:101], v[174:177], v[206:209], v[98:101]
	v_mfma_f32_16x16x32_bf16 v[90:93], v[166:169], v[214:217], v[90:93]
	v_mfma_f32_16x16x32_bf16 v[82:85], v[174:177], v[214:217], v[82:85]
	v_mfma_f32_16x16x32_bf16 v[74:77], v[166:169], v[222:225], v[74:77]
	v_mfma_f32_16x16x32_bf16 v[62:65], v[174:177], v[222:225], v[62:65]
	v_mfma_f32_16x16x32_bf16 v[126:129], v[178:181], v[194:197], v[126:129]
	v_mfma_f32_16x16x32_bf16 v[118:121], v[186:189], v[194:197], v[118:121]
	v_mfma_f32_16x16x32_bf16 v[110:113], v[178:181], v[202:205], v[110:113]
	v_mfma_f32_16x16x32_bf16 v[102:105], v[186:189], v[202:205], v[102:105]
	v_mfma_f32_16x16x32_bf16 v[94:97], v[178:181], v[210:213], v[94:97]
	v_mfma_f32_16x16x32_bf16 v[86:89], v[186:189], v[210:213], v[86:89]
	v_mfma_f32_16x16x32_bf16 v[78:81], v[178:181], v[218:221], v[78:81]
	v_mfma_f32_16x16x32_bf16 v[70:73], v[186:189], v[218:221], v[70:73]
	v_mfma_f32_16x16x32_bf16 v[126:129], v[182:185], v[198:201], v[126:129]
	v_mfma_f32_16x16x32_bf16 v[118:121], v[190:193], v[198:201], v[118:121]
	v_mfma_f32_16x16x32_bf16 v[110:113], v[182:185], v[206:209], v[110:113]
	v_mfma_f32_16x16x32_bf16 v[102:105], v[190:193], v[206:209], v[102:105]
	v_mfma_f32_16x16x32_bf16 v[94:97], v[182:185], v[214:217], v[94:97]
	v_mfma_f32_16x16x32_bf16 v[86:89], v[190:193], v[214:217], v[86:89]
	v_mfma_f32_16x16x32_bf16 v[78:81], v[182:185], v[222:225], v[78:81]
	v_mfma_f32_16x16x32_bf16 v[70:73], v[190:193], v[222:225], v[70:73]
	s_barrier
	s_add_i32 s26, s33, s29
	s_add_i32 m0, s26, 0xffffff80
	s_nop 0
	global_load_lds_dwordx4 v132, s[22:23] offset:128
	s_add_i32 m0, s26, 0x1f80
	s_add_i32 s26, s42, s29
	global_load_lds_dwordx4 v136, s[22:23] offset:128
	s_add_u32 s22, s22, 0x100080
	s_addc_u32 s23, s23, 0
	s_mov_b32 m0, s26
	s_nop 0
	global_load_lds_dwordx4 v132, s[22:23]
	s_add_i32 m0, s26, 0x2000
	s_nop 0
	global_load_lds_dwordx4 v136, s[22:23]
	s_mov_b32 m0, s41
	s_nop 0
	global_load_lds_dwordx4 v130, s[100:101]
	s_mov_b32 m0, s43
	s_nop 0
	global_load_lds_dwordx4 v134, s[100:101]
	ds_read_b128 v[194:197], v155 offset:49152
	ds_read_b128 v[198:201], v155 offset:50176
	ds_read_b128 v[202:205], v155 offset:51200
	ds_read_b128 v[206:209], v155 offset:52224
	ds_read_b128 v[210:213], v155 offset:53248
	ds_read_b128 v[214:217], v155 offset:54272
	ds_read_b128 v[218:221], v155 offset:55296
	ds_read_b128 v[222:225], v155 offset:56320
	s_waitcnt vmcnt(8) lgkmcnt(0)
	s_barrier
	v_mfma_f32_16x16x32_bf16 v[58:61], v[160:163], v[194:197], v[58:61]
	v_mfma_f32_16x16x32_bf16 v[50:53], v[170:173], v[194:197], v[50:53]
	v_mfma_f32_16x16x32_bf16 v[42:45], v[160:163], v[202:205], v[42:45]
	v_mfma_f32_16x16x32_bf16 v[34:37], v[170:173], v[202:205], v[34:37]
	v_mfma_f32_16x16x32_bf16 v[26:29], v[160:163], v[210:213], v[26:29]
	v_mfma_f32_16x16x32_bf16 v[18:21], v[170:173], v[210:213], v[18:21]
	v_mfma_f32_16x16x32_bf16 v[10:13], v[160:163], v[218:221], v[10:13]
	v_mfma_f32_16x16x32_bf16 v[2:5], v[170:173], v[218:221], v[2:5]
	v_mfma_f32_16x16x32_bf16 v[58:61], v[166:169], v[198:201], v[58:61]
	v_mfma_f32_16x16x32_bf16 v[50:53], v[174:177], v[198:201], v[50:53]
	v_mfma_f32_16x16x32_bf16 v[42:45], v[166:169], v[206:209], v[42:45]
	v_mfma_f32_16x16x32_bf16 v[34:37], v[174:177], v[206:209], v[34:37]
	v_mfma_f32_16x16x32_bf16 v[26:29], v[166:169], v[214:217], v[26:29]
	v_mfma_f32_16x16x32_bf16 v[18:21], v[174:177], v[214:217], v[18:21]
	v_mfma_f32_16x16x32_bf16 v[10:13], v[166:169], v[222:225], v[10:13]
	v_mfma_f32_16x16x32_bf16 v[2:5], v[174:177], v[222:225], v[2:5]
	v_mfma_f32_16x16x32_bf16 v[66:69], v[178:181], v[194:197], v[66:69]
	v_mfma_f32_16x16x32_bf16 v[54:57], v[186:189], v[194:197], v[54:57]
	v_mfma_f32_16x16x32_bf16 v[46:49], v[178:181], v[202:205], v[46:49]
	v_mfma_f32_16x16x32_bf16 v[38:41], v[186:189], v[202:205], v[38:41]
	v_mfma_f32_16x16x32_bf16 v[30:33], v[178:181], v[210:213], v[30:33]
	v_mfma_f32_16x16x32_bf16 v[22:25], v[186:189], v[210:213], v[22:25]
	v_mfma_f32_16x16x32_bf16 v[14:17], v[178:181], v[218:221], v[14:17]
	v_mfma_f32_16x16x32_bf16 v[6:9], v[186:189], v[218:221], v[6:9]
	v_mfma_f32_16x16x32_bf16 v[66:69], v[182:185], v[198:201], v[66:69]
	v_mfma_f32_16x16x32_bf16 v[54:57], v[190:193], v[198:201], v[54:57]
	v_mfma_f32_16x16x32_bf16 v[46:49], v[182:185], v[206:209], v[46:49]
	v_mfma_f32_16x16x32_bf16 v[38:41], v[190:193], v[206:209], v[38:41]
	v_mfma_f32_16x16x32_bf16 v[30:33], v[182:185], v[214:217], v[30:33]
	v_mfma_f32_16x16x32_bf16 v[22:25], v[190:193], v[214:217], v[22:25]
	v_mfma_f32_16x16x32_bf16 v[14:17], v[182:185], v[222:225], v[14:17]
	v_mfma_f32_16x16x32_bf16 v[6:9], v[190:193], v[222:225], v[6:9]
	s_barrier
	s_add_i32 s52, s52, 2
	s_add_u32 s24, s24, 0x100
	s_addc_u32 s25, s25, 0
	s_add_u32 s50, s50, 0x100
	s_addc_u32 s51, s51, 0
	s_cmp_gt_u32 s52, 61
	s_cbranch_scc0 .LBB0_1681
	s_and_b64 vcc, exec, s[8:9]
	s_cbranch_vccz .LBB0_1684
	s_barrier

; #define PG8_STAGE(bufoff, gbase, voff) do { _Pragma("unroll") for (int _i = 0; _i < 2; ++_i) \
;         __builtin_amdgcn_global_load_lds((const unsigned*)((const char*)(gbase) + (voff)[_i]), (PG8_LAS unsigned*)(lds + (bufoff) + ldsw + _i * 8192), 16, 0, 0); } while (0)
; #define PG8_LDA(dst, b, h) do { _Pragma("unroll") for (int m = 0; m < 4; ++m) _Pragma("unroll") for (int k = 0; k < 2; ++k) dst[m][k] = *(const PG8_LAS bf16x8*)(lds + PG8_SA(b, h) + aoff + m * 2048 + k * 1024); } while (0)
; #define PG8_LDB(dst, b, h) do { _Pragma("unroll") for (int n = 0; n < 2; ++n) _Pragma("unroll") for (int k = 0; k < 2; ++k) dst[n][k] = *(const PG8_LAS bf16x8*)(lds + PG8_SB(b, h) + boff + n * 2048 + k * 1024); } while (0)
; #define PG8_MMA(ai, bj, At, Bt) do { __builtin_amdgcn_s_setprio(1); _Pragma("unroll") for (int m = 0; m < 4; ++m) _Pragma("unroll") for (int n = 0; n < 2; ++n) _Pragma("unroll") for (int k = 0; k < 2; ++k) \
;         acc[ai][bj][m][n] = __builtin_amdgcn_mfma_f32_16x16x32_bf16(Bt[n][k], At[m][k], acc[ai][bj][m][n], 0, 0, 0); __builtin_amdgcn_s_setprio(0); } while (0)
; #define PG8_WAIT_V(n) asm volatile("s_waitcnt vmcnt(" #n ")" ::: "memory")
; #define PG8_WAIT_L(n) asm volatile("s_waitcnt lgkmcnt(" #n ")" ::: "memory")
; #define PG8_BAR __builtin_amdgcn_s_barrier()
; #define PG8_SCHED __builtin_amdgcn_sched_barrier(0)
; template <class Epi, class Sched, bool ALIGN_EPI = false, bool SP2 = false>
; __device__ __forceinline__ void gemm_phase(PG8_LAS unsigned char* lds, const Gemm g, const Sched& S, const Epi& E) {
;     ...
;             PG8_LDB(B0, 0, 0); PG8_LDB(B1, 0, 1); PG8_SCHED; PG8_LDA(At, 0, 0); PG8_STAGE(PG8_SA(1, 1), a1 + hstep, voffA);
;             PG8_WAIT_V(8); PG8_WAIT_L(0); PG8_BAR; PG8_MMA(0, 0, At, B0); PG8_MMA(0, 1, At, B1); PG8_BAR; PG8_SCHED;
;             PG8_LDA(At, 0, 1); PG8_STAGE(PG8_SB(0, 0), b2, voffB); PG8_STAGE(PG8_SB(0, 1), b2 + hstep, voffB); PG8_STAGE(PG8_SA(0, 0), a2, voffA);
;             PG8_WAIT_V(8); PG8_WAIT_L(0); PG8_BAR; PG8_MMA(1, 0, At, B0); PG8_MMA(1, 1, At, B1); PG8_BAR; PG8_SCHED;
.LBB0_1801:
	s_add_u32 s16, s18, 0xffd50080
	s_addc_u32 s17, s19, -1
	s_cmpk_eq_i32 s48, 0xa8
	s_cselect_b32 s21, s5, s17
	s_cselect_b32 s20, s4, s16
	s_cselect_b32 s17, s15, s47
	s_cselect_b32 s16, s14, s46
	s_add_i32 m0, s25, 0xc000
	s_nop 0
	global_load_lds_dwordx4 v0, s[18:19]
	s_add_i32 m0, s25, 0xe000
	s_nop 0
	global_load_lds_dwordx4 v162, s[18:19]
	ds_read_b128 v[130:133], v241 offset:0
	ds_read_b128 v[134:137], v241 offset:1024
	ds_read_b128 v[138:141], v241 offset:2048
	ds_read_b128 v[142:145], v241 offset:3072
	ds_read_b128 v[146:149], v241 offset:16384
	ds_read_b128 v[150:153], v241 offset:17408
	ds_read_b128 v[170:173], v241 offset:18432
	ds_read_b128 v[174:177], v241 offset:19456
	ds_read_b128 v[178:181], v184
	ds_read_b128 v[186:189], v184 offset:1024
	ds_read_b128 v[190:193], v184 offset:2048
	ds_read_b128 v[194:197], v184 offset:3072
	ds_read_b128 v[198:201], v184 offset:4096
	ds_read_b128 v[202:205], v184 offset:5120
	ds_read_b128 v[206:209], v184 offset:6144
	ds_read_b128 v[210:213], v184 offset:7168
	s_waitcnt vmcnt(8) lgkmcnt(0)
	s_barrier
	v_mfma_f32_16x16x32_bf16 v[114:117], v[130:133], v[178:181], v[114:117]
	v_mfma_f32_16x16x32_bf16 v[118:121], v[138:141], v[178:181], v[118:121]
	v_mfma_f32_16x16x32_bf16 v[106:109], v[130:133], v[190:193], v[106:109]
	v_mfma_f32_16x16x32_bf16 v[98:101], v[138:141], v[190:193], v[98:101]
	v_mfma_f32_16x16x32_bf16 v[90:93], v[130:133], v[198:201], v[90:93]
	v_mfma_f32_16x16x32_bf16 v[82:85], v[138:141], v[198:201], v[82:85]
	v_mfma_f32_16x16x32_bf16 v[74:77], v[130:133], v[206:209], v[74:77]
	v_mfma_f32_16x16x32_bf16 v[66:69], v[138:141], v[206:209], v[66:69]
	v_mfma_f32_16x16x32_bf16 v[114:117], v[134:137], v[186:189], v[114:117]
	v_mfma_f32_16x16x32_bf16 v[118:121], v[142:145], v[186:189], v[118:121]
	v_mfma_f32_16x16x32_bf16 v[106:109], v[134:137], v[194:197], v[106:109]
	v_mfma_f32_16x16x32_bf16 v[98:101], v[142:145], v[194:197], v[98:101]
	v_mfma_f32_16x16x32_bf16 v[90:93], v[134:137], v[202:205], v[90:93]
	v_mfma_f32_16x16x32_bf16 v[82:85], v[142:145], v[202:205], v[82:85]
	v_mfma_f32_16x16x32_bf16 v[74:77], v[134:137], v[210:213], v[74:77]
	v_mfma_f32_16x16x32_bf16 v[66:69], v[142:145], v[210:213], v[66:69]
	v_mfma_f32_16x16x32_bf16 v[122:125], v[146:149], v[178:181], v[122:125]
	v_mfma_f32_16x16x32_bf16 v[126:129], v[170:173], v[178:181], v[126:129]
	v_mfma_f32_16x16x32_bf16 v[110:113], v[146:149], v[190:193], v[110:113]
	v_mfma_f32_16x16x32_bf16 v[102:105], v[170:173], v[190:193], v[102:105]
	v_mfma_f32_16x16x32_bf16 v[94:97], v[146:149], v[198:201], v[94:97]
	v_mfma_f32_16x16x32_bf16 v[86:89], v[170:173], v[198:201], v[86:89]
	v_mfma_f32_16x16x32_bf16 v[78:81], v[146:149], v[206:209], v[78:81]
	v_mfma_f32_16x16x32_bf16 v[70:73], v[170:173], v[206:209], v[70:73]
	v_mfma_f32_16x16x32_bf16 v[122:125], v[150:153], v[186:189], v[122:125]
	v_mfma_f32_16x16x32_bf16 v[126:129], v[174:177], v[186:189], v[126:129]
	v_mfma_f32_16x16x32_bf16 v[110:113], v[150:153], v[194:197], v[110:113]
	v_mfma_f32_16x16x32_bf16 v[102:105], v[174:177], v[194:197], v[102:105]
	v_mfma_f32_16x16x32_bf16 v[94:97], v[150:153], v[202:205], v[94:97]
	v_mfma_f32_16x16x32_bf16 v[86:89], v[174:177], v[202:205], v[86:89]
	v_mfma_f32_16x16x32_bf16 v[78:81], v[150:153], v[210:213], v[78:81]
	v_mfma_f32_16x16x32_bf16 v[70:73], v[174:177], v[210:213], v[70:73]
	s_barrier
	s_add_i32 s33, s36, s24
	s_mov_b32 m0, s33
	s_nop 0
	global_load_lds_dwordx4 v156, s[16:17]
	s_add_i32 m0, s33, 0x2000
	s_add_u32 s50, s16, 0x2b0000
	s_addc_u32 s51, s17, 0
	s_add_i32 s33, s37, s24
	global_load_lds_dwordx4 v160, s[16:17]
	s_mov_b32 m0, s33
	s_add_u32 s100, s20, 0x80
	s_addc_u32 s101, s21, 0
	global_load_lds_dwordx4 v156, s[50:51]
	s_add_i32 m0, s33, 0x2000
	s_nop 0
	global_load_lds_dwordx4 v160, s[50:51]
	s_mov_b32 m0, s25
	s_nop 0
	global_load_lds_dwordx4 v154, s[20:21]
	s_mov_b32 m0, s26
	s_nop 0
	global_load_lds_dwordx4 v158, s[20:21]
	ds_read_b128 v[178:181], v184 offset:16384
	ds_read_b128 v[186:189], v184 offset:17408
	ds_read_b128 v[190:193], v184 offset:18432
	ds_read_b128 v[194:197], v184 offset:19456
	ds_read_b128 v[198:201], v184 offset:20480
	ds_read_b128 v[202:205], v184 offset:21504
	ds_read_b128 v[206:209], v184 offset:22528
	ds_read_b128 v[210:213], v184 offset:23552
	s_waitcnt vmcnt(8) lgkmcnt(0)
	s_barrier
	v_mfma_f32_16x16x32_bf16 v[58:61], v[130:133], v[178:181], v[58:61]
	v_mfma_f32_16x16x32_bf16 v[54:57], v[138:141], v[178:181], v[54:57]
	v_mfma_f32_16x16x32_bf16 v[42:45], v[130:133], v[190:193], v[42:45]
	v_mfma_f32_16x16x32_bf16 v[34:37], v[138:141], v[190:193], v[34:37]
	v_mfma_f32_16x16x32_bf16 v[26:29], v[130:133], v[198:201], v[26:29]
	v_mfma_f32_16x16x32_bf16 v[18:21], v[138:141], v[198:201], v[18:21]
	v_mfma_f32_16x16x32_bf16 v[6:9], v[130:133], v[206:209], v[6:9]
	v_mfma_f32_16x16x32_bf16 v[2:5], v[138:141], v[206:209], v[2:5]
	v_mfma_f32_16x16x32_bf16 v[58:61], v[134:137], v[186:189], v[58:61]
	v_mfma_f32_16x16x32_bf16 v[54:57], v[142:145], v[186:189], v[54:57]
	v_mfma_f32_16x16x32_bf16 v[42:45], v[134:137], v[194:197], v[42:45]
	v_mfma_f32_16x16x32_bf16 v[34:37], v[142:145], v[194:197], v[34:37]
	v_mfma_f32_16x16x32_bf16 v[26:29], v[134:137], v[202:205], v[26:29]
	v_mfma_f32_16x16x32_bf16 v[18:21], v[142:145], v[202:205], v[18:21]
	v_mfma_f32_16x16x32_bf16 v[6:9], v[134:137], v[210:213], v[6:9]
	v_mfma_f32_16x16x32_bf16 v[2:5], v[142:145], v[210:213], v[2:5]
	v_mfma_f32_16x16x32_bf16 v[62:65], v[146:149], v[178:181], v[62:65]
	v_mfma_f32_16x16x32_bf16 v[50:53], v[170:173], v[178:181], v[50:53]
	v_mfma_f32_16x16x32_bf16 v[46:49], v[146:149], v[190:193], v[46:49]
	v_mfma_f32_16x16x32_bf16 v[38:41], v[170:173], v[190:193], v[38:41]
	v_mfma_f32_16x16x32_bf16 v[30:33], v[146:149], v[198:201], v[30:33]
	v_mfma_f32_16x16x32_bf16 v[22:25], v[170:173], v[198:201], v[22:25]
	v_mfma_f32_16x16x32_bf16 v[10:13], v[146:149], v[206:209], v[10:13]
	v_mfma_f32_16x16x32_bf16 v[14:17], v[170:173], v[206:209], v[14:17]
	v_mfma_f32_16x16x32_bf16 v[62:65], v[150:153], v[186:189], v[62:65]
	v_mfma_f32_16x16x32_bf16 v[50:53], v[174:177], v[186:189], v[50:53]
	v_mfma_f32_16x16x32_bf16 v[46:49], v[150:153], v[194:197], v[46:49]
	v_mfma_f32_16x16x32_bf16 v[38:41], v[174:177], v[194:197], v[38:41]
	v_mfma_f32_16x16x32_bf16 v[30:33], v[150:153], v[202:205], v[30:33]
	v_mfma_f32_16x16x32_bf16 v[22:25], v[174:177], v[202:205], v[22:25]
	v_mfma_f32_16x16x32_bf16 v[10:13], v[150:153], v[210:213], v[10:13]
	v_mfma_f32_16x16x32_bf16 v[14:17], v[174:177], v[210:213], v[14:17]
	s_barrier
; #define PG8_STAGE(bufoff, gbase, voff) do { _Pragma("unroll") for (int _i = 0; _i < 2; ++_i) \
;         __builtin_amdgcn_global_load_lds((const unsigned*)((const char*)(gbase) + (voff)[_i]), (PG8_LAS unsigned*)(lds + (bufoff) + ldsw + _i * 8192), 16, 0, 0); } while (0)
; #define PG8_LDA(dst, b, h) do { _Pragma("unroll") for (int m = 0; m < 4; ++m) _Pragma("unroll") for (int k = 0; k < 2; ++k) dst[m][k] = *(const PG8_LAS bf16x8*)(lds + PG8_SA(b, h) + aoff + m * 2048 + k * 1024); } while (0)
; #define PG8_LDB(dst, b, h) do { _Pragma("unroll") for (int n = 0; n < 2; ++n) _Pragma("unroll") for (int k = 0; k < 2; ++k) dst[n][k] = *(const PG8_LAS bf16x8*)(lds + PG8_SB(b, h) + boff + n * 2048 + k * 1024); } while (0)
; #define PG8_MMA(ai, bj, At, Bt) do { __builtin_amdgcn_s_setprio(1); _Pragma("unroll") for (int m = 0; m < 4; ++m) _Pragma("unroll") for (int n = 0; n < 2; ++n) _Pragma("unroll") for (int k = 0; k < 2; ++k) \
;         acc[ai][bj][m][n] = __builtin_amdgcn_mfma_f32_16x16x32_bf16(Bt[n][k], At[m][k], acc[ai][bj][m][n], 0, 0, 0); __builtin_amdgcn_s_setprio(0); } while (0)
; #define PG8_WAIT_V(n) asm volatile("s_waitcnt vmcnt(" #n ")" ::: "memory")
; #define PG8_WAIT_L(n) asm volatile("s_waitcnt lgkmcnt(" #n ")" ::: "memory")
; #define PG8_BAR __builtin_amdgcn_s_barrier()
; #define PG8_SCHED __builtin_amdgcn_sched_barrier(0)
; template <class Epi, class Sched, bool ALIGN_EPI = false, bool SP2 = false>
; __device__ __forceinline__ void gemm_phase(PG8_LAS unsigned char* lds, const Gemm g, const Sched& S, const Epi& E) {
;     ...
;             PG8_LDB(B0, 1, 0); PG8_LDB(B1, 1, 1); PG8_SCHED; PG8_LDA(At, 1, 0); PG8_STAGE(PG8_SA(0, 1), a2 + hstep, voffA);
;             PG8_WAIT_V(8); PG8_WAIT_L(0); PG8_BAR; PG8_MMA(0, 0, At, B0); PG8_MMA(0, 1, At, B1); PG8_BAR; PG8_SCHED;
;             PG8_LDA(At, 1, 1); PG8_STAGE(PG8_SB(1, 0), b3, voffB); PG8_STAGE(PG8_SB(1, 1), b3 + hstep, voffB); PG8_STAGE(PG8_SA(1, 0), a3, voffA);
;             PG8_WAIT_V(8); PG8_WAIT_L(0); PG8_BAR; PG8_MMA(1, 0, At, B0); PG8_MMA(1, 1, At, B1); PG8_BAR; PG8_SCHED;
;     ...
;         if constexpr (ALIGN_EPI) { if (wr == 0) PG8_BAR; }
	s_add_i32 s33, 0, 0x18000
	s_add_i32 s42, 0, 0x1c000
	s_add_u32 s20, s20, 0x2b0000
	s_addc_u32 s21, s21, 0
	s_mov_b32 m0, s27
	s_nop 0
	global_load_lds_dwordx4 v154, s[20:21]
	s_mov_b32 m0, s28
	s_nop 0
	global_load_lds_dwordx4 v158, s[20:21]
	ds_read_b128 v[130:133], v241 offset:32768
	ds_read_b128 v[134:137], v241 offset:33792
	ds_read_b128 v[138:141], v241 offset:34816
	ds_read_b128 v[142:145], v241 offset:35840
	ds_read_b128 v[146:149], v241 offset:49152
	ds_read_b128 v[150:153], v241 offset:50176
	ds_read_b128 v[170:173], v241 offset:51200
	ds_read_b128 v[174:177], v241 offset:52224
	ds_read_b128 v[178:181], v184 offset:32768
	ds_read_b128 v[186:189], v184 offset:33792
	ds_read_b128 v[190:193], v184 offset:34816
	ds_read_b128 v[194:197], v184 offset:35840
	ds_read_b128 v[198:201], v184 offset:36864
	ds_read_b128 v[202:205], v184 offset:37888
	ds_read_b128 v[206:209], v184 offset:38912
	ds_read_b128 v[210:213], v184 offset:39936
	s_waitcnt vmcnt(8) lgkmcnt(0)
	s_barrier
	v_mfma_f32_16x16x32_bf16 v[114:117], v[130:133], v[178:181], v[114:117]
	v_mfma_f32_16x16x32_bf16 v[118:121], v[138:141], v[178:181], v[118:121]
	v_mfma_f32_16x16x32_bf16 v[106:109], v[130:133], v[190:193], v[106:109]
	v_mfma_f32_16x16x32_bf16 v[98:101], v[138:141], v[190:193], v[98:101]
	v_mfma_f32_16x16x32_bf16 v[90:93], v[130:133], v[198:201], v[90:93]
	v_mfma_f32_16x16x32_bf16 v[82:85], v[138:141], v[198:201], v[82:85]
	v_mfma_f32_16x16x32_bf16 v[74:77], v[130:133], v[206:209], v[74:77]
	v_mfma_f32_16x16x32_bf16 v[66:69], v[138:141], v[206:209], v[66:69]
	v_mfma_f32_16x16x32_bf16 v[114:117], v[134:137], v[186:189], v[114:117]
	v_mfma_f32_16x16x32_bf16 v[118:121], v[142:145], v[186:189], v[118:121]
	v_mfma_f32_16x16x32_bf16 v[106:109], v[134:137], v[194:197], v[106:109]
	v_mfma_f32_16x16x32_bf16 v[98:101], v[142:145], v[194:197], v[98:101]
	v_mfma_f32_16x16x32_bf16 v[90:93], v[134:137], v[202:205], v[90:93]
	v_mfma_f32_16x16x32_bf16 v[82:85], v[142:145], v[202:205], v[82:85]
	v_mfma_f32_16x16x32_bf16 v[74:77], v[134:137], v[210:213], v[74:77]
	v_mfma_f32_16x16x32_bf16 v[66:69], v[142:145], v[210:213], v[66:69]
	v_mfma_f32_16x16x32_bf16 v[122:125], v[146:149], v[178:181], v[122:125]
	v_mfma_f32_16x16x32_bf16 v[126:129], v[170:173], v[178:181], v[126:129]
	v_mfma_f32_16x16x32_bf16 v[110:113], v[146:149], v[190:193], v[110:113]
	v_mfma_f32_16x16x32_bf16 v[102:105], v[170:173], v[190:193], v[102:105]
	v_mfma_f32_16x16x32_bf16 v[94:97], v[146:149], v[198:201], v[94:97]
	v_mfma_f32_16x16x32_bf16 v[86:89], v[170:173], v[198:201], v[86:89]
	v_mfma_f32_16x16x32_bf16 v[78:81], v[146:149], v[206:209], v[78:81]
	v_mfma_f32_16x16x32_bf16 v[70:73], v[170:173], v[206:209], v[70:73]
	v_mfma_f32_16x16x32_bf16 v[122:125], v[150:153], v[186:189], v[122:125]
	v_mfma_f32_16x16x32_bf16 v[126:129], v[174:177], v[186:189], v[126:129]
	v_mfma_f32_16x16x32_bf16 v[110:113], v[150:153], v[194:197], v[110:113]
	v_mfma_f32_16x16x32_bf16 v[102:105], v[174:177], v[194:197], v[102:105]
	v_mfma_f32_16x16x32_bf16 v[94:97], v[150:153], v[202:205], v[94:97]
	v_mfma_f32_16x16x32_bf16 v[86:89], v[174:177], v[202:205], v[86:89]
	v_mfma_f32_16x16x32_bf16 v[78:81], v[150:153], v[210:213], v[78:81]
	v_mfma_f32_16x16x32_bf16 v[70:73], v[174:177], v[210:213], v[70:73]
	s_barrier
	s_add_i32 s20, s33, s24
	s_add_i32 m0, s20, 0xffffff80
	s_nop 0
	global_load_lds_dwordx4 v156, s[16:17] offset:128
	s_add_i32 m0, s20, 0x1f80
	s_add_i32 s20, s42, s24
	global_load_lds_dwordx4 v160, s[16:17] offset:128
	s_add_u32 s16, s16, 0x2b0080
	s_addc_u32 s17, s17, 0
	s_mov_b32 m0, s20
	s_nop 0
	global_load_lds_dwordx4 v156, s[16:17]
	s_add_i32 m0, s20, 0x2000
	s_nop 0
	global_load_lds_dwordx4 v160, s[16:17]
	s_mov_b32 m0, s30
	s_nop 0
	global_load_lds_dwordx4 v154, s[100:101]
	s_mov_b32 m0, s31
	s_nop 0
	global_load_lds_dwordx4 v158, s[100:101]
	ds_read_b128 v[178:181], v184 offset:49152
	ds_read_b128 v[186:189], v184 offset:50176
	ds_read_b128 v[190:193], v184 offset:51200
	ds_read_b128 v[194:197], v184 offset:52224
	ds_read_b128 v[198:201], v184 offset:53248
	ds_read_b128 v[202:205], v184 offset:54272
	ds_read_b128 v[206:209], v184 offset:55296
	ds_read_b128 v[210:213], v184 offset:56320
	s_waitcnt vmcnt(8) lgkmcnt(0)
	s_barrier
	v_mfma_f32_16x16x32_bf16 v[58:61], v[130:133], v[178:181], v[58:61]
	v_mfma_f32_16x16x32_bf16 v[54:57], v[138:141], v[178:181], v[54:57]
	v_mfma_f32_16x16x32_bf16 v[42:45], v[130:133], v[190:193], v[42:45]
	v_mfma_f32_16x16x32_bf16 v[34:37], v[138:141], v[190:193], v[34:37]
	v_mfma_f32_16x16x32_bf16 v[26:29], v[130:133], v[198:201], v[26:29]
	v_mfma_f32_16x16x32_bf16 v[18:21], v[138:141], v[198:201], v[18:21]
	v_mfma_f32_16x16x32_bf16 v[6:9], v[130:133], v[206:209], v[6:9]
	v_mfma_f32_16x16x32_bf16 v[2:5], v[138:141], v[206:209], v[2:5]
	v_mfma_f32_16x16x32_bf16 v[58:61], v[134:137], v[186:189], v[58:61]
	v_mfma_f32_16x16x32_bf16 v[54:57], v[142:145], v[186:189], v[54:57]
	v_mfma_f32_16x16x32_bf16 v[42:45], v[134:137], v[194:197], v[42:45]
	v_mfma_f32_16x16x32_bf16 v[34:37], v[142:145], v[194:197], v[34:37]
	v_mfma_f32_16x16x32_bf16 v[26:29], v[134:137], v[202:205], v[26:29]
	v_mfma_f32_16x16x32_bf16 v[18:21], v[142:145], v[202:205], v[18:21]
	v_mfma_f32_16x16x32_bf16 v[6:9], v[134:137], v[210:213], v[6:9]
	v_mfma_f32_16x16x32_bf16 v[2:5], v[142:145], v[210:213], v[2:5]
	v_mfma_f32_16x16x32_bf16 v[62:65], v[146:149], v[178:181], v[62:65]
	v_mfma_f32_16x16x32_bf16 v[50:53], v[170:173], v[178:181], v[50:53]
	v_mfma_f32_16x16x32_bf16 v[46:49], v[146:149], v[190:193], v[46:49]
	v_mfma_f32_16x16x32_bf16 v[38:41], v[170:173], v[190:193], v[38:41]
	v_mfma_f32_16x16x32_bf16 v[30:33], v[146:149], v[198:201], v[30:33]
	v_mfma_f32_16x16x32_bf16 v[22:25], v[170:173], v[198:201], v[22:25]
	v_mfma_f32_16x16x32_bf16 v[10:13], v[146:149], v[206:209], v[10:13]
	v_mfma_f32_16x16x32_bf16 v[14:17], v[170:173], v[206:209], v[14:17]
	v_mfma_f32_16x16x32_bf16 v[62:65], v[150:153], v[186:189], v[62:65]
	v_mfma_f32_16x16x32_bf16 v[50:53], v[174:177], v[186:189], v[50:53]
	v_mfma_f32_16x16x32_bf16 v[46:49], v[150:153], v[194:197], v[46:49]
	v_mfma_f32_16x16x32_bf16 v[38:41], v[174:177], v[194:197], v[38:41]
	v_mfma_f32_16x16x32_bf16 v[30:33], v[150:153], v[202:205], v[30:33]
	v_mfma_f32_16x16x32_bf16 v[22:25], v[174:177], v[202:205], v[22:25]
	v_mfma_f32_16x16x32_bf16 v[10:13], v[150:153], v[210:213], v[10:13]
	v_mfma_f32_16x16x32_bf16 v[14:17], v[174:177], v[210:213], v[14:17]
	s_barrier
	s_add_i32 s48, s48, 2
	s_add_u32 s18, s18, 0x100
	s_addc_u32 s19, s19, 0
	s_add_u32 s46, s46, 0x100
	s_addc_u32 s47, s47, 0
	s_cmpk_gt_u32 s48, 0xa9
	s_cbranch_scc0 .LBB0_1801
	s_and_b64 vcc, exec, s[12:13]
	s_cbranch_vccz .LBB0_1804
	s_barrier
